# batch serialized load-wait chains: sample_item LRU gate matvec (128 loads), ret_m1 V copy, ret_m2 V/S copies, ssd_m2 S copy
# speedup vs baseline: 1.0704x; 1.0479x over previous
; #define LAS __attribute__((address_space(3)))
; __device__ __forceinline__ void rot16(const bf16_t* src, const float* rc, const float* rs, float scale, LAS bf16_t* dst) {
;     float x1[16], x2[16], o1[16], o2[16];
;     unpack8(*(const u32x4*)src, x1); unpack8(*(const u32x4*)(src + 8), x1 + 8);
;     unpack8(*(const u32x4*)(src + 32), x2); unpack8(*(const u32x4*)(src + 40), x2 + 8);
; #pragma unroll
;     for (int e = 0; e < 16; ++e) { const float c = rc[e], s = rs[e]; o1[e] = (x1[e] * c - x2[e] * s) * scale; o2[e] = (x1[e] * s + x2[e] * c) * scale; }
; __device__ void ret_m2(const Params& p, LAS unsigned char* lds, int l, int b, int c, int hp) {
;     ...
;     const int row0 = b * SEQ + c * 64, pos0 = c * 64;
;     constexpr int HB = 63488;
;     {
;         const int j = tid >> 3, sub = tid & 7, hh = sub >> 2, which = (sub >> 1) & 1, d0 = (sub & 1) * 16, h = 2 * hp + hh;
;         LAS bf16_t* dst = (LAS bf16_t*)(lds + hh * HB + which * 9216) + j * 72 + d0;
;         rot16(proj + (size_t)(row0 + j) * NPROJ + (which ? PC_K : PC_Q) + h * 64 + d0, rc + (pos0 + j) * 32 + d0, rs + (pos0 + j) * 32 + d0, which ? 0.125f : 1.f, dst);
.LBB0_299:
	s_ashr_i32 s3, s26, 6
	s_bfe_u32 s0, s26, 0x50001
	s_lshl_b32 s1, s3, 11
	s_lshl_b32 s24, s0, 6
	v_mov_b32_e32 v44, v163
	s_or_b32 s2, s24, s1
	s_lshl_b32 s1, s26, 1
	s_and_b32 s1, s1, 2
	v_bfe_u32 v0, v44, 2, 1
	v_bfe_u32 v3, v44, 1, 1
	v_lshlrev_b32_e32 v58, 4, v44
	v_ashrrev_i32_e32 v8, 3, v44
	v_and_b32_e32 v9, 16, v58
	v_or_b32_e32 v10, s1, v0
	v_mul_u32_u24_e32 v0, 0xf800, v0
	s_waitcnt lgkmcnt(0)
	v_mul_u32_u24_e32 v2, 0x2400, v3
	v_add3_u32 v0, 0, v0, v2
	v_mul_lo_u32 v4, v8, s43
	v_lshlrev_b32_e32 v2, 1, v9
	v_add3_u32 v45, v0, v4, v2
	v_add_u32_e32 v4, s2, v8
	v_ashrrev_i32_e32 v5, 31, v4
	v_lshlrev_b64 v[4:5], 13, v[4:5]
	v_cmp_eq_u32_e32 vcc, 0, v3
	v_mov_b32_e32 v0, 0xa00
	v_mov_b32_e32 v3, 0x800
	v_lshl_add_u64 v[4:5], s[34:35], 0, v[4:5]
	v_cndmask_b32_e32 v0, v0, v3, vcc
	v_lshl_add_u64 v[4:5], v[4:5], 0, v[0:1]
	v_lshlrev_b32_e32 v0, 7, v10
	v_lshl_add_u64 v[4:5], v[4:5], 0, v[0:1]
	v_mov_b32_e32 v3, v1
	v_lshl_add_u64 v[16:17], v[4:5], 0, v[2:3]
	v_add_lshl_u32 v2, s24, v8, 5
	v_ashrrev_i32_e32 v3, 31, v2
	v_lshlrev_b64 v[2:3], 2, v[2:3]
	v_lshl_add_u64 v[4:5], s[54:55], 0, v[2:3]
	v_lshlrev_b32_e32 v0, 2, v9
	v_lshl_add_u64 v[2:3], s[48:49], 0, v[2:3]
	v_lshl_add_u64 v[32:33], v[4:5], 0, v[0:1]
	v_lshl_add_u64 v[50:51], v[2:3], 0, v[0:1]
	global_load_dwordx4 v[2:5], v[16:17], off offset:16
	global_load_dwordx4 v[8:11], v[16:17], off
	global_load_dwordx4 v[12:15], v[16:17], off offset:80
	s_nop 0
	global_load_dwordx4 v[16:19], v[16:17], off offset:64
	s_waitcnt lgkmcnt(0)
	global_load_dwordx4 v[20:23], v[32:33], off offset:48
	global_load_dwordx4 v[24:27], v[32:33], off offset:32
	global_load_dwordx4 v[28:31], v[32:33], off offset:16
	s_nop 0
	global_load_dwordx4 v[32:35], v[32:33], off
	s_nop 0
	global_load_dwordx4 v[36:39], v[50:51], off offset:48
	global_load_dwordx4 v[40:43], v[50:51], off offset:32
	global_load_dwordx4 v[46:49], v[50:51], off offset:16
	s_nop 0
	global_load_dwordx4 v[50:53], v[50:51], off
	v_cndmask_b32_e64 v0, v169, 1.0, vcc
	s_lshl_b32 s3, s3, 2
	s_or_b32 s3, s1, s3
	v_and_b32_e32 v6, 15, v44
	v_lshrrev_b32_e32 v7, 2, v44
	v_and_b32_e32 v90, 63, v44
	s_waitcnt vmcnt(10)
	v_lshlrev_b32_e32 v54, 16, v8
	s_waitcnt vmcnt(8)
	v_lshlrev_b32_e32 v55, 16, v16
	s_waitcnt vmcnt(4)
	v_mov_b32_e32 v56, v32
	s_waitcnt vmcnt(0)
	v_mov_b32_e32 v57, v50
	v_pk_mul_f32 v[56:57], v[56:57], v[54:55]
	s_nop 0
	v_sub_f32_e32 v56, v56, v57
	v_mul_f32_e32 v59, v0, v56
	v_mov_b32_e32 v56, v50
	v_mov_b32_e32 v57, v32
	v_pk_mul_f32 v[54:55], v[56:57], v[54:55]
	v_mov_b32_e32 v50, v33
	v_add_f32_e32 v32, v55, v54
	v_and_b32_e32 v55, 0xffff0000, v16
	v_and_b32_e32 v54, 0xffff0000, v8
	v_mul_f32_e32 v60, v0, v32
	v_pk_mul_f32 v[56:57], v[50:51], v[54:55]
	v_mov_b32_e32 v32, v51
	v_sub_f32_e32 v8, v56, v57
	v_pk_mul_f32 v[32:33], v[32:33], v[54:55]
	v_mul_f32_e32 v56, v0, v8
	v_add_f32_e32 v8, v33, v32
	v_lshlrev_b32_e32 v33, 16, v17
	v_lshlrev_b32_e32 v32, 16, v9
	v_mov_b32_e32 v50, v34
	v_mov_b32_e32 v51, v52
	v_pk_mul_f32 v[50:51], v[50:51], v[32:33]
	v_mul_f32_e32 v54, v0, v8
	v_sub_f32_e32 v8, v50, v51
	v_mov_b32_e32 v50, v52
	v_mov_b32_e32 v51, v34
	v_pk_mul_f32 v[32:33], v[50:51], v[32:33]
	v_mul_f32_e32 v55, v0, v8
	v_add_f32_e32 v8, v33, v32
	v_and_b32_e32 v17, 0xffff0000, v17
	v_and_b32_e32 v16, 0xffff0000, v9
	v_mov_b32_e32 v52, v35
	v_mul_f32_e32 v32, v0, v8
	v_pk_mul_f32 v[8:9], v[52:53], v[16:17]
	v_mov_b32_e32 v34, v53
	v_sub_f32_e32 v8, v8, v9
	v_mul_f32_e32 v33, v0, v8
	v_pk_mul_f32 v[8:9], v[34:35], v[16:17]
	v_mov_b32_e32 v16, v28
	v_add_f32_e32 v8, v9, v8
	v_mul_f32_e32 v34, v0, v8
	v_lshlrev_b32_e32 v9, 16, v18
	v_lshlrev_b32_e32 v8, 16, v10
	v_mov_b32_e32 v17, v46
	v_pk_mul_f32 v[16:17], v[16:17], v[8:9]
	s_nop 0
	v_sub_f32_e32 v16, v16, v17
	v_mul_f32_e32 v35, v0, v16
	v_mov_b32_e32 v16, v46
	v_mov_b32_e32 v17, v28
	v_pk_mul_f32 v[8:9], v[16:17], v[8:9]
	v_mov_b32_e32 v46, v29
	v_add_f32_e32 v8, v9, v8
	v_mul_f32_e32 v50, v0, v8
	v_and_b32_e32 v9, 0xffff0000, v18
	v_and_b32_e32 v8, 0xffff0000, v10
	v_mov_b32_e32 v28, v47
	v_pk_mul_f32 v[16:17], v[46:47], v[8:9]
	v_pk_mul_f32 v[8:9], v[28:29], v[8:9]
	v_sub_f32_e32 v10, v16, v17
	v_add_f32_e32 v8, v9, v8
	v_mul_f32_e32 v28, v0, v8
	v_lshlrev_b32_e32 v9, 16, v19
	v_lshlrev_b32_e32 v8, 16, v11
	v_mov_b32_e32 v16, v30
	v_mov_b32_e32 v17, v48
	v_pk_mul_f32 v[16:17], v[16:17], v[8:9]
	v_mul_f32_e32 v18, v0, v10
	v_sub_f32_e32 v10, v16, v17
	v_mov_b32_e32 v16, v48
	v_mov_b32_e32 v17, v30
	v_pk_mul_f32 v[8:9], v[16:17], v[8:9]
	v_mov_b32_e32 v48, v31
	v_add_f32_e32 v8, v9, v8
	v_mul_f32_e32 v16, v0, v8
	v_and_b32_e32 v9, 0xffff0000, v19
	v_and_b32_e32 v8, 0xffff0000, v11
	v_mov_b32_e32 v30, v49
	v_mul_f32_e32 v29, v0, v10
	v_pk_mul_f32 v[10:11], v[48:49], v[8:9]
	v_pk_mul_f32 v[8:9], v[30:31], v[8:9]
	v_sub_f32_e32 v10, v10, v11
	v_add_f32_e32 v8, v9, v8
	v_mul_f32_e32 v17, v0, v10
	v_mul_f32_e32 v19, v0, v8
	v_lshlrev_b32_e32 v9, 16, v12
	v_lshlrev_b32_e32 v8, 16, v2
	v_mov_b32_e32 v10, v24
	v_mov_b32_e32 v11, v40
	v_pk_mul_f32 v[10:11], v[10:11], v[8:9]
	v_and_or_b32 v49, v7, 48, v6
	v_sub_f32_e32 v10, v10, v11
	v_mul_f32_e32 v30, v0, v10
	v_mov_b32_e32 v10, v40
	v_mov_b32_e32 v11, v24
	v_pk_mul_f32 v[8:9], v[10:11], v[8:9]
	v_mov_b32_e32 v40, v25
	v_add_f32_e32 v8, v9, v8
	v_mul_f32_e32 v31, v0, v8
	v_and_b32_e32 v9, 0xffff0000, v12
	v_and_b32_e32 v8, 0xffff0000, v2
	v_pk_mul_f32 v[10:11], v[40:41], v[8:9]
	v_mov_b32_e32 v24, v41
	v_sub_f32_e32 v2, v10, v11
	v_pk_mul_f32 v[8:9], v[24:25], v[8:9]
	v_mul_f32_e32 v12, v0, v2
	v_add_f32_e32 v2, v9, v8
	v_lshlrev_b32_e32 v9, 16, v13
	v_lshlrev_b32_e32 v8, 16, v3
	v_mov_b32_e32 v10, v26
	v_mov_b32_e32 v11, v42
; #define LAS __attribute__((address_space(3)))
; __device__ __forceinline__ u32x4 pack8(const float* f) { u32x4 w; w.x = pk2(f[0], f[1]); w.y = pk2(f[2], f[3]); w.z = pk2(f[4], f[5]); w.w = pk2(f[6], f[7]); return w; }
; __device__ __forceinline__ void rot16(const bf16_t* src, const float* rc, const float* rs, float scale, LAS bf16_t* dst) {
;     ...
;     for (int e = 0; e < 16; ++e) { const float c = rc[e], s = rs[e]; o1[e] = (x1[e] * c - x2[e] * s) * scale; o2[e] = (x1[e] * s + x2[e] * c) * scale; }
;     *(LAS u32x4*)dst = pack8(o1); *(LAS u32x4*)(dst + 8) = pack8(o1 + 8);
;     *(LAS u32x4*)(dst + 32) = pack8(o2); *(LAS u32x4*)(dst + 40) = pack8(o2 + 8);
; __device__ void ret_m2(const Params& p, LAS unsigned char* lds, int l, int b, int c, int hp) {
;     ...
;         for (int i = 0; i < 4; ++i) { const int id = tid + 512 * i, h2 = id >> 10, jj = (id >> 4) & 63, cc = id & 15;
;             *(LAS u32x4*)((LAS bf16_t*)(lds + h2 * HB + 18432) + jj * 136 + cc * 8) = *(const u32x4*)(proj + (size_t)(row0 + jj) * NPROJ + PC_V + (2 * hp + h2) * 128 + cc * 8); }
; #pragma unroll
;         for (int i = 0; i < 4; ++i) { const int id = tid + 512 * i, h2 = id >> 10, v = (id >> 3) & 127, kc = id & 7;
;             *(LAS u32x4*)((LAS bf16_t*)(lds + h2 * HB + 35840) + v * 72 + kc * 8) = *(const u32x4*)(sp + ((size_t)((b * 4 + 2 * hp + h2) * NCH + c)) * 8192 + v * 64 + kc * 8); }
;     }
;     __syncthreads();
	v_pk_mul_f32 v[10:11], v[10:11], v[8:9]
	v_mul_f32_e32 v24, v0, v2
	v_sub_f32_e32 v2, v10, v11
	v_mov_b32_e32 v10, v42
	v_mov_b32_e32 v11, v26
	v_pk_mul_f32 v[8:9], v[10:11], v[8:9]
	v_mul_f32_e32 v25, v0, v2
	v_add_f32_e32 v2, v9, v8
	v_and_b32_e32 v9, 0xffff0000, v13
	v_and_b32_e32 v8, 0xffff0000, v3
	v_mov_b32_e32 v42, v27
	v_mul_f32_e32 v10, v0, v2
	v_pk_mul_f32 v[2:3], v[42:43], v[8:9]
	v_mov_b32_e32 v26, v43
	v_sub_f32_e32 v2, v2, v3
	v_mul_f32_e32 v11, v0, v2
	v_pk_mul_f32 v[2:3], v[26:27], v[8:9]
	v_mov_b32_e32 v8, v20
	v_add_f32_e32 v2, v3, v2
	v_mul_f32_e32 v13, v0, v2
	v_lshlrev_b32_e32 v3, 16, v14
	v_lshlrev_b32_e32 v2, 16, v4
	v_mov_b32_e32 v9, v36
	v_pk_mul_f32 v[8:9], v[8:9], v[2:3]
	v_or_b32_e32 v80, s2, v49
	v_sub_f32_e32 v8, v8, v9
	v_mul_f32_e32 v26, v0, v8
	v_mov_b32_e32 v8, v36
	v_mov_b32_e32 v9, v20
	v_pk_mul_f32 v[2:3], v[8:9], v[2:3]
	v_mov_b32_e32 v36, v21
	v_add_f32_e32 v2, v3, v2
	v_mul_f32_e32 v27, v0, v2
	v_and_b32_e32 v3, 0xffff0000, v14
	v_and_b32_e32 v2, 0xffff0000, v4
	v_mov_b32_e32 v20, v37
	v_pk_mul_f32 v[8:9], v[36:37], v[2:3]
	v_pk_mul_f32 v[2:3], v[20:21], v[2:3]
	v_sub_f32_e32 v4, v8, v9
	v_add_f32_e32 v2, v3, v2
	v_mul_f32_e32 v20, v0, v2
	v_lshlrev_b32_e32 v3, 16, v15
	v_lshlrev_b32_e32 v2, 16, v5
	v_mov_b32_e32 v8, v22
	v_mov_b32_e32 v9, v38
	v_pk_mul_f32 v[8:9], v[8:9], v[2:3]
	v_mul_f32_e32 v14, v0, v4
	v_sub_f32_e32 v4, v8, v9
	v_mov_b32_e32 v8, v38
	v_mov_b32_e32 v9, v22
	v_pk_mul_f32 v[2:3], v[8:9], v[2:3]
	v_mov_b32_e32 v38, v23
	v_add_f32_e32 v2, v3, v2
	v_mul_f32_e32 v8, v0, v2
	v_and_b32_e32 v3, 0xffff0000, v15
	v_and_b32_e32 v2, 0xffff0000, v5
	v_mov_b32_e32 v22, v39
	v_mul_f32_e32 v21, v0, v4
	v_pk_mul_f32 v[4:5], v[38:39], v[2:3]
	v_pk_mul_f32 v[2:3], v[22:23], v[2:3]
	v_sub_f32_e32 v4, v4, v5
	v_add_f32_e32 v2, v3, v2
	v_mul_f32_e32 v9, v0, v4
	v_mul_f32_e32 v0, v0, v2
	v_cvt_pk_bf16_f32 v2, v59, v56
	v_cvt_pk_bf16_f32 v3, v55, v33
	v_cvt_pk_bf16_f32 v4, v35, v18
	v_cvt_pk_bf16_f32 v5, v29, v17
	ds_write_b128 v45, v[2:5]
	v_cvt_pk_bf16_f32 v2, v30, v12
	v_cvt_pk_bf16_f32 v3, v25, v11
	v_cvt_pk_bf16_f32 v4, v26, v14
	v_cvt_pk_bf16_f32 v5, v21, v9
	ds_write_b128 v45, v[2:5] offset:16
	v_cvt_pk_bf16_f32 v2, v60, v54
	v_cvt_pk_bf16_f32 v3, v32, v34
	v_cvt_pk_bf16_f32 v4, v50, v28
	v_cvt_pk_bf16_f32 v5, v16, v19
	ds_write_b128 v45, v[2:5] offset:64
	v_cvt_pk_bf16_f32 v2, v31, v24
	v_cvt_pk_bf16_f32 v3, v10, v13
	v_cvt_pk_bf16_f32 v4, v27, v20
	v_cvt_pk_bf16_f32 v5, v8, v0
	v_bfe_u32 v8, v44, 4, 6
	ds_write_b128 v45, v[2:5] offset:80
	v_or_b32_e32 v2, s2, v8
	v_ashrrev_i32_e32 v3, 31, v2
	v_ashrrev_i32_e32 v18, 10, v44
	v_lshlrev_b64 v[2:3], 13, v[2:3]
	v_lshl_add_u64 v[10:11], s[34:35], 0, v[2:3]
	v_add_lshl_u32 v2, v18, s1, 7
	v_ashrrev_i32_e32 v3, 31, v2
	v_lshl_add_u64 v[2:3], v[2:3], 1, v[10:11]
	v_and_b32_e32 v0, 0xf0, v58
	v_lshl_add_u64 v[2:3], v[2:3], 0, v[0:1]
	global_load_dwordx4 v[172:175], v[2:3], off offset:3072
	v_mad_i32_i24 v14, v18, s45, 0
	v_mul_u32_u24_e32 v13, 0x110, v8
	v_add_u32_e32 v15, 0x200, v44
	v_add3_u32 v8, v14, v13, v0
	v_bfe_u32 v9, v15, 4, 6
	v_ashrrev_i32_e32 v16, 10, v15
	v_ashrrev_i32_e32 v81, 31, v80
	v_lshlrev_b32_e32 v45, 3, v44
	v_and_b32_e32 v45, 24, v45
	v_mov_b32_e32 v150, v8
	v_or_b32_e32 v2, s2, v9
	v_ashrrev_i32_e32 v3, 31, v2
	v_lshlrev_b64 v[2:3], 13, v[2:3]
	v_add_lshl_u32 v4, v16, s1, 7
	v_lshl_add_u64 v[2:3], s[34:35], 0, v[2:3]
	v_ashrrev_i32_e32 v5, 31, v4
	v_lshl_add_u64 v[2:3], v[4:5], 1, v[2:3]
	v_lshl_add_u64 v[2:3], v[2:3], 0, v[0:1]
	global_load_dwordx4 v[176:179], v[2:3], off offset:3072
	v_mad_i32_i24 v8, v16, s45, 0
	v_mul_u32_u24_e32 v9, 0x110, v9
	v_add3_u32 v9, v8, v9, v0
	v_mov_b32_e32 v151, v9
	v_add_u32_e32 v2, 0x400, v44
	v_ashrrev_i32_e32 v12, 10, v2
	v_add_lshl_u32 v2, v12, s1, 7
	v_ashrrev_i32_e32 v3, 31, v2
	v_lshl_add_u64 v[2:3], v[2:3], 1, v[10:11]
	v_lshl_add_u64 v[2:3], v[2:3], 0, v[0:1]
	global_load_dwordx4 v[180:183], v[2:3], off offset:3072
	v_mad_i32_i24 v9, v12, s45, 0
	v_add3_u32 v10, v9, v13, v0
	v_mov_b32_e32 v152, v10
	v_add_u32_e32 v10, 0x600, v44
	v_bfe_u32 v17, v10, 4, 6
	v_or_b32_e32 v2, s2, v17
	v_ashrrev_i32_e32 v11, 10, v10
	v_ashrrev_i32_e32 v3, 31, v2
	v_lshlrev_b64 v[2:3], 13, v[2:3]
	v_add_lshl_u32 v4, v11, s1, 7
	v_lshl_add_u64 v[2:3], s[34:35], 0, v[2:3]
	v_ashrrev_i32_e32 v5, 31, v4
	v_lshl_add_u64 v[2:3], v[4:5], 1, v[2:3]
	v_lshl_add_u64 v[2:3], v[2:3], 0, v[0:1]
	global_load_dwordx4 v[184:187], v[2:3], off offset:3072
	v_mad_i32_i24 v13, v11, s45, 0
	v_mul_u32_u24_e32 v17, 0x110, v17
	v_add3_u32 v0, v13, v17, v0
	v_bfe_u32 v17, v44, 3, 7
	v_mul_u32_u24_e32 v22, 0x90, v17
	v_mov_b32_e32 v153, v0
	v_add_u32_e32 v0, s3, v18
	v_lshl_or_b32 v2, v0, 5, s0
	v_ashrrev_i32_e32 v3, 31, v2
	v_lshlrev_b64 v[2:3], 14, v[2:3]
	v_lshl_add_u64 v[2:3], s[58:59], 0, v[2:3]
	v_lshlrev_b32_e32 v0, 7, v17
	v_lshl_add_u64 v[4:5], v[2:3], 0, v[0:1]
	v_and_b32_e32 v2, 0x70, v58
	v_mov_b32_e32 v3, v1
	v_lshl_add_u64 v[4:5], v[4:5], 0, v[2:3]
	global_load_dwordx4 v[188:191], v[4:5], off
	v_add3_u32 v4, v14, v22, v2
	v_mov_b32_e32 v154, v4
	v_add_u32_e32 v4, s3, v16
	v_lshl_or_b32 v4, v4, 5, s0
	v_ashrrev_i32_e32 v5, 31, v4
	v_bfe_u32 v18, v15, 3, 7
	v_lshlrev_b64 v[4:5], 14, v[4:5]
	v_lshl_add_u64 v[4:5], s[58:59], 0, v[4:5]
	v_lshlrev_b32_e32 v14, 7, v18
	v_mov_b32_e32 v15, v1
	v_lshl_add_u64 v[4:5], v[4:5], 0, v[14:15]
	v_lshl_add_u64 v[4:5], v[4:5], 0, v[2:3]
	global_load_dwordx4 v[192:195], v[4:5], off
	v_mul_u32_u24_e32 v4, 0x90, v18
	v_add3_u32 v4, v8, v4, v2
	v_mov_b32_e32 v155, v4
	v_add_u32_e32 v4, s3, v12
	v_lshl_or_b32 v4, v4, 5, s0
	v_ashrrev_i32_e32 v5, 31, v4
	v_lshlrev_b64 v[4:5], 14, v[4:5]
	v_lshl_add_u64 v[4:5], s[58:59], 0, v[4:5]
	v_lshl_add_u64 v[4:5], v[4:5], 0, v[0:1]
	v_lshl_add_u64 v[4:5], v[4:5], 0, v[2:3]
	global_load_dwordx4 v[196:199], v[4:5], off
	v_add3_u32 v0, v9, v22, v2
	v_bfe_u32 v12, v10, 3, 7
	v_mov_b32_e32 v156, v0
	v_add_u32_e32 v0, s3, v11
	v_lshl_or_b32 v4, v0, 5, s0
	v_ashrrev_i32_e32 v5, 31, v4
	v_lshlrev_b64 v[4:5], 14, v[4:5]
	v_lshl_add_u64 v[4:5], s[58:59], 0, v[4:5]
	v_lshlrev_b32_e32 v0, 7, v12
	v_lshl_add_u64 v[4:5], v[4:5], 0, v[0:1]
	v_lshl_add_u64 v[4:5], v[4:5], 0, v[2:3]
	global_load_dwordx4 v[200:203], v[4:5], off
	v_mul_u32_u24_e32 v0, 0x90, v12
	v_add3_u32 v0, v13, v0, v2
	v_mov_b32_e32 v157, v0
	v_ashrrev_i32_e32 v0, 8, v44
	v_add_u32_e32 v18, s1, v0
	v_cvt_f32_i32_e32 v2, v18
	v_mad_i32_i24 v48, v0, s45, 0
	s_waitcnt vmcnt(7)
	ds_write_b128 v150, v[172:175] offset:18432
	s_waitcnt vmcnt(6)
	ds_write_b128 v151, v[176:179] offset:18432
	s_waitcnt vmcnt(5)
	ds_write_b128 v152, v[180:183] offset:18432
	s_waitcnt vmcnt(4)
	ds_write_b128 v153, v[184:187] offset:18432
	s_waitcnt vmcnt(3)
	ds_write_b128 v154, v[188:191] offset:35840
	s_waitcnt vmcnt(2)
	ds_write_b128 v155, v[192:195] offset:35840
	s_waitcnt vmcnt(1)
	ds_write_b128 v156, v[196:199] offset:35840
	s_waitcnt vmcnt(0)
	ds_write_b128 v157, v[200:203] offset:35840
	s_waitcnt lgkmcnt(0)
	s_barrier
; #define LAS __attribute__((address_space(3)))
; __device__ __forceinline__ unsigned pk2(float lo, float hi) { unsigned r; asm volatile("v_cvt_pk_bf16_f32 %0, %1, %2" : "=v"(r) : "v"(lo), "v"(hi)); return r; }
; __device__ __forceinline__ float fexp_(float x) { return __builtin_amdgcn_exp2f(x * 1.44269504089f); }
; #define MFMA(X, Y, C) __builtin_amdgcn_mfma_f32_16x16x32_bf16((X), (Y), (C), 0, 0, 0)
; __device__ __forceinline__ float ret_logg(int h) { return log1pf(-exp2f(-5.f - (float)h)); }
; __device__ void ret_m2(const Params& p, LAS unsigned char* lds, int l, int b, int c, int hp) {
;     ...
;     const int hh = wid >> 2, it = wid & 3, i0 = it * 16, h = 2 * hp + hh;
;     const float lg = ret_logg(h);
;     LAS bf16_t* Q = (LAS bf16_t*)(lds + hh * HB); LAS bf16_t* Kk = Q + 64 * 72; LAS bf16_t* V = (LAS bf16_t*)(lds + hh * HB + 18432);
;     LAS bf16_t* S = (LAS bf16_t*)(lds + hh * HB + 35840); LAS bf16_t* P = (LAS bf16_t*)(lds + hh * HB + 54272);
;     bf16x8 Yq[2];
; #pragma unroll
;     for (int kk = 0; kk < 2; ++kk) Yq[kk] = frag_row(Q, 72, i0, kk * 32, fr, fq);
;     const int irow = i0 + fr;
; #pragma unroll
;     for (int jt = 0; jt < 4; ++jt) {
;         f32x4 sc = {0.f, 0.f, 0.f, 0.f};
; #pragma unroll
;         for (int kk = 0; kk < 2; ++kk) sc = MFMA(frag_row(Kk, 72, jt * 16, kk * 32, fr, fq), Yq[kk], sc);
;         float v[4];
; #pragma unroll
;         for (int i = 0; i < 4; ++i) { const int j = jt * 16 + 4 * fq + i; v[i] = j <= irow ? sc[i] * fexp_((float)(irow - j) * lg) : 0.f; }
;         u32x2 w; w.x = pk2(v[0], v[1]); w.y = pk2(v[2], v[3]);
;         *(LAS u32x2*)(P + irow * 72 + jt * 16 + 4 * fq) = w;
;     }
	v_sub_f32_e32 v2, 0xc0a00000, v2
	v_cmp_gt_f32_e32 vcc, s46, v2
	v_bfe_u32 v0, v44, 4, 2
	s_nop 0
	v_cndmask_b32_e32 v3, 0, v230, vcc
	v_add_f32_e32 v2, v2, v3
	v_exp_f32_e32 v2, v2
	v_cndmask_b32_e32 v3, 0, v231, vcc
	v_ldexp_f32 v19, v2, v3
	v_sub_f32_e32 v4, 1.0, v19
	v_add_f32_e32 v2, -1.0, v4
	v_sub_f32_e32 v3, v2, v4
	v_add_f32_e32 v3, 1.0, v3
	v_sub_f32_e64 v2, -v19, v2
	v_add_f32_e32 v5, v2, v3
	v_frexp_mant_f32_e32 v2, v4
	v_cmp_gt_f32_e32 vcc, s47, v2
	v_cvt_f64_f32_e32 v[2:3], v4
	v_frexp_exp_i32_f64_e32 v2, v[2:3]
	v_subbrev_co_u32_e32 v12, vcc, 0, v2, vcc
	v_sub_u32_e32 v2, 0, v12
	v_ldexp_f32 v3, v4, v2
	v_add_f32_e32 v4, -1.0, v3
	v_add_f32_e32 v8, 1.0, v3
	v_ldexp_f32 v2, v5, v2
	v_add_f32_e32 v5, 1.0, v4
	v_add_f32_e32 v9, -1.0, v8
	v_sub_f32_e32 v5, v3, v5
	v_sub_f32_e32 v3, v3, v9
	v_add_f32_e32 v5, v2, v5
	v_add_f32_e32 v2, v2, v3
	v_add_f32_e32 v13, v8, v2
	v_rcp_f32_e32 v15, v13
	v_sub_f32_e32 v3, v13, v8
	v_sub_f32_e32 v14, v2, v3
	v_add_f32_e32 v3, v4, v5
	v_mul_f32_e32 v17, v3, v15
	v_sub_f32_e32 v2, v3, v4
	v_mul_f32_e32 v4, v13, v17
	v_fma_f32 v8, v17, v13, -v4
	v_fmac_f32_e32 v8, v17, v14
	v_sub_f32_e32 v16, v5, v2
	v_add_f32_e32 v2, v4, v8
	v_sub_f32_e32 v5, v3, v2
	v_pk_add_f32 v[10:11], v[2:3], v[4:5] neg_lo:[0,1] neg_hi:[0,1]
	v_mov_b32_e32 v9, v2
	v_pk_add_f32 v[2:3], v[10:11], v[8:9] neg_lo:[0,1] neg_hi:[0,1]
	v_cmp_nlt_f32_e64 s[0:1], 1.0, v19
	v_add_f32_e32 v3, v16, v3
	v_add_f32_e32 v2, v2, v3
	v_add_f32_e32 v3, v5, v2
	v_mul_f32_e32 v16, v15, v3
	v_mul_f32_e32 v4, v13, v16
	v_fma_f32 v8, v16, v13, -v4
	v_fmac_f32_e32 v8, v16, v14
	v_sub_f32_e32 v5, v5, v3
	v_add_f32_e32 v13, v2, v5
	v_add_f32_e32 v2, v4, v8
	v_sub_f32_e32 v5, v3, v2
	v_pk_add_f32 v[10:11], v[2:3], v[4:5] neg_lo:[0,1] neg_hi:[0,1]
	v_mov_b32_e32 v9, v2
	v_pk_add_f32 v[2:3], v[10:11], v[8:9] neg_lo:[0,1] neg_hi:[0,1]
	v_cmp_gt_f32_e32 vcc, s50, v19
	v_add_f32_e32 v3, v13, v3
	v_add_f32_e32 v2, v2, v3
	v_add_f32_e32 v3, v17, v16
	v_add_f32_e32 v2, v5, v2
	v_sub_f32_e32 v4, v3, v17
	v_mul_f32_e32 v2, v15, v2
	v_sub_f32_e32 v4, v16, v4
	v_add_f32_e32 v4, v4, v2
	v_add_f32_e32 v8, v3, v4
	v_mul_f32_e32 v9, v8, v8
	v_fmamk_f32 v2, v9, 0x3e9b6dac, v225
	v_fmaak_f32 v171, v9, v2, 0x3f2aaada
	v_cvt_f32_i32_e32 v2, v12
	v_sub_f32_e32 v3, v8, v3
	v_sub_f32_e32 v3, v4, v3
	v_ldexp_f32 v10, v3, 1
	v_mul_f32_e32 v3, v8, v9
	v_ldexp_f32 v5, v8, 1
	v_pk_mul_f32 v[8:9], v[2:3], v[170:171]
	s_nop 0
	v_fma_f32 v4, v2, s51, -v8
	v_fmac_f32_e32 v4, 0xb102e308, v2
	v_pk_add_f32 v[2:3], v[8:9], v[4:5]
	s_nop 0
	v_sub_f32_e32 v5, v3, v5
	v_sub_f32_e32 v5, v9, v5
	v_add_f32_e32 v11, v10, v5
	v_mov_b32_e32 v10, v8
	v_pk_add_f32 v[8:9], v[2:3], v[8:9] neg_lo:[0,1] neg_hi:[0,1]
	v_pk_add_f32 v[12:13], v[2:3], v[10:11]
	v_mov_b32_e32 v5, v2
	v_mov_b32_e32 v9, v13
	v_pk_add_f32 v[14:15], v[4:5], v[8:9] neg_lo:[0,1] neg_hi:[0,1]
	v_pk_add_f32 v[4:5], v[4:5], v[8:9]
	v_mov_b32_e32 v10, v11
	v_pk_add_f32 v[8:9], v[4:5], v[2:3] op_sel:[1,0] op_sel_hi:[0,1] neg_lo:[0,1] neg_hi:[0,1]
	v_pk_add_f32 v[16:17], v[12:13], v[8:9] op_sel_hi:[1,0] neg_lo:[0,1] neg_hi:[0,1]
	v_mov_b32_e32 v12, v13
	v_mov_b32_e32 v13, v5
	v_pk_mov_b32 v[8:9], v[2:3], v[8:9] op_sel:[1,0]
	v_mov_b32_e32 v11, v2
	v_pk_add_f32 v[8:9], v[12:13], v[8:9] neg_lo:[0,1] neg_hi:[0,1]
	v_mov_b32_e32 v16, v14
	v_pk_add_f32 v[2:3], v[10:11], v[8:9] neg_lo:[0,1] neg_hi:[0,1]
	v_mov_b32_e32 v15, v5
	v_pk_add_f32 v[8:9], v[16:17], v[2:3]
	s_nop 0
	v_pk_add_f32 v[10:11], v[8:9], v[8:9] op_sel:[0,1] op_sel_hi:[1,0]
	s_nop 0
	v_pk_add_f32 v[4:5], v[4:5], v[10:11] op_sel:[1,0] op_sel_hi:[0,1]
	v_mov_b32_e32 v9, v4
	v_pk_add_f32 v[12:13], v[8:9], v[14:15] neg_lo:[0,1] neg_hi:[0,1]
	v_mov_b32_e32 v3, v10
	v_sub_f32_e32 v5, v8, v12
	v_pk_add_f32 v[10:11], v[2:3], v[12:13] neg_lo:[0,1] neg_hi:[0,1]
	v_sub_f32_e32 v5, v14, v5
	v_add_f32_e32 v5, v10, v5
	v_add_f32_e32 v5, v5, v11
	v_add_f32_e32 v4, v4, v5
	v_cndmask_b32_e64 v4, v232, v4, s[0:1]
	v_cmp_neq_f32_e64 s[0:1], 1.0, v19
	v_mad_u32_u24 v3, v49, s43, v48
	v_and_b32_e32 v2, 48, v44
	v_cndmask_b32_e64 v4, v233, v4, s[0:1]
	v_cndmask_b32_e64 v51, v4, -v19, vcc
	v_mul_u32_u24_e32 v4, 0x90, v6
	v_add_u32_e32 v50, v3, v2
	v_add3_u32 v91, v48, v2, v4
	ds_read_b128 v[34:37], v50
	ds_read_b128 v[30:33], v50 offset:64
	ds_read_b128 v[4:7], v91 offset:9216
	ds_read_b128 v[8:11], v91 offset:9280
	s_waitcnt lgkmcnt(1)
	v_mfma_f32_16x16x32_bf16 v[4:7], v[4:7], v[34:37], 0
	v_lshlrev_b32_e32 v12, 2, v0
	v_lshlrev_b32_e32 v0, 3, v0
	v_add_u32_e32 v3, v3, v0
	s_waitcnt lgkmcnt(0)
	v_mfma_f32_16x16x32_bf16 v[4:7], v[8:11], v[30:33], v[4:7]
	v_sub_co_u32_e32 v8, vcc, v49, v12
	v_cvt_f32_u32_e32 v8, v8
	v_bfe_u32 v44, v44, 2, 2
	v_or_b32_e32 v44, v0, v44
	v_mul_u32_u24_e32 v44, 0x110, v44
	v_mul_f32_e32 v8, v51, v8
	v_mul_f32_e32 v8, 0x3fb8aa3b, v8
	v_exp_f32_e32 v8, v8
	s_nop 0
	v_mul_f32_e32 v4, v8, v4
	v_xad_u32 v8, v12, -1, v49
	v_cvt_f32_u32_e32 v8, v8
	v_cndmask_b32_e64 v4, v4, 0, vcc
	v_cmp_lt_u32_e32 vcc, v12, v49
	v_mul_f32_e32 v8, v51, v8
	v_mul_f32_e32 v8, 0x3fb8aa3b, v8
	v_exp_f32_e32 v8, v8
	s_nop 0
	v_mul_f32_e32 v5, v8, v5
	v_or_b32_e32 v8, 2, v12
	v_cndmask_b32_e32 v5, 0, v5, vcc
	v_sub_co_u32_e32 v8, vcc, v49, v8
	v_cvt_f32_u32_e32 v8, v8
	v_cvt_pk_bf16_f32 v4, v4, v5
	v_mul_f32_e32 v8, v51, v8
	v_mul_f32_e32 v8, 0x3fb8aa3b, v8
	v_exp_f32_e32 v8, v8
	s_nop 0
	v_mul_f32_e32 v6, v8, v6
	v_or_b32_e32 v8, 3, v12
	v_cndmask_b32_e64 v6, v6, 0, vcc
	v_sub_co_u32_e32 v8, vcc, v49, v8
	v_cvt_f32_u32_e32 v8, v8
	v_mul_f32_e32 v8, v51, v8
	v_mul_f32_e32 v8, 0x3fb8aa3b, v8
	v_exp_f32_e32 v8, v8
	s_nop 0
	v_mul_f32_e32 v7, v8, v7
	v_cndmask_b32_e64 v7, v7, 0, vcc
	v_cvt_pk_bf16_f32 v5, v6, v7
	ds_write_b64 v3, v[4:5] offset:54272
	ds_read_b128 v[4:7], v91 offset:11520
	ds_read_b128 v[8:11], v91 offset:11584
	s_waitcnt lgkmcnt(1)
; #define LAS __attribute__((address_space(3)))
; __device__ __forceinline__ unsigned pk2(float lo, float hi) { unsigned r; asm volatile("v_cvt_pk_bf16_f32 %0, %1, %2" : "=v"(r) : "v"(lo), "v"(hi)); return r; }
; __device__ __forceinline__ float fexp_(float x) { return __builtin_amdgcn_exp2f(x * 1.44269504089f); }
; #define MFMA(X, Y, C) __builtin_amdgcn_mfma_f32_16x16x32_bf16((X), (Y), (C), 0, 0, 0)
; __device__ void ret_m2(const Params& p, LAS unsigned char* lds, int l, int b, int c, int hp) {
;     ...
;     for (int jt = 0; jt < 4; ++jt) {
;         f32x4 sc = {0.f, 0.f, 0.f, 0.f};
; #pragma unroll
;         for (int kk = 0; kk < 2; ++kk) sc = MFMA(frag_row(Kk, 72, jt * 16, kk * 32, fr, fq), Yq[kk], sc);
;         float v[4];
; #pragma unroll
;         for (int i = 0; i < 4; ++i) { const int j = jt * 16 + 4 * fq + i; v[i] = j <= irow ? sc[i] * fexp_((float)(irow - j) * lg) : 0.f; }
;         u32x2 w; w.x = pk2(v[0], v[1]); w.y = pk2(v[2], v[3]);
;         *(LAS u32x2*)(P + irow * 72 + jt * 16 + 4 * fq) = w;
;     }
;     __syncthreads();
;     const size_t t = row0 + irow;
;     u32x2 rgv[8]; f32x4 ngv[8];
; #pragma unroll
;     for (int vt = 0; vt < 8; ++vt) { rgv[vt] = *(const u32x2*)(proj + t * NPROJ + PC_RG + h * 128 + vt * 16 + 4 * fq); ngv[vt] = *(const f32x4*)(p.in[17] + l * 512 + h * 128 + vt * 16 + 4 * fq); }
;     bf16x8 Yp[2];
; #pragma unroll
;     for (int kk = 0; kk < 2; ++kk) Yp[kk] = frag_row(P, 72, i0, kk * 32, fr, fq);
;     const float qdec = fexp_((float)(irow + 1) * lg);
	v_mfma_f32_16x16x32_bf16 v[4:7], v[4:7], v[34:37], 0
	s_waitcnt lgkmcnt(0)
	v_mfma_f32_16x16x32_bf16 v[4:7], v[8:11], v[30:33], v[4:7]
	v_or_b32_e32 v8, 16, v12
	v_sub_co_u32_e32 v8, vcc, v49, v8
	v_cvt_f32_u32_e32 v8, v8
	v_mul_f32_e32 v8, v51, v8
	v_mul_f32_e32 v8, 0x3fb8aa3b, v8
	v_exp_f32_e32 v8, v8
	s_nop 1
	v_mul_f32_e32 v4, v8, v4
	v_or_b32_e32 v8, 17, v12
	v_cndmask_b32_e64 v4, v4, 0, vcc
	v_sub_co_u32_e32 v8, vcc, v49, v8
	v_cvt_f32_u32_e32 v8, v8
	v_mul_f32_e32 v8, v51, v8
	v_mul_f32_e32 v8, 0x3fb8aa3b, v8
	v_exp_f32_e32 v8, v8
	s_nop 0
	v_mul_f32_e32 v5, v8, v5
	v_or_b32_e32 v8, 18, v12
	v_cndmask_b32_e64 v5, v5, 0, vcc
	v_sub_co_u32_e32 v8, vcc, v49, v8
	v_cvt_f32_u32_e32 v8, v8
	v_cvt_pk_bf16_f32 v4, v4, v5
	v_mul_f32_e32 v8, v51, v8
	v_mul_f32_e32 v8, 0x3fb8aa3b, v8
	v_exp_f32_e32 v8, v8
	s_nop 0
	v_mul_f32_e32 v6, v8, v6
	v_or_b32_e32 v8, 19, v12
	v_cndmask_b32_e64 v6, v6, 0, vcc
	v_sub_co_u32_e32 v8, vcc, v49, v8
	v_cvt_f32_u32_e32 v8, v8
	v_mul_f32_e32 v8, v51, v8
	v_mul_f32_e32 v8, 0x3fb8aa3b, v8
	v_exp_f32_e32 v8, v8
	s_nop 0
	v_mul_f32_e32 v7, v8, v7
	v_cndmask_b32_e64 v7, v7, 0, vcc
	v_cvt_pk_bf16_f32 v5, v6, v7
	ds_write_b64 v3, v[4:5] offset:54304
	ds_read_b128 v[4:7], v91 offset:13824
	ds_read_b128 v[8:11], v91 offset:13888
	s_waitcnt lgkmcnt(1)
	v_mfma_f32_16x16x32_bf16 v[4:7], v[4:7], v[34:37], 0
	s_waitcnt lgkmcnt(0)
	v_mfma_f32_16x16x32_bf16 v[4:7], v[8:11], v[30:33], v[4:7]
	v_or_b32_e32 v8, 32, v12
	v_sub_co_u32_e32 v8, vcc, v49, v8
	v_cvt_f32_u32_e32 v8, v8
	v_mul_f32_e32 v8, v51, v8
	v_mul_f32_e32 v8, 0x3fb8aa3b, v8
	v_exp_f32_e32 v8, v8
	s_nop 1
	v_mul_f32_e32 v4, v8, v4
	v_or_b32_e32 v8, 33, v12
	v_cndmask_b32_e64 v4, v4, 0, vcc
	v_sub_co_u32_e32 v8, vcc, v49, v8
	v_cvt_f32_u32_e32 v8, v8
	v_mul_f32_e32 v8, v51, v8
	v_mul_f32_e32 v8, 0x3fb8aa3b, v8
	v_exp_f32_e32 v8, v8
	s_nop 0
	v_mul_f32_e32 v5, v8, v5
	v_or_b32_e32 v8, 34, v12
	v_cndmask_b32_e64 v5, v5, 0, vcc
	v_sub_co_u32_e32 v8, vcc, v49, v8
	v_cvt_f32_u32_e32 v8, v8
	v_cvt_pk_bf16_f32 v4, v4, v5
	v_mul_f32_e32 v8, v51, v8
	v_mul_f32_e32 v8, 0x3fb8aa3b, v8
	v_exp_f32_e32 v8, v8
	s_nop 0
	v_mul_f32_e32 v6, v8, v6
	v_or_b32_e32 v8, 35, v12
	v_cndmask_b32_e64 v6, v6, 0, vcc
	v_sub_co_u32_e32 v8, vcc, v49, v8
	v_cvt_f32_u32_e32 v8, v8
	v_mul_f32_e32 v8, v51, v8
	v_mul_f32_e32 v8, 0x3fb8aa3b, v8
	v_exp_f32_e32 v8, v8
	s_nop 0
	v_mul_f32_e32 v7, v8, v7
	v_cndmask_b32_e64 v7, v7, 0, vcc
	v_cvt_pk_bf16_f32 v5, v6, v7
	ds_write_b64 v3, v[4:5] offset:54336
	ds_read_b128 v[4:7], v91 offset:16128
	ds_read_b128 v[8:11], v91 offset:16192
	s_waitcnt lgkmcnt(1)
	v_mfma_f32_16x16x32_bf16 v[4:7], v[4:7], v[34:37], 0
	s_waitcnt lgkmcnt(0)
	v_mfma_f32_16x16x32_bf16 v[4:7], v[8:11], v[30:33], v[4:7]
	v_or_b32_e32 v8, 48, v12
	v_sub_co_u32_e32 v8, vcc, v49, v8
	v_cvt_f32_u32_e32 v8, v8
	v_mul_f32_e32 v8, v51, v8
	v_mul_f32_e32 v8, 0x3fb8aa3b, v8
	v_exp_f32_e32 v8, v8
	s_nop 1
	v_mul_f32_e32 v4, v8, v4
	v_or_b32_e32 v8, 49, v12
	v_cndmask_b32_e64 v4, v4, 0, vcc
	v_sub_co_u32_e32 v8, vcc, v49, v8
	v_cvt_f32_u32_e32 v8, v8
	v_mul_f32_e32 v8, v51, v8
	v_mul_f32_e32 v8, 0x3fb8aa3b, v8
	v_exp_f32_e32 v8, v8
	s_nop 0
	v_mul_f32_e32 v5, v8, v5
	v_or_b32_e32 v8, 50, v12
	v_cndmask_b32_e64 v5, v5, 0, vcc
	v_sub_co_u32_e32 v8, vcc, v49, v8
	v_cvt_f32_u32_e32 v8, v8
	v_cvt_pk_bf16_f32 v4, v4, v5
	v_mul_f32_e32 v8, v51, v8
	v_mul_f32_e32 v8, 0x3fb8aa3b, v8
	v_exp_f32_e32 v8, v8
	s_nop 0
	v_mul_f32_e32 v6, v8, v6
	v_or_b32_e32 v8, 51, v12
	v_cndmask_b32_e64 v6, v6, 0, vcc
	v_sub_co_u32_e32 v8, vcc, v49, v8
	v_cvt_f32_u32_e32 v8, v8
	v_add_u32_e32 v49, 1, v49
	v_cvt_f32_ubyte0_e32 v49, v49
	v_mul_f32_e32 v49, v51, v49
	v_mul_f32_e32 v8, v51, v8
	v_mul_f32_e32 v8, 0x3fb8aa3b, v8
	v_exp_f32_e32 v8, v8
	v_mul_f32_e32 v49, 0x3fb8aa3b, v49
	v_exp_f32_e32 v112, v49
	v_mul_f32_e32 v7, v8, v7
	v_cndmask_b32_e64 v7, v7, 0, vcc
	v_cvt_pk_bf16_f32 v5, v6, v7
	v_lshlrev_b32_e32 v8, 7, v18
	ds_write_b64 v3, v[4:5] offset:54368
	v_lshlrev_b64 v[4:5], 13, v[80:81]
	v_ashrrev_i32_e32 v9, 31, v8
	v_lshl_add_u64 v[4:5], s[34:35], 0, v[4:5]
	v_lshlrev_b64 v[82:83], 1, v[8:9]
	v_lshl_add_u64 v[4:5], v[4:5], 0, v[82:83]
	v_lshl_add_u64 v[6:7], v[4:5], 0, v[0:1]
	v_lshl_add_u64 v[4:5], v[6:7], 0, s[56:57]
	v_lshl_add_u64 v[8:9], v[8:9], 2, s[40:41]
	v_mov_b32_e32 v3, v1
	v_add_co_u32_e32 v6, vcc, s42, v6
	v_lshl_add_u64 v[2:3], v[8:9], 0, v[2:3]
	s_nop 0
	v_addc_co_u32_e32 v7, vcc, 0, v7, vcc
	v_add3_u32 v81, v48, v45, v44
	s_waitcnt lgkmcnt(0)
	s_barrier
; __device__ __forceinline__ float fexp_(float x) { return __builtin_amdgcn_exp2f(x * 1.44269504089f); }
; #define MFMA(X, Y, C) __builtin_amdgcn_mfma_f32_16x16x32_bf16((X), (Y), (C), 0, 0, 0)
; __device__ void ret_m2(const Params& p, LAS unsigned char* lds, int l, int b, int c, int hp) {
;     ...
;     const size_t t = row0 + irow;
;     u32x2 rgv[8]; f32x4 ngv[8];
; #pragma unroll
;     for (int vt = 0; vt < 8; ++vt) { rgv[vt] = *(const u32x2*)(proj + t * NPROJ + PC_RG + h * 128 + vt * 16 + 4 * fq); ngv[vt] = *(const f32x4*)(p.in[17] + l * 512 + h * 128 + vt * 16 + 4 * fq); }
;     bf16x8 Yp[2];
; #pragma unroll
;     for (int kk = 0; kk < 2; ++kk) Yp[kk] = frag_row(P, 72, i0, kk * 32, fr, fq);
;     const float qdec = fexp_((float)(irow + 1) * lg);
;     f32x4 o[8]; float ssq = 0.f;
; #pragma unroll
;     for (int vt = 0; vt < 8; ++vt) {
;         f32x4 a1 = {0.f, 0.f, 0.f, 0.f}, a2 = {0.f, 0.f, 0.f, 0.f};
; #pragma unroll
;         for (int kk = 0; kk < 2; ++kk) { a1 = MFMA(frag_tr(V, 136, kk * 32, vt * 16, fr, fq), Yp[kk], a1); a2 = MFMA(frag_row(S, 72, vt * 16, kk * 32, fr, fq), Yq[kk], a2); }
;         o[vt] = a1 + a2 * qdec;
;         ssq += o[vt][0] * o[vt][0] + o[vt][1] * o[vt][1] + o[vt][2] * o[vt][2] + o[vt][3] * o[vt][3];
;     }
	global_load_dwordx2 v[84:85], v[6:7], off
	global_load_dwordx4 v[38:41], v[2:3], off
	global_load_dwordx2 v[78:79], v[4:5], off offset:32
	global_load_dwordx4 v[26:29], v[2:3], off offset:64
	global_load_dwordx2 v[72:73], v[4:5], off offset:64
	global_load_dwordx4 v[22:25], v[2:3], off offset:128
	global_load_dwordx2 v[66:67], v[4:5], off offset:96
	global_load_dwordx4 v[18:21], v[2:3], off offset:192
	global_load_dwordx2 v[58:59], v[4:5], off offset:128
	global_load_dwordx4 v[14:17], v[2:3], off offset:256
	global_load_dwordx2 v[52:53], v[4:5], off offset:160
	global_load_dwordx4 v[10:13], v[2:3], off offset:320
	global_load_dwordx2 v[46:47], v[4:5], off offset:192
	global_load_dwordx4 v[6:9], v[2:3], off offset:384
	global_load_dwordx2 v[42:43], v[4:5], off offset:224
	s_nop 0
	global_load_dwordx4 v[2:5], v[2:3], off offset:448
	ds_read_b128 v[92:95], v50 offset:54272
	ds_read_b128 v[96:99], v50 offset:54336
	ds_read_b64_tr_b16 v[50:51], v81 offset:19520
	ds_read_b64_tr_b16 v[48:49], v81 offset:18432
	ds_read_b64_tr_b16 v[54:55], v81 offset:18464
	ds_read_b128 v[60:63], v91 offset:35840
	ds_read_b64_tr_b16 v[68:69], v81 offset:27136
	ds_read_b64_tr_b16 v[70:71], v81 offset:28224
	s_waitcnt lgkmcnt(4)
	v_mfma_f32_16x16x32_bf16 v[48:51], v[48:51], v[92:95], 0
	ds_read_b64_tr_b16 v[56:57], v81 offset:19552
	s_waitcnt lgkmcnt(1)
	v_mfma_f32_16x16x32_bf16 v[48:51], v[68:71], v[96:99], v[48:51]
	ds_read_b128 v[68:71], v91 offset:35904
	v_mfma_f32_16x16x32_bf16 v[60:63], v[60:63], v[34:37], 0
	s_waitcnt lgkmcnt(0)
	v_mfma_f32_16x16x32_bf16 v[60:63], v[68:71], v[30:33], v[60:63]
	s_nop 7
	v_pk_fma_f32 v[88:89], v[112:113], v[60:61], v[48:49] op_sel_hi:[0,1,1]
	v_pk_fma_f32 v[86:87], v[112:113], v[62:63], v[50:51] op_sel_hi:[0,1,1]
	v_mul_f32_e32 v48, v89, v89
	v_fmac_f32_e32 v48, v88, v88
	v_pk_mul_f32 v[44:45], v[86:87], v[86:87]
	s_nop 0
	v_add_f32_e32 v44, v44, v48
	v_mfma_f32_16x16x32_bf16 v[48:51], v[54:57], v[92:95], 0
	ds_read_b128 v[54:57], v91 offset:38144
	ds_read_b64_tr_b16 v[60:61], v81 offset:27168
	ds_read_b64_tr_b16 v[62:63], v81 offset:28256
	v_add_f32_e32 v64, v45, v44
	s_waitcnt lgkmcnt(0)
	v_mfma_f32_16x16x32_bf16 v[48:51], v[60:63], v[96:99], v[48:51]
	ds_read_b128 v[60:63], v91 offset:38208
	v_mfma_f32_16x16x32_bf16 v[54:57], v[54:57], v[34:37], 0
	s_waitcnt lgkmcnt(0)
	v_mfma_f32_16x16x32_bf16 v[54:57], v[60:63], v[30:33], v[54:57]
	s_nop 7
	v_pk_fma_f32 v[76:77], v[112:113], v[54:55], v[48:49] op_sel_hi:[0,1,1]
	v_pk_fma_f32 v[74:75], v[112:113], v[56:57], v[50:51] op_sel_hi:[0,1,1]
	v_mul_f32_e32 v48, v77, v77
	v_fmac_f32_e32 v48, v76, v76
	v_pk_mul_f32 v[44:45], v[74:75], v[74:75]
	s_nop 0
	v_add_f32_e32 v44, v44, v48
	ds_read_b64_tr_b16 v[48:49], v81 offset:18496
	ds_read_b64_tr_b16 v[50:51], v81 offset:19584
	ds_read_b128 v[54:57], v91 offset:40448
	ds_read_b64_tr_b16 v[60:61], v81 offset:27200
	ds_read_b64_tr_b16 v[62:63], v81 offset:28288
	s_waitcnt lgkmcnt(3)
	v_mfma_f32_16x16x32_bf16 v[48:51], v[48:51], v[92:95], 0
	v_add_f32_e32 v44, v45, v44
	v_add_f32_e32 v64, v64, v44
	s_waitcnt lgkmcnt(0)
	v_mfma_f32_16x16x32_bf16 v[48:51], v[60:63], v[96:99], v[48:51]
	ds_read_b128 v[60:63], v91 offset:40512
	v_mfma_f32_16x16x32_bf16 v[54:57], v[54:57], v[34:37], 0
	s_waitcnt lgkmcnt(0)
	v_mfma_f32_16x16x32_bf16 v[54:57], v[60:63], v[30:33], v[54:57]
	s_nop 7
	v_pk_fma_f32 v[70:71], v[112:113], v[54:55], v[48:49] op_sel_hi:[0,1,1]
	v_pk_fma_f32 v[68:69], v[112:113], v[56:57], v[50:51] op_sel_hi:[0,1,1]
	v_mul_f32_e32 v48, v71, v71
	v_fmac_f32_e32 v48, v70, v70
	v_pk_mul_f32 v[44:45], v[68:69], v[68:69]
	s_nop 0
	v_add_f32_e32 v44, v44, v48
	ds_read_b64_tr_b16 v[48:49], v81 offset:18528
	ds_read_b64_tr_b16 v[50:51], v81 offset:19616
	ds_read_b128 v[54:57], v91 offset:42752
	ds_read_b64_tr_b16 v[60:61], v81 offset:27232
	ds_read_b64_tr_b16 v[62:63], v81 offset:28320
	s_waitcnt lgkmcnt(3)
	v_mfma_f32_16x16x32_bf16 v[48:51], v[48:51], v[92:95], 0
	v_add_f32_e32 v44, v45, v44
	v_add_f32_e32 v100, v64, v44
	s_waitcnt lgkmcnt(0)
	v_mfma_f32_16x16x32_bf16 v[48:51], v[60:63], v[96:99], v[48:51]
	ds_read_b128 v[60:63], v91 offset:42816
	v_mfma_f32_16x16x32_bf16 v[54:57], v[54:57], v[34:37], 0
	s_waitcnt lgkmcnt(0)
	v_mfma_f32_16x16x32_bf16 v[54:57], v[60:63], v[30:33], v[54:57]
	s_nop 7
	v_pk_fma_f32 v[64:65], v[112:113], v[54:55], v[48:49] op_sel_hi:[0,1,1]
	v_pk_fma_f32 v[62:63], v[112:113], v[56:57], v[50:51] op_sel_hi:[0,1,1]
	v_pk_mul_f32 v[48:49], v[64:65], v[64:65]
	v_pk_mul_f32 v[44:45], v[62:63], v[62:63]
	v_add_f32_e32 v48, v48, v49
	v_add_f32_e32 v44, v44, v48
	ds_read_b64_tr_b16 v[48:49], v81 offset:18560
	ds_read_b64_tr_b16 v[50:51], v81 offset:19648
	v_add_f32_e32 v44, v45, v44
	v_add_f32_e32 v108, v100, v44
	ds_read_b128 v[54:57], v91 offset:45056
	ds_read_b64_tr_b16 v[100:101], v81 offset:27264
	ds_read_b64_tr_b16 v[102:103], v81 offset:28352
	s_waitcnt lgkmcnt(3)
	v_mfma_f32_16x16x32_bf16 v[48:51], v[48:51], v[92:95], 0
	s_waitcnt lgkmcnt(0)
	v_mfma_f32_16x16x32_bf16 v[48:51], v[100:103], v[96:99], v[48:51]
	ds_read_b128 v[100:103], v91 offset:45120
	v_mfma_f32_16x16x32_bf16 v[54:57], v[54:57], v[34:37], 0
	s_waitcnt lgkmcnt(0)
	v_mfma_f32_16x16x32_bf16 v[54:57], v[100:103], v[30:33], v[54:57]
	s_nop 7
	v_pk_fma_f32 v[56:57], v[112:113], v[56:57], v[50:51] op_sel_hi:[0,1,1]
	v_pk_fma_f32 v[60:61], v[112:113], v[54:55], v[48:49] op_sel_hi:[0,1,1]
	ds_read_b64_tr_b16 v[48:49], v81 offset:18592
	ds_read_b64_tr_b16 v[50:51], v81 offset:19680
	ds_read_b128 v[100:103], v91 offset:47360
	ds_read_b64_tr_b16 v[104:105], v81 offset:27296
	ds_read_b64_tr_b16 v[106:107], v81 offset:28384
	s_waitcnt lgkmcnt(3)
; __device__ __forceinline__ unsigned pk2(float lo, float hi) { unsigned r; asm volatile("v_cvt_pk_bf16_f32 %0, %1, %2" : "=v"(r) : "v"(lo), "v"(hi)); return r; }
; __device__ __forceinline__ float siluf_(float x) { return x * __builtin_amdgcn_rcpf(1.f + fexp_(-x)); }
; __device__ __forceinline__ float shfl_xor_(float v, int o, int lane) { return shfl_idx(v, lane ^ o); }
; #define MFMA(X, Y, C) __builtin_amdgcn_mfma_f32_16x16x32_bf16((X), (Y), (C), 0, 0, 0)
; __device__ void ret_m2(const Params& p, LAS unsigned char* lds, int l, int b, int c, int hp) {
;     ...
;     for (int vt = 0; vt < 8; ++vt) {
;         f32x4 a1 = {0.f, 0.f, 0.f, 0.f}, a2 = {0.f, 0.f, 0.f, 0.f};
; #pragma unroll
;         for (int kk = 0; kk < 2; ++kk) { a1 = MFMA(frag_tr(V, 136, kk * 32, vt * 16, fr, fq), Yp[kk], a1); a2 = MFMA(frag_row(S, 72, vt * 16, kk * 32, fr, fq), Yq[kk], a2); }
;         o[vt] = a1 + a2 * qdec;
;         ssq += o[vt][0] * o[vt][0] + o[vt][1] * o[vt][1] + o[vt][2] * o[vt][2] + o[vt][3] * o[vt][3];
;     }
;     ssq += shfl_xor_(ssq, 16, lane); ssq += shfl_xor_(ssq, 32, lane);
;     const float rstd = rsqrtf(ssq * (1.f / 128.f) + EPS);
; #pragma unroll
;     for (int vt = 0; vt < 8; ++vt) {
;         const int v = vt * 16 + 4 * fq;
;         float gt[4]; unpack4(rgv[vt], gt);
;         const f32x4 ng = ngv[vt];
;         float y[4];
; #pragma unroll
;         for (int i = 0; i < 4; ++i) y[i] = siluf_(gt[i]) * (o[vt][i] * rstd * ng[i]);
;         u32x2 w; w.x = pk2(y[0], y[1]); w.y = pk2(y[2], y[3]);
;         *(u32x2*)(mix + t * DMIX + 512 + h * 128 + v) = w;
;     }
	v_mfma_f32_16x16x32_bf16 v[48:51], v[48:51], v[92:95], 0
	v_mov_b32_e32 v44, v60
	s_waitcnt lgkmcnt(0)
	v_mfma_f32_16x16x32_bf16 v[48:51], v[104:107], v[96:99], v[48:51]
	ds_read_b128 v[104:107], v91 offset:47424
	v_mfma_f32_16x16x32_bf16 v[100:103], v[100:103], v[34:37], 0
	s_waitcnt lgkmcnt(0)
	v_mfma_f32_16x16x32_bf16 v[100:103], v[104:107], v[30:33], v[100:103]
	s_nop 7
	v_pk_fma_f32 v[54:55], v[112:113], v[100:101], v[48:49] op_sel_hi:[0,1,1]
	v_mov_b32_e32 v48, v61
	v_mov_b32_e32 v49, v55
	v_pk_fma_f32 v[50:51], v[112:113], v[102:103], v[50:51] op_sel_hi:[0,1,1]
	v_mov_b32_e32 v45, v54
	v_pk_mul_f32 v[48:49], v[48:49], v[48:49]
	ds_read_b64_tr_b16 v[100:101], v81 offset:18624
	ds_read_b64_tr_b16 v[102:103], v81 offset:19712
	v_pk_fma_f32 v[44:45], v[44:45], v[44:45], v[48:49]
	v_mov_b32_e32 v48, v56
	v_mov_b32_e32 v49, v50
	v_pk_fma_f32 v[44:45], v[48:49], v[48:49], v[44:45]
	v_mov_b32_e32 v48, v57
	v_mov_b32_e32 v49, v51
	v_pk_fma_f32 v[44:45], v[48:49], v[48:49], v[44:45]
	ds_read_b128 v[104:107], v91 offset:49664
	v_add_f32_e32 v44, v108, v44
	ds_read_b64_tr_b16 v[108:109], v81 offset:27328
	ds_read_b64_tr_b16 v[110:111], v81 offset:28416
	s_waitcnt lgkmcnt(3)
	v_mfma_f32_16x16x32_bf16 v[100:103], v[100:103], v[92:95], 0
	v_add_f32_e32 v113, v44, v45
	s_waitcnt lgkmcnt(0)
	v_mfma_f32_16x16x32_bf16 v[100:103], v[108:111], v[96:99], v[100:103]
	ds_read_b128 v[108:111], v91 offset:49728
	v_mfma_f32_16x16x32_bf16 v[104:107], v[104:107], v[34:37], 0
	s_waitcnt lgkmcnt(0)
	v_mfma_f32_16x16x32_bf16 v[104:107], v[108:111], v[30:33], v[104:107]
	s_nop 7
	v_pk_fma_f32 v[44:45], v[112:113], v[106:107], v[102:103] op_sel_hi:[0,1,1]
	v_pk_fma_f32 v[48:49], v[112:113], v[104:105], v[100:101] op_sel_hi:[0,1,1]
	ds_read_b64_tr_b16 v[100:101], v81 offset:18656
	ds_read_b64_tr_b16 v[102:103], v81 offset:19744
	s_waitcnt lgkmcnt(0)
	v_mfma_f32_16x16x32_bf16 v[92:95], v[100:103], v[92:95], 0
	ds_read_b128 v[100:103], v91 offset:51968
	s_waitcnt lgkmcnt(0)
	v_mfma_f32_16x16x32_bf16 v[34:37], v[100:103], v[34:37], 0
	ds_read_b64_tr_b16 v[100:101], v81 offset:27360
	ds_read_b64_tr_b16 v[102:103], v81 offset:28448
	s_waitcnt lgkmcnt(0)
	v_mfma_f32_16x16x32_bf16 v[92:95], v[100:103], v[96:99], v[92:95]
	ds_read_b128 v[96:99], v91 offset:52032
	s_waitcnt lgkmcnt(0)
	v_mfma_f32_16x16x32_bf16 v[32:35], v[96:99], v[30:33], v[34:37]
	s_nop 2
	v_mov_b32_e32 v36, v49
	s_nop 3
	v_pk_fma_f32 v[32:33], v[112:113], v[32:33], v[92:93] op_sel_hi:[0,1,1]
	v_mov_b32_e32 v37, v33
	v_pk_fma_f32 v[30:31], v[112:113], v[34:35], v[94:95] op_sel_hi:[0,1,1]
	v_mov_b32_e32 v34, v48
	v_mov_b32_e32 v35, v32
	v_pk_mul_f32 v[36:37], v[36:37], v[36:37]
	s_waitcnt vmcnt(14)
	v_mov_b32_e32 v93, v38
	v_pk_fma_f32 v[34:35], v[34:35], v[34:35], v[36:37]
	v_mov_b32_e32 v36, v44
	v_mov_b32_e32 v37, v30
	v_pk_fma_f32 v[34:35], v[36:37], v[36:37], v[34:35]
	v_mov_b32_e32 v36, v45
	v_mov_b32_e32 v37, v31
	v_pk_fma_f32 v[34:35], v[36:37], v[36:37], v[34:35]
	s_nop 0
	v_add_f32_e32 v34, v113, v34
	v_add_f32_e32 v34, v34, v35
	v_lshlrev_b32_e32 v35, 2, v90
	v_xor_b32_e32 v36, 64, v35
	ds_bpermute_b32 v36, v36, v34
	v_xor_b32_e32 v35, 0x80, v35
	s_waitcnt lgkmcnt(0)
	v_add_f32_e32 v34, v34, v36
	ds_bpermute_b32 v35, v35, v34
	v_lshlrev_b32_e32 v36, 16, v84
	v_mul_f32_e32 v37, 0xbfb8aa3b, v36
	v_exp_f32_e32 v37, v37
	s_waitcnt lgkmcnt(0)
	v_add_f32_e32 v34, v34, v35
	v_fmamk_f32 v34, v34, 0x3c000000, v162
	v_cmp_gt_f32_e32 vcc, s30, v34
	v_mul_f32_e32 v35, 0x4b800000, v34
	v_add_f32_e32 v37, 1.0, v37
	v_cndmask_b32_e32 v34, v34, v35, vcc
	v_rsq_f32_e32 v34, v34
	v_rcp_f32_e32 v92, v37
	v_mul_f32_e32 v35, 0x45800000, v34
	v_cndmask_b32_e32 v90, v34, v35, vcc
	v_mov_b64_e32 v[34:35], s[88:89]
	v_mul_f32_e32 v37, v88, v90
	v_mad_i64_i32 v[34:35], s[0:1], v80, s44, v[34:35]
	v_and_b32_e32 v80, 0xffff0000, v84
	v_pk_mul_f32 v[36:37], v[92:93], v[36:37]
	v_mul_f32_e32 v81, v89, v90
	v_mul_f32_e32 v88, v36, v37
	v_mul_f32_e32 v36, 0xbfb8aa3b, v80
	v_exp_f32_e32 v36, v36
	v_lshl_add_u64 v[34:35], v[34:35], 0, v[82:83]
	v_lshlrev_b32_e32 v82, 16, v85
	v_mul_f32_e32 v83, v86, v90
	v_add_f32_e32 v36, 1.0, v36
	v_rcp_f32_e32 v38, v36
	v_and_b32_e32 v84, 0xffff0000, v85
	v_mul_f32_e32 v85, v87, v90
	s_mov_b64 s[0:1], 0x7245a00
	v_pk_mul_f32 v[36:37], v[38:39], v[80:81]
	s_waitcnt vmcnt(13)
	v_lshlrev_b32_e32 v80, 16, v78
	v_mul_f32_e32 v38, v36, v37
	v_mul_f32_e32 v36, 0xbfb8aa3b, v82
	v_exp_f32_e32 v36, v36
	v_mov_b32_e32 v37, v40
	v_mul_f32_e32 v81, v76, v90
	v_add_f32_e32 v36, 1.0, v36
	v_rcp_f32_e32 v36, v36
	s_nop 0
	v_pk_mul_f32 v[36:37], v[36:37], v[82:83]
	s_nop 0
	v_mul_f32_e32 v39, v36, v37
	v_mul_f32_e32 v36, 0xbfb8aa3b, v84
	v_exp_f32_e32 v36, v36
	s_nop 0
	v_add_f32_e32 v36, 1.0, v36
	v_rcp_f32_e32 v40, v36
	s_nop 0
	v_pk_mul_f32 v[36:37], v[40:41], v[84:85]
	s_nop 0
	v_mul_f32_e32 v37, v36, v37
	v_cvt_pk_bf16_f32 v36, v88, v38
	v_cvt_pk_bf16_f32 v37, v39, v37
	v_lshl_add_u64 v[38:39], v[34:35], 0, v[0:1]
	v_lshl_add_u64 v[34:35], v[38:39], 0, s[0:1]
	v_add_co_u32_e32 v38, vcc, s52, v38
	v_and_b32_e32 v40, 0xffff0000, v78
	s_nop 0
	v_addc_co_u32_e32 v39, vcc, 0, v39, vcc
	global_store_dwordx2 v[38:39], v[36:37], off offset:2560
	v_lshlrev_b32_e32 v38, 16, v79
	v_and_b32_e32 v36, 0xffff0000, v79
	s_waitcnt vmcnt(13)
	v_mov_b32_e32 v79, v26
	v_mul_f32_e32 v26, 0xbfb8aa3b, v40
	v_exp_f32_e32 v26, v26
	v_mul_f32_e32 v41, v77, v90
	v_mul_f32_e32 v39, v74, v90
	v_mul_f32_e32 v0, 0xbfb8aa3b, v80
	v_add_f32_e32 v26, 1.0, v26
	v_rcp_f32_e32 v26, v26
	v_exp_f32_e32 v0, v0
	v_mul_f32_e32 v37, v75, v90
	v_pk_mul_f32 v[26:27], v[26:27], v[40:41]
	s_nop 0
	v_mul_f32_e32 v40, v26, v27
	v_mul_f32_e32 v26, 0xbfb8aa3b, v38
	v_exp_f32_e32 v26, v26
	v_mov_b32_e32 v27, v28
	v_add_f32_e32 v0, 1.0, v0
	v_rcp_f32_e32 v78, v0
	v_add_f32_e32 v26, 1.0, v26
	v_rcp_f32_e32 v26, v26
	s_waitcnt vmcnt(11)
; __device__ __forceinline__ unsigned pk2(float lo, float hi) { unsigned r; asm volatile("v_cvt_pk_bf16_f32 %0, %1, %2" : "=v"(r) : "v"(lo), "v"(hi)); return r; }
; __device__ __forceinline__ float siluf_(float x) { return x * __builtin_amdgcn_rcpf(1.f + fexp_(-x)); }
; __device__ void ret_m2(const Params& p, LAS unsigned char* lds, int l, int b, int c, int hp) {
;     ...
;     for (int vt = 0; vt < 8; ++vt) {
;         const int v = vt * 16 + 4 * fq;
;         float gt[4]; unpack4(rgv[vt], gt);
;         const f32x4 ng = ngv[vt];
;         float y[4];
; #pragma unroll
;         for (int i = 0; i < 4; ++i) y[i] = siluf_(gt[i]) * (o[vt][i] * rstd * ng[i]);
;         u32x2 w; w.x = pk2(y[0], y[1]); w.y = pk2(y[2], y[3]);
;         *(u32x2*)(mix + t * DMIX + 512 + h * 128 + v) = w;
;     }
	v_mov_b32_e32 v41, v22
	v_pk_mul_f32 v[78:79], v[78:79], v[80:81]
	v_pk_mul_f32 v[26:27], v[26:27], v[38:39]
	s_nop 0
	v_mul_f32_e32 v38, v26, v27
	v_mul_f32_e32 v26, 0xbfb8aa3b, v36
	v_exp_f32_e32 v26, v26
	v_mul_f32_e32 v0, v78, v79
	v_mul_f32_e32 v39, v69, v90
	v_add_f32_e32 v26, 1.0, v26
	v_rcp_f32_e32 v28, v26
	s_nop 0
	v_pk_mul_f32 v[26:27], v[28:29], v[36:37]
	s_nop 0
	v_mul_f32_e32 v27, v26, v27
	v_cvt_pk_bf16_f32 v26, v0, v40
	v_cvt_pk_bf16_f32 v27, v38, v27
	global_store_dwordx2 v[34:35], v[26:27], off offset:32
	v_lshlrev_b32_e32 v26, 16, v72
	v_and_b32_e32 v28, 0xffff0000, v72
	v_mul_f32_e32 v0, 0xbfb8aa3b, v26
	v_mul_f32_e32 v22, 0xbfb8aa3b, v28
	v_exp_f32_e32 v0, v0
	v_exp_f32_e32 v22, v22
	v_mul_f32_e32 v27, v70, v90
	v_mul_f32_e32 v29, v71, v90
	v_add_f32_e32 v0, 1.0, v0
	v_add_f32_e32 v22, 1.0, v22
	v_rcp_f32_e32 v40, v0
	v_rcp_f32_e32 v22, v22
	v_lshlrev_b32_e32 v36, 16, v73
	v_mul_f32_e32 v37, v68, v90
	v_pk_mul_f32 v[26:27], v[40:41], v[26:27]
	v_pk_mul_f32 v[22:23], v[22:23], v[28:29]
	v_mul_f32_e32 v0, v26, v27
	v_mul_f32_e32 v26, v22, v23
	v_mul_f32_e32 v22, 0xbfb8aa3b, v36
	v_exp_f32_e32 v22, v22
	v_mov_b32_e32 v23, v24
	v_and_b32_e32 v38, 0xffff0000, v73
	s_waitcnt vmcnt(11)
	v_and_b32_e32 v28, 0xffff0000, v67
	v_add_f32_e32 v22, 1.0, v22
	v_rcp_f32_e32 v22, v22
	v_mul_f32_e32 v29, v63, v90
	v_pk_mul_f32 v[22:23], v[22:23], v[36:37]
	s_nop 0
	v_mul_f32_e32 v27, v22, v23
	v_mul_f32_e32 v22, 0xbfb8aa3b, v38
	v_exp_f32_e32 v22, v22
	s_waitcnt vmcnt(10)
	v_mov_b32_e32 v37, v18
	v_add_f32_e32 v22, 1.0, v22
	v_rcp_f32_e32 v24, v22
	s_nop 0
	v_pk_mul_f32 v[22:23], v[24:25], v[38:39]
	s_nop 0
	v_mul_f32_e32 v23, v22, v23
	v_cvt_pk_bf16_f32 v22, v0, v26
	v_cvt_pk_bf16_f32 v23, v27, v23
	global_store_dwordx2 v[34:35], v[22:23], off offset:64
	v_lshlrev_b32_e32 v22, 16, v66
	v_and_b32_e32 v24, 0xffff0000, v66
	v_mul_f32_e32 v0, 0xbfb8aa3b, v22
	v_mul_f32_e32 v18, 0xbfb8aa3b, v24
	v_exp_f32_e32 v0, v0
	v_exp_f32_e32 v18, v18
	v_mul_f32_e32 v23, v64, v90
	v_mul_f32_e32 v25, v65, v90
	v_add_f32_e32 v0, 1.0, v0
	v_add_f32_e32 v18, 1.0, v18
	v_rcp_f32_e32 v36, v0
	v_rcp_f32_e32 v18, v18
	v_lshlrev_b32_e32 v26, 16, v67
	v_mul_f32_e32 v27, v62, v90
	v_pk_mul_f32 v[22:23], v[36:37], v[22:23]
	v_pk_mul_f32 v[18:19], v[18:19], v[24:25]
	v_mul_f32_e32 v0, v22, v23
	v_mul_f32_e32 v22, v18, v19
	v_mul_f32_e32 v18, 0xbfb8aa3b, v26
	v_exp_f32_e32 v18, v18
	v_mov_b32_e32 v19, v20
	s_waitcnt vmcnt(10)
	v_and_b32_e32 v24, 0xffff0000, v59
	v_mul_f32_e32 v25, v57, v90
	v_add_f32_e32 v18, 1.0, v18
	v_rcp_f32_e32 v18, v18
	s_nop 0
	v_pk_mul_f32 v[18:19], v[18:19], v[26:27]
	s_nop 0
	v_mul_f32_e32 v23, v18, v19
	v_mul_f32_e32 v18, 0xbfb8aa3b, v28
	v_exp_f32_e32 v18, v18
	s_waitcnt vmcnt(9)
	v_mov_b32_e32 v27, v14
	v_add_f32_e32 v18, 1.0, v18
	v_rcp_f32_e32 v20, v18
	s_nop 0
	v_pk_mul_f32 v[18:19], v[20:21], v[28:29]
	s_nop 0
	v_mul_f32_e32 v19, v18, v19
	v_cvt_pk_bf16_f32 v18, v0, v22
	v_cvt_pk_bf16_f32 v19, v23, v19
	global_store_dwordx2 v[34:35], v[18:19], off offset:96
	v_lshlrev_b32_e32 v18, 16, v58
	v_and_b32_e32 v20, 0xffff0000, v58
	v_mul_f32_e32 v0, 0xbfb8aa3b, v18
	v_mul_f32_e32 v14, 0xbfb8aa3b, v20
	v_exp_f32_e32 v0, v0
	v_exp_f32_e32 v14, v14
	v_mul_f32_e32 v19, v60, v90
	v_mul_f32_e32 v21, v61, v90
	v_add_f32_e32 v0, 1.0, v0
	v_add_f32_e32 v14, 1.0, v14
	v_rcp_f32_e32 v26, v0
	v_rcp_f32_e32 v14, v14
	v_lshlrev_b32_e32 v22, 16, v59
	v_mul_f32_e32 v23, v56, v90
	v_pk_mul_f32 v[18:19], v[26:27], v[18:19]
	v_pk_mul_f32 v[14:15], v[14:15], v[20:21]
	v_mul_f32_e32 v0, v18, v19
	v_mul_f32_e32 v18, v14, v15
	v_mul_f32_e32 v14, 0xbfb8aa3b, v22
	v_exp_f32_e32 v14, v14
	v_mov_b32_e32 v15, v16
	s_waitcnt vmcnt(9)
	v_and_b32_e32 v20, 0xffff0000, v53
	v_mul_f32_e32 v21, v51, v90
	v_add_f32_e32 v14, 1.0, v14
	v_rcp_f32_e32 v14, v14
	s_nop 0
	v_pk_mul_f32 v[14:15], v[14:15], v[22:23]
	s_nop 0
	v_mul_f32_e32 v19, v14, v15
	v_mul_f32_e32 v14, 0xbfb8aa3b, v24
	v_exp_f32_e32 v14, v14
	s_waitcnt vmcnt(8)
	v_mov_b32_e32 v23, v10
	v_add_f32_e32 v14, 1.0, v14
	v_rcp_f32_e32 v16, v14
	s_nop 0
	v_pk_mul_f32 v[14:15], v[16:17], v[24:25]
	s_nop 0
	v_mul_f32_e32 v15, v14, v15
	v_cvt_pk_bf16_f32 v14, v0, v18
	v_cvt_pk_bf16_f32 v15, v19, v15
	global_store_dwordx2 v[34:35], v[14:15], off offset:128
	v_lshlrev_b32_e32 v14, 16, v52
	v_and_b32_e32 v16, 0xffff0000, v52
	v_mul_f32_e32 v0, 0xbfb8aa3b, v14
	v_mul_f32_e32 v10, 0xbfb8aa3b, v16
	v_exp_f32_e32 v0, v0
	v_exp_f32_e32 v10, v10
	v_mul_f32_e32 v15, v54, v90
	v_mul_f32_e32 v17, v55, v90
	v_add_f32_e32 v0, 1.0, v0
	v_add_f32_e32 v10, 1.0, v10
	v_rcp_f32_e32 v22, v0
	v_rcp_f32_e32 v10, v10
	v_lshlrev_b32_e32 v18, 16, v53
	v_mul_f32_e32 v19, v50, v90
	v_pk_mul_f32 v[14:15], v[22:23], v[14:15]
	v_pk_mul_f32 v[10:11], v[10:11], v[16:17]
	v_mul_f32_e32 v0, v14, v15
	v_mul_f32_e32 v14, v10, v11
	v_mul_f32_e32 v10, 0xbfb8aa3b, v18
	v_exp_f32_e32 v10, v10
	v_mov_b32_e32 v11, v12
	s_waitcnt vmcnt(8)
; __device__ __forceinline__ unsigned pk2(float lo, float hi) { unsigned r; asm volatile("v_cvt_pk_bf16_f32 %0, %1, %2" : "=v"(r) : "v"(lo), "v"(hi)); return r; }
; __device__ __forceinline__ float siluf_(float x) { return x * __builtin_amdgcn_rcpf(1.f + fexp_(-x)); }
; __device__ void ret_m2(const Params& p, LAS unsigned char* lds, int l, int b, int c, int hp) {
;     ...
;     for (int vt = 0; vt < 8; ++vt) {
;         const int v = vt * 16 + 4 * fq;
;         float gt[4]; unpack4(rgv[vt], gt);
;         const f32x4 ng = ngv[vt];
;         float y[4];
; #pragma unroll
;         for (int i = 0; i < 4; ++i) y[i] = siluf_(gt[i]) * (o[vt][i] * rstd * ng[i]);
;         u32x2 w; w.x = pk2(y[0], y[1]); w.y = pk2(y[2], y[3]);
;         *(u32x2*)(mix + t * DMIX + 512 + h * 128 + v) = w;
;     }
;     __syncthreads();
; __device__ void phase_m2(const Params& p, LAS unsigned char* lds, int l) {
;     for (int rr = 0; rr < 1 + ((REP_ITEM >> 4) & 1); ++rr) { if (IT_EN(4)) for (int it = blockIdx.x; it < 512; it += gridDim.x) ret_m2(p, lds, l, it >> 6, (it >> 1) & 31, it & 1); }
;     for (int rr = 0; rr < 1 + ((REP_ITEM >> 5) & 1); ++rr) { if (IT_EN(5)) for (int it = blockIdx.x; it < 512; it += gridDim.x) ssd_m2(p, lds, l, it >> 6, (it >> 1) & 31, it & 1); }
	v_and_b32_e32 v16, 0xffff0000, v47
	v_mul_f32_e32 v17, v45, v90
	v_add_f32_e32 v10, 1.0, v10
	v_rcp_f32_e32 v10, v10
	s_nop 0
	v_pk_mul_f32 v[10:11], v[10:11], v[18:19]
	s_nop 0
	v_mul_f32_e32 v15, v10, v11
	v_mul_f32_e32 v10, 0xbfb8aa3b, v20
	v_exp_f32_e32 v10, v10
	s_waitcnt vmcnt(7)
	v_mov_b32_e32 v19, v6
	v_add_f32_e32 v10, 1.0, v10
	v_rcp_f32_e32 v12, v10
	s_nop 0
	v_pk_mul_f32 v[10:11], v[12:13], v[20:21]
	s_nop 0
	v_mul_f32_e32 v11, v10, v11
	v_cvt_pk_bf16_f32 v10, v0, v14
	v_cvt_pk_bf16_f32 v11, v15, v11
	global_store_dwordx2 v[34:35], v[10:11], off offset:160
	v_lshlrev_b32_e32 v10, 16, v46
	v_and_b32_e32 v12, 0xffff0000, v46
	v_mul_f32_e32 v0, 0xbfb8aa3b, v10
	v_mul_f32_e32 v6, 0xbfb8aa3b, v12
	v_exp_f32_e32 v0, v0
	v_exp_f32_e32 v6, v6
	v_mul_f32_e32 v11, v48, v90
	v_mul_f32_e32 v13, v49, v90
	v_add_f32_e32 v0, 1.0, v0
	v_add_f32_e32 v6, 1.0, v6
	v_rcp_f32_e32 v18, v0
	v_rcp_f32_e32 v6, v6
	v_lshlrev_b32_e32 v14, 16, v47
	v_mul_f32_e32 v15, v44, v90
	v_pk_mul_f32 v[10:11], v[18:19], v[10:11]
	v_pk_mul_f32 v[6:7], v[6:7], v[12:13]
	v_mul_f32_e32 v0, v10, v11
	v_mul_f32_e32 v10, v6, v7
	v_mul_f32_e32 v6, 0xbfb8aa3b, v14
	v_exp_f32_e32 v6, v6
	v_mov_b32_e32 v7, v8
	s_waitcnt vmcnt(7)
	v_lshlrev_b32_e32 v12, 16, v43
	v_mul_f32_e32 v13, v30, v90
	v_add_f32_e32 v6, 1.0, v6
	v_rcp_f32_e32 v6, v6
	s_nop 0
	v_pk_mul_f32 v[6:7], v[6:7], v[14:15]
	s_nop 0
	v_mul_f32_e32 v11, v6, v7
	v_mul_f32_e32 v6, 0xbfb8aa3b, v16
	v_exp_f32_e32 v6, v6
	s_waitcnt vmcnt(6)
	v_mov_b32_e32 v15, v2
	v_add_f32_e32 v6, 1.0, v6
	v_rcp_f32_e32 v8, v6
	s_nop 0
	v_pk_mul_f32 v[6:7], v[8:9], v[16:17]
	s_nop 0
	v_mul_f32_e32 v7, v6, v7
	v_cvt_pk_bf16_f32 v6, v0, v10
	v_and_b32_e32 v10, 0xffff0000, v42
	v_lshlrev_b32_e32 v8, 16, v42
	v_mul_f32_e32 v2, 0xbfb8aa3b, v10
	v_mul_f32_e32 v0, 0xbfb8aa3b, v8
	v_exp_f32_e32 v2, v2
	v_exp_f32_e32 v0, v0
	v_cvt_pk_bf16_f32 v7, v11, v7
	v_mul_f32_e32 v11, v33, v90
	v_add_f32_e32 v2, 1.0, v2
	v_add_f32_e32 v0, 1.0, v0
	v_rcp_f32_e32 v2, v2
	v_rcp_f32_e32 v14, v0
	v_mul_f32_e32 v9, v32, v90
	global_store_dwordx2 v[34:35], v[6:7], off offset:192
	v_pk_mul_f32 v[2:3], v[2:3], v[10:11]
	v_and_b32_e32 v6, 0xffff0000, v43
	v_pk_mul_f32 v[8:9], v[14:15], v[8:9]
	v_mul_f32_e32 v2, v2, v3
	v_mul_f32_e32 v3, 0xbfb8aa3b, v12
	v_mul_f32_e32 v0, v8, v9
	v_exp_f32_e32 v3, v3
	v_mov_b32_e32 v9, v4
	v_mul_f32_e32 v4, 0xbfb8aa3b, v6
	v_exp_f32_e32 v4, v4
	v_add_f32_e32 v3, 1.0, v3
	v_rcp_f32_e32 v8, v3
	v_mul_f32_e32 v7, v31, v90
	v_add_f32_e32 v4, 1.0, v4
	v_rcp_f32_e32 v4, v4
	v_pk_mul_f32 v[8:9], v[8:9], v[12:13]
	v_cvt_pk_bf16_f32 v2, v0, v2
	v_pk_mul_f32 v[4:5], v[4:5], v[6:7]
	v_mul_f32_e32 v3, v8, v9
	v_mul_f32_e32 v4, v4, v5
	v_cvt_pk_bf16_f32 v3, v3, v4
	global_store_dwordx2 v[34:35], v[2:3], off offset:224
	s_barrier
	s_load_dword s0, s[36:37], 0x10
	s_waitcnt lgkmcnt(0)
	s_lshr_b32 s0, s0, 16
	s_cmp_lg_u32 s0, 0
	s_cselect_b64 s[0:1], -1, 0
	s_cmp_lg_u64 s[0:1], 0
	s_addc_u32 s26, s26, s94
	s_cmpk_lt_i32 s26, 0x200
	s_cbranch_scc1 .LBB0_299
	v_readlane_b32 s40, v254, 16
	v_readlane_b32 s54, v254, 30
	v_readlane_b32 s0, v254, 54
	v_readlane_b32 s55, v254, 31
	v_readlane_b32 s1, v254, 55
	s_add_u32 s0, s54, s0
	s_addc_u32 s1, s55, s1
	v_readlane_b32 s41, v254, 17
	v_readlane_b32 s42, v254, 18
	v_readlane_b32 s43, v254, 19
	v_readlane_b32 s44, v254, 20
	v_readlane_b32 s45, v254, 21
	v_readlane_b32 s46, v254, 22
	v_readlane_b32 s47, v254, 23
	v_readlane_b32 s48, v254, 24
	v_readlane_b32 s49, v254, 25
	v_readlane_b32 s50, v254, 26
	v_readlane_b32 s51, v254, 27
	v_readlane_b32 s52, v254, 28
	v_readlane_b32 s53, v254, 29
	v_writelane_b32 v254, s0, 59
	s_mov_b64 s[90:91], 0x1000
	s_mov_b32 s82, 0x7245000
	v_writelane_b32 v254, s1, 60
	s_nop 0
	v_readlane_b32 s0, v254, 47
	s_ashr_i32 s0, s0, 31
	s_nop 0
	v_writelane_b32 v254, s0, 61
	v_readlane_b32 s0, v253, 46
	s_mov_b32 s93, s0
	v_writelane_b32 v254, s88, 63
	v_readlane_b32 s1, v253, 47
	s_nop 0
	v_writelane_b32 v255, s89, 0
	s_branch .LBB0_302

; #define LAS __attribute__((address_space(3)))
; __device__ __forceinline__ float siluf_(float x) { return x * __builtin_amdgcn_rcpf(1.f + fexp_(-x)); }
; __device__ void ssd_m2(const Params& p, LAS unsigned char* lds, int l, int b, int c, int g) {
;     ...
;         for (int i = 0; i < 4; ++i) { const int id = tid + 512 * i, h2 = id >> 10, pp = (id >> 4) & 63, nc = id & 15;
;             *(LAS u32x4*)((LAS bf16_t*)(lds + PB + h2 * HB + 18432) + pp * 136 + nc * 8) = *(const u32x4*)(sp + ((size_t)((b * 8 + hbase + h2) * NCH + c)) * 8192 + pp * 128 + nc * 8); }
;     ...
;             const int pp = pt * 16 + 4 * fq;
;             float xv[4], zv[4]; unpack4(*(const LAS u32x2*)(X + irow * 72 + pp), xv);
;             unpack4(zraw[pt], zv);
;             f32x4 r;
; #pragma unroll
;             for (int i = 0; i < 4; ++i) { const float y = a1[i] + ecum * a2[i] + Dh * xv[i]; r[i] = y * siluf_(zv[i]); ssq += r[i] * r[i]; }
;             gy[pr][pt] = r;
;         }
.LBB0_356:
	s_or_b64 exec, exec, s[0:1]
	v_mul_f32_e32 v44, 0x3fb8aa3b, v133
	s_waitcnt vmcnt(4)
	v_lshlrev_b32_e32 v47, 16, v140
	v_exp_f32_e32 v60, v44
	v_and_b32_e32 v48, 0xffff0000, v140
	v_mul_f32_e32 v44, 0xbfb8aa3b, v47
	v_exp_f32_e32 v44, v44
	v_mul_f32_e32 v45, 0xbfb8aa3b, v48
	v_exp_f32_e32 v45, v45
	v_lshlrev_b32_e32 v49, 16, v141
	v_add_f32_e32 v44, 1.0, v44
	v_and_b32_e32 v51, 0xffff0000, v141
	v_rcp_f32_e32 v61, v44
	v_add_f32_e32 v44, 1.0, v45
	v_mul_f32_e32 v45, 0xbfb8aa3b, v49
	v_exp_f32_e32 v45, v45
	v_mul_f32_e32 v50, 0xbfb8aa3b, v51
	v_exp_f32_e32 v50, v50
	v_rcp_f32_e32 v74, v44
	v_add_f32_e32 v44, 1.0, v45
	v_rcp_f32_e32 v68, v44
	v_add_f32_e32 v44, 1.0, v50
	s_waitcnt vmcnt(3)
	v_lshlrev_b32_e32 v57, 16, v138
	v_rcp_f32_e32 v66, v44
	v_and_b32_e32 v53, 0xffff0000, v138
	v_mul_f32_e32 v44, 0xbfb8aa3b, v57
	v_exp_f32_e32 v44, v44
	v_mul_f32_e32 v45, 0xbfb8aa3b, v53
	v_exp_f32_e32 v45, v45
	v_lshlrev_b32_e32 v50, 16, v139
	v_add_f32_e32 v44, 1.0, v44
	v_and_b32_e32 v52, 0xffff0000, v139
	v_rcp_f32_e32 v69, v44
	v_add_f32_e32 v44, 1.0, v45
	v_mul_f32_e32 v45, 0xbfb8aa3b, v50
	v_exp_f32_e32 v45, v45
	v_mul_f32_e32 v54, 0xbfb8aa3b, v52
	v_exp_f32_e32 v54, v54
	v_rcp_f32_e32 v76, v44
	v_add_f32_e32 v44, 1.0, v45
	v_rcp_f32_e32 v71, v44
	v_add_f32_e32 v44, 1.0, v54
	s_waitcnt vmcnt(2)
	v_lshlrev_b32_e32 v64, 16, v136
	v_rcp_f32_e32 v67, v44
	v_and_b32_e32 v54, 0xffff0000, v136
	v_mul_f32_e32 v44, 0xbfb8aa3b, v64
	v_exp_f32_e32 v44, v44
	v_mul_f32_e32 v45, 0xbfb8aa3b, v54
	v_exp_f32_e32 v45, v45
	v_lshlrev_b32_e32 v81, 16, v38
	v_fma_f32 v2, v60, v2, v6
	s_waitcnt vmcnt(0)
	v_fmac_f32_e32 v2, v205, v81
	v_mul_f32_e32 v6, v61, v47
	v_lshlrev_b32_e32 v55, 16, v137
	v_add_f32_e32 v44, 1.0, v44
	v_and_b32_e32 v38, 0xffff0000, v38
	v_mul_f32_e32 v47, v6, v2
	v_fma_f32 v2, v60, v3, v7
	v_and_b32_e32 v56, 0xffff0000, v137
	v_rcp_f32_e32 v72, v44
	v_add_f32_e32 v44, 1.0, v45
	v_mul_f32_e32 v45, 0xbfb8aa3b, v55
	v_fmac_f32_e32 v2, v205, v38
	v_mul_f32_e32 v3, v74, v48
	v_exp_f32_e32 v45, v45
	v_mul_f32_e32 v58, 0xbfb8aa3b, v56
	v_lshlrev_b32_e32 v82, 16, v39
	v_mul_f32_e32 v48, v3, v2
	v_fma_f32 v2, v60, v4, v8
	v_exp_f32_e32 v58, v58
	v_and_b32_e32 v39, 0xffff0000, v39
	v_fmac_f32_e32 v2, v205, v82
	v_mul_f32_e32 v3, v68, v49
	v_fmac_f32_e32 v9, v60, v5
	v_mul_f32_e32 v49, v3, v2
	v_fmac_f32_e32 v9, v205, v39
	v_mul_f32_e32 v2, v66, v51
	v_mul_f32_e32 v51, v2, v9
	v_lshlrev_b32_e32 v2, 16, v40
	v_fma_f32 v6, v60, v10, v14
	v_rcp_f32_e32 v79, v44
	v_add_f32_e32 v44, 1.0, v45
	v_fmac_f32_e32 v6, v205, v2
	v_mul_f32_e32 v2, v69, v57
	v_rcp_f32_e32 v75, v44
	v_add_f32_e32 v44, 1.0, v58
	v_lshlrev_b32_e32 v65, 16, v134
	v_and_b32_e32 v3, 0xffff0000, v40
	v_mul_f32_e32 v40, v2, v6
	v_fma_f32 v2, v60, v11, v15
	v_rcp_f32_e32 v70, v44
	v_and_b32_e32 v58, 0xffff0000, v134
	v_mul_f32_e32 v44, 0xbfb8aa3b, v65
	v_fmac_f32_e32 v2, v205, v3
	v_mul_f32_e32 v3, v76, v53
	v_exp_f32_e32 v44, v44
	v_mul_f32_e32 v45, 0xbfb8aa3b, v58
	v_lshlrev_b32_e32 v4, 16, v41
	v_and_b32_e32 v5, 0xffff0000, v41
	v_mul_f32_e32 v41, v3, v2
	v_fma_f32 v2, v60, v12, v16
	v_exp_f32_e32 v45, v45
	v_fmac_f32_e32 v2, v205, v4
	v_mul_f32_e32 v3, v71, v50
	v_fmac_f32_e32 v17, v60, v13
	v_mul_f32_e32 v50, v3, v2
	v_fmac_f32_e32 v17, v205, v5
	v_mul_f32_e32 v2, v67, v52
	v_mul_f32_e32 v52, v2, v17
	v_lshlrev_b32_e32 v2, 16, v34
	v_fma_f32 v6, v60, v18, v22
	v_lshlrev_b32_e32 v59, 16, v135
	v_add_f32_e32 v44, 1.0, v44
	v_fmac_f32_e32 v6, v205, v2
	v_mul_f32_e32 v2, v72, v64
	v_and_b32_e32 v63, 0xffff0000, v135
	v_rcp_f32_e32 v77, v44
	v_add_f32_e32 v44, 1.0, v45
	v_mul_f32_e32 v45, 0xbfb8aa3b, v59
	v_and_b32_e32 v3, 0xffff0000, v34
	v_mul_f32_e32 v53, v2, v6
	v_fma_f32 v2, v60, v19, v23
	v_exp_f32_e32 v45, v45
	v_mul_f32_e32 v62, 0xbfb8aa3b, v63
	v_fmac_f32_e32 v2, v205, v3
	v_mul_f32_e32 v3, v79, v54
	v_exp_f32_e32 v62, v62
	v_lshlrev_b32_e32 v4, 16, v35
	v_mul_f32_e32 v54, v3, v2
	v_fma_f32 v2, v60, v20, v24
	v_and_b32_e32 v5, 0xffff0000, v35
	v_fmac_f32_e32 v2, v205, v4
	v_mul_f32_e32 v3, v75, v55
	v_fmac_f32_e32 v25, v60, v21
	v_rcp_f32_e32 v80, v44
	v_mul_f32_e32 v55, v3, v2
	v_fmac_f32_e32 v25, v205, v5
	v_mul_f32_e32 v2, v70, v56
	v_add_f32_e32 v44, 1.0, v45
	v_mul_f32_e32 v56, v2, v25
	v_lshlrev_b32_e32 v2, 16, v36
	v_fma_f32 v6, v60, v26, v30
	v_rcp_f32_e32 v78, v44
	v_add_f32_e32 v44, 1.0, v62
	v_fmac_f32_e32 v6, v205, v2
	v_mul_f32_e32 v2, v77, v65
	v_rcp_f32_e32 v73, v44
	v_and_b32_e32 v3, 0xffff0000, v36
	v_mul_f32_e32 v57, v2, v6
	v_fma_f32 v2, v60, v27, v31
	v_fmac_f32_e32 v2, v205, v3
	v_mul_f32_e32 v3, v80, v58
	v_lshlrev_b32_e32 v4, 16, v37
	v_mul_f32_e32 v58, v3, v2
	v_fma_f32 v2, v60, v28, v32
	v_and_b32_e32 v5, 0xffff0000, v37
	v_fmac_f32_e32 v2, v205, v4
	v_mul_f32_e32 v3, v78, v59
	v_fmac_f32_e32 v33, v60, v29
	s_or_b32 s0, s94, 2
	v_mul_f32_e32 v59, v3, v2
	v_fmac_f32_e32 v33, v205, v5
	v_mul_f32_e32 v2, v73, v63
	s_or_b32 s1, s0, s24
	v_mul_f32_e32 v60, v2, v33
	v_add_u32_e32 v2, s1, v197
	v_lshl_or_b32 v2, v2, 5, s95
	v_ashrrev_i32_e32 v3, 31, v2
	v_readlane_b32 s2, v254, 44
	v_lshlrev_b32_e32 v0, 7, v202
	v_lshlrev_b64 v[2:3], 14, v[2:3]
	v_readlane_b32 s3, v254, 45
	v_lshlrev_b32_e32 v0, 1, v0
	v_mov_b32_e32 v133, v1
	v_lshl_add_u64 v[2:3], s[2:3], 0, v[2:3]
	v_lshl_add_u64 v[2:3], v[2:3], 0, v[0:1]
	v_lshl_add_u64 v[2:3], v[2:3], 0, v[132:133]
	global_load_dwordx4 v[210:213], v[2:3], off
	v_lshlrev_b32_e32 v43, 7, v203
	v_lshlrev_b32_e32 v62, 7, v201
	v_add_u32_e32 v38, v189, v193
	v_and_b32_e32 v46, 63, v127
	v_ashrrev_i32_e32 v127, 31, v126
	v_readlane_b32 s40, v254, 16
	v_readlane_b32 s52, v254, 28
	v_readlane_b32 s53, v254, 29
; #define LAS __attribute__((address_space(3)))
; __device__ __forceinline__ unsigned pk2(float lo, float hi) { unsigned r; asm volatile("v_cvt_pk_bf16_f32 %0, %1, %2" : "=v"(r) : "v"(lo), "v"(hi)); return r; }
; __device__ __forceinline__ float fexp_(float x) { return __builtin_amdgcn_exp2f(x * 1.44269504089f); }
; #define MFMA(X, Y, C) __builtin_amdgcn_mfma_f32_16x16x32_bf16((X), (Y), (C), 0, 0, 0)
; __device__ void ssd_m2(const Params& p, LAS unsigned char* lds, int l, int b, int c, int g) {
;     ...
;         for (int i = 0; i < 4; ++i) { const int id = tid + 512 * i, h2 = id >> 10, pp = (id >> 4) & 63, nc = id & 15;
;             *(LAS u32x4*)((LAS bf16_t*)(lds + PB + h2 * HB + 18432) + pp * 136 + nc * 8) = *(const u32x4*)(sp + ((size_t)((b * 8 + hbase + h2) * NCH + c)) * 8192 + pp * 128 + nc * 8); }
;         __syncthreads();
;         const int h = hbase + hh, hl = 2 * pr + hh;
;         LAS bf16_t* P = (LAS bf16_t*)(lds + PB + hh * HB); LAS bf16_t* X = P + 64 * 72; LAS bf16_t* S = (LAS bf16_t*)(lds + PB + hh * HB + 18432);
;         bf16x8 Yc[4];
; #pragma unroll
;         for (int kk = 0; kk < 4; ++kk) Yc[kk] = frag_row(Cm, 136, i0, kk * 32, fr, fq);
;         const float cumi = cum[hl * 64 + irow];
; #pragma unroll
;         for (int jh = 0; jh < 2; ++jh) {
;             bf16x8 Xb[2][4]; f32x4 cj[2], dj[2];
; #pragma unroll
;             for (int q = 0; q < 2; ++q) {
; #pragma unroll
;                 for (int kk = 0; kk < 4; ++kk) Xb[q][kk] = frag_row(Bm, 136, (2 * jh + q) * 16, kk * 32, fr, fq);
;                 cj[q] = *(const LAS f32x4*)(cum + hl * 64 + (2 * jh + q) * 16 + 4 * fq); dj[q] = *(const LAS f32x4*)(dtv + hl * 64 + (2 * jh + q) * 16 + 4 * fq);
;             }
; #pragma unroll
;             for (int q = 0; q < 2; ++q) {
;                 const int jt = 2 * jh + q;
;                 f32x4 sc = {0.f, 0.f, 0.f, 0.f};
; #pragma unroll
;                 for (int kk = 0; kk < 4; ++kk) sc = MFMA(Xb[q][kk], Yc[kk], sc);
;                 float v[4];
; #pragma unroll
;                 for (int i = 0; i < 4; ++i) { const int j = jt * 16 + 4 * fq + i; v[i] = j <= irow ? sc[i] * fexp_(cumi - cj[q][i]) * dj[q][i] : 0.f; }
;                 u32x2 w; w.x = pk2(v[0], v[1]); w.y = pk2(v[2], v[3]);
;                 *(LAS u32x2*)(P + irow * 72 + jt * 16 + 4 * fq) = w;
;             }
;         }
	v_mul_u32_u24_e32 v45, 0x90, v204
	v_lshlrev_b32_e32 v44, 6, v126
	v_mul_f32_e32 v61, v48, v48
	v_fmac_f32_e32 v61, v47, v47
	v_fmac_f32_e32 v61, v49, v49
	v_fmac_f32_e32 v61, v51, v51
	v_fmac_f32_e32 v61, v40, v40
	v_fmac_f32_e32 v61, v41, v41
	v_fmac_f32_e32 v61, v50, v50
	v_fmac_f32_e32 v61, v52, v52
	v_fmac_f32_e32 v61, v53, v53
	v_fmac_f32_e32 v61, v54, v54
	v_fmac_f32_e32 v61, v55, v55
	v_fmac_f32_e32 v61, v56, v56
	v_fmac_f32_e32 v61, v57, v57
	v_fmac_f32_e32 v61, v58, v58
	v_fmac_f32_e32 v61, v59, v59
	v_fmac_f32_e32 v61, v60, v60
	v_cmp_gt_u32_e32 vcc, 16, v46
	v_readlane_b32 s41, v254, 17
	v_readlane_b32 s42, v254, 18
	v_readlane_b32 s43, v254, 19
	v_readlane_b32 s44, v254, 20
	v_readlane_b32 s45, v254, 21
	v_readlane_b32 s46, v254, 22
	v_readlane_b32 s47, v254, 23
	v_readlane_b32 s48, v254, 24
	v_readlane_b32 s49, v254, 25
	v_readlane_b32 s50, v254, 26
	v_readlane_b32 s51, v254, 27
	v_readlane_b32 s54, v254, 30
	v_readlane_b32 s55, v254, 31
	v_mov_b32_e32 v222, v200
	v_add_u32_e32 v2, s1, v195
	v_lshl_or_b32 v2, v2, 5, s95
	v_ashrrev_i32_e32 v3, 31, v2
	v_lshlrev_b64 v[2:3], 14, v[2:3]
	v_lshl_add_u64 v[2:3], s[2:3], 0, v[2:3]
	v_lshlrev_b32_e32 v4, 1, v43
	v_mov_b32_e32 v5, v1
	v_lshl_add_u64 v[2:3], v[2:3], 0, v[4:5]
	v_lshl_add_u64 v[2:3], v[2:3], 0, v[132:133]
	global_load_dwordx4 v[214:217], v[2:3], off
	v_mov_b32_e32 v223, v199
	v_add_u32_e32 v2, s1, v196
	v_lshl_or_b32 v2, v2, 5, s95
	v_ashrrev_i32_e32 v3, 31, v2
	v_lshlrev_b64 v[2:3], 14, v[2:3]
	v_lshl_add_u64 v[2:3], s[2:3], 0, v[2:3]
	v_lshl_add_u64 v[2:3], v[2:3], 0, v[0:1]
	v_lshl_add_u64 v[2:3], v[2:3], 0, v[132:133]
	global_load_dwordx4 v[218:221], v[2:3], off
	v_add_u32_e32 v0, s1, v194
	v_readlane_b32 s1, v254, 61
	v_mov_b32_e32 v236, v198
	v_lshl_or_b32 v2, v0, 5, s95
	v_ashrrev_i32_e32 v3, 31, v2
	v_lshlrev_b64 v[2:3], 14, v[2:3]
	v_lshl_add_u64 v[2:3], s[2:3], 0, v[2:3]
	v_lshlrev_b32_e32 v0, 1, v62
	v_lshl_add_u64 v[2:3], v[2:3], 0, v[0:1]
	v_lshl_add_u64 v[2:3], v[2:3], 0, v[132:133]
	global_load_dwordx4 v[246:249], v[2:3], off
	v_readlane_b32 s2, v255, 1
	v_readlane_b32 s3, v255, 2
	v_mov_b32_e32 v237, v191
	s_waitcnt vmcnt(3)
	ds_write_b128 v222, v[210:213] offset:53248
	s_waitcnt vmcnt(2)
	ds_write_b128 v223, v[214:217] offset:53248
	s_waitcnt vmcnt(1)
	ds_write_b128 v236, v[218:221] offset:53248
	s_waitcnt vmcnt(0)
	ds_write_b128 v237, v[246:249] offset:53248
	s_waitcnt lgkmcnt(0)
	s_barrier
	ds_read_b128 v[14:17], v190
	ds_read_b128 v[10:13], v190 offset:64
	ds_read_b128 v[6:9], v190 offset:128
	ds_read_b128 v[2:5], v190 offset:192
	ds_read_b32 v0, v192 offset:512
	ds_read_b128 v[22:25], v38 offset:17408
	ds_read_b128 v[26:29], v38 offset:17472
	ds_read_b128 v[30:33], v38 offset:17536
	ds_read_b128 v[34:37], v38 offset:17600
	ds_read_b128 v[62:65], v186 offset:512
	ds_read_b128 v[66:69], v187 offset:512
	ds_read_b128 v[70:73], v38 offset:21760
	ds_read_b128 v[74:77], v38 offset:21824
	ds_read_b128 v[78:81], v38 offset:21888
	ds_read_b128 v[82:85], v38 offset:21952
	ds_read_b128 v[86:89], v186 offset:576
	ds_read_b128 v[18:21], v187 offset:576
	s_waitcnt lgkmcnt(11)
	v_mfma_f32_16x16x32_bf16 v[22:25], v[22:25], v[14:17], 0
	s_waitcnt lgkmcnt(10)
	v_mfma_f32_16x16x32_bf16 v[22:25], v[26:29], v[10:13], v[22:25]
	s_waitcnt lgkmcnt(7)
	v_sub_f32_e32 v26, v0, v62
	v_mul_f32_e32 v26, 0x3fb8aa3b, v26
	v_exp_f32_e32 v26, v26
	v_mfma_f32_16x16x32_bf16 v[22:25], v[30:33], v[6:9], v[22:25]
	v_mfma_f32_16x16x32_bf16 v[22:25], v[34:37], v[2:5], v[22:25]
	s_nop 7
	v_mul_f32_e32 v22, v26, v22
	v_sub_f32_e32 v26, v0, v63
	v_mul_f32_e32 v26, 0x3fb8aa3b, v26
	v_exp_f32_e32 v26, v26
	s_waitcnt lgkmcnt(6)
	v_mul_f32_e32 v22, v66, v22
	v_cndmask_b32_e64 v22, v22, 0, s[68:69]
	v_mul_f32_e32 v23, v26, v23
	v_sub_f32_e32 v26, v0, v64
	v_mul_f32_e32 v26, 0x3fb8aa3b, v26
	v_exp_f32_e32 v26, v26
	v_mul_f32_e32 v23, v67, v23
	v_cndmask_b32_e64 v23, 0, v23, s[70:71]
	v_cvt_pk_bf16_f32 v22, v22, v23
	v_mul_f32_e32 v24, v26, v24
	v_sub_f32_e32 v26, v0, v65
	v_mul_f32_e32 v26, 0x3fb8aa3b, v26
	v_exp_f32_e32 v26, v26
	v_mul_f32_e32 v24, v68, v24
	v_cndmask_b32_e64 v24, v24, 0, s[66:67]
	v_mul_f32_e32 v25, v26, v25
	v_mul_f32_e32 v25, v69, v25
	v_cndmask_b32_e64 v25, v25, 0, s[64:65]
	v_cvt_pk_bf16_f32 v23, v24, v25
	ds_write_b64 v184, v[22:23] offset:34816
	s_waitcnt lgkmcnt(6)
	v_mfma_f32_16x16x32_bf16 v[22:25], v[70:73], v[14:17], 0
	s_waitcnt lgkmcnt(2)
	v_sub_f32_e32 v26, v0, v86
	v_mul_f32_e32 v26, 0x3fb8aa3b, v26
	v_exp_f32_e32 v26, v26
	v_mfma_f32_16x16x32_bf16 v[22:25], v[74:77], v[10:13], v[22:25]
	v_mfma_f32_16x16x32_bf16 v[22:25], v[78:81], v[6:9], v[22:25]
	v_mfma_f32_16x16x32_bf16 v[22:25], v[82:85], v[2:5], v[22:25]
	s_nop 7
	v_mul_f32_e32 v22, v26, v22
	s_waitcnt lgkmcnt(1)
	v_mul_f32_e32 v18, v18, v22
	v_sub_f32_e32 v22, v0, v87
	v_mul_f32_e32 v22, 0x3fb8aa3b, v22
	v_exp_f32_e32 v22, v22
	v_cndmask_b32_e64 v18, v18, 0, s[62:63]
	v_mul_f32_e32 v22, v22, v23
	v_mul_f32_e32 v19, v19, v22
	v_sub_f32_e32 v22, v0, v88
	v_mul_f32_e32 v22, 0x3fb8aa3b, v22
	v_exp_f32_e32 v22, v22
	v_cndmask_b32_e64 v19, v19, 0, s[58:59]
	v_cvt_pk_bf16_f32 v18, v18, v19
	v_mul_f32_e32 v22, v22, v24
	v_mul_f32_e32 v20, v20, v22
	v_sub_f32_e32 v22, v0, v89
	v_mul_f32_e32 v22, 0x3fb8aa3b, v22
	v_exp_f32_e32 v22, v22
	v_cndmask_b32_e64 v20, v20, 0, s[60:61]
	v_mul_f32_e32 v22, v22, v25
	v_mul_f32_e32 v21, v21, v22
	v_cndmask_b32_e64 v21, v21, 0, s[56:57]
	v_cvt_pk_bf16_f32 v19, v20, v21
	ds_write_b64 v184, v[18:19] offset:34848
	ds_read_b128 v[26:29], v38 offset:26112
	ds_read_b128 v[30:33], v38 offset:26176
	ds_read_b128 v[34:37], v38 offset:26240
	ds_read_b128 v[62:65], v38 offset:26304
	ds_read_b128 v[66:69], v186 offset:640
	ds_read_b128 v[70:73], v187 offset:640
	ds_read_b128 v[74:77], v38 offset:30464
	ds_read_b128 v[78:81], v38 offset:30528
	ds_read_b128 v[82:85], v38 offset:30592
	ds_read_b128 v[86:89], v38 offset:30656
	ds_read_b128 v[22:25], v186 offset:704
	ds_read_b128 v[18:21], v187 offset:704
	s_waitcnt lgkmcnt(11)
; #define LAS __attribute__((address_space(3)))
; __device__ __forceinline__ float fexp_(float x) { return __builtin_amdgcn_exp2f(x * 1.44269504089f); }
; __device__ __forceinline__ float siluf_(float x) { return x * __builtin_amdgcn_rcpf(1.f + fexp_(-x)); }
; #define MFMA(X, Y, C) __builtin_amdgcn_mfma_f32_16x16x32_bf16((X), (Y), (C), 0, 0, 0)
; __device__ void ssd_m2(const Params& p, LAS unsigned char* lds, int l, int b, int c, int g) {
;     ...
;         __syncthreads();
;         u32x2 zraw[4];
; #pragma unroll
;         for (int pt = 0; pt < 4; ++pt) zraw[pt] = *(const u32x2*)(proj + t * NPROJ + PC_Z + h * 64 + pt * 16 + 4 * fq);
;         bf16x8 Yp[2];
; #pragma unroll
;         for (int kk = 0; kk < 2; ++kk) Yp[kk] = frag_row(P, 72, i0, kk * 32, fr, fq);
;         const float ecum = fexp_(cumi), Dh = p.in[22][l * 8 + h];
; #pragma unroll
;         for (int pt = 0; pt < 4; ++pt) {
;             f32x4 a1 = {0.f, 0.f, 0.f, 0.f}, a2 = {0.f, 0.f, 0.f, 0.f};
; #pragma unroll
;             for (int kk = 0; kk < 2; ++kk) a1 = MFMA(frag_tr(X, 72, kk * 32, pt * 16, fr, fq), Yp[kk], a1);
; #pragma unroll
;             for (int kk = 0; kk < 4; ++kk) a2 = MFMA(frag_row(S, 136, pt * 16, kk * 32, fr, fq), Yc[kk], a2);
;             const int pp = pt * 16 + 4 * fq;
;             float xv[4], zv[4]; unpack4(*(const LAS u32x2*)(X + irow * 72 + pp), xv);
;             unpack4(zraw[pt], zv);
;             f32x4 r;
; #pragma unroll
;             for (int i = 0; i < 4; ++i) { const float y = a1[i] + ecum * a2[i] + Dh * xv[i]; r[i] = y * siluf_(zv[i]); ssq += r[i] * r[i]; }
;             gy[pr][pt] = r;
;         }
	v_mfma_f32_16x16x32_bf16 v[26:29], v[26:29], v[14:17], 0
	s_waitcnt lgkmcnt(1)
	v_sub_f32_e32 v22, v0, v22
	v_mfma_f32_16x16x32_bf16 v[26:29], v[30:33], v[10:13], v[26:29]
	v_sub_f32_e32 v30, v0, v66
	v_mul_f32_e32 v30, 0x3fb8aa3b, v30
	v_exp_f32_e32 v30, v30
	v_mfma_f32_16x16x32_bf16 v[26:29], v[34:37], v[6:9], v[26:29]
	v_mul_f32_e32 v22, 0x3fb8aa3b, v22
	v_exp_f32_e32 v22, v22
	v_add_u32_e32 v36, v185, v45
	v_mfma_f32_16x16x32_bf16 v[26:29], v[62:65], v[2:5], v[26:29]
	s_nop 7
	v_mul_f32_e32 v26, v30, v26
	v_sub_f32_e32 v30, v0, v67
	v_mul_f32_e32 v30, 0x3fb8aa3b, v30
	v_exp_f32_e32 v30, v30
	v_mul_f32_e32 v26, v70, v26
	v_cndmask_b32_e64 v26, v26, 0, s[84:85]
	v_mul_f32_e32 v27, v30, v27
	v_sub_f32_e32 v30, v0, v68
	v_mul_f32_e32 v30, 0x3fb8aa3b, v30
	v_exp_f32_e32 v30, v30
	v_mul_f32_e32 v27, v71, v27
	v_cndmask_b32_e64 v27, v27, 0, s[2:3]
	v_cvt_pk_bf16_f32 v26, v26, v27
	v_mul_f32_e32 v28, v30, v28
	v_sub_f32_e32 v30, v0, v69
	v_mul_f32_e32 v30, 0x3fb8aa3b, v30
	v_exp_f32_e32 v30, v30
	v_mul_f32_e32 v28, v72, v28
	v_cndmask_b32_e64 v28, v28, 0, s[20:21]
	v_readlane_b32 s2, v254, 54
	v_mul_f32_e32 v29, v30, v29
	v_mul_f32_e32 v29, v73, v29
	v_cndmask_b32_e64 v29, v29, 0, s[88:89]
	v_cvt_pk_bf16_f32 v27, v28, v29
	ds_write_b64 v184, v[26:27] offset:34880
	v_mfma_f32_16x16x32_bf16 v[26:29], v[74:77], v[14:17], 0
	v_readlane_b32 s3, v254, 55
	v_mfma_f32_16x16x32_bf16 v[26:29], v[78:81], v[10:13], v[26:29]
	v_mfma_f32_16x16x32_bf16 v[26:29], v[82:85], v[6:9], v[26:29]
	v_mfma_f32_16x16x32_bf16 v[26:29], v[86:89], v[2:5], v[26:29]
	s_nop 7
	v_mul_f32_e32 v22, v22, v26
	s_waitcnt lgkmcnt(1)
	v_mul_f32_e32 v18, v18, v22
	v_sub_f32_e32 v22, v0, v23
	v_mul_f32_e32 v22, 0x3fb8aa3b, v22
	v_exp_f32_e32 v22, v22
	v_cndmask_b32_e64 v18, v18, 0, s[72:73]
	v_mul_f32_e32 v22, v22, v27
	v_mul_f32_e32 v19, v19, v22
	v_sub_f32_e32 v22, v0, v24
	v_mul_f32_e32 v22, 0x3fb8aa3b, v22
	v_exp_f32_e32 v22, v22
	v_cndmask_b32_e64 v19, v19, 0, s[76:77]
	v_cvt_pk_bf16_f32 v18, v18, v19
	v_mul_f32_e32 v22, v22, v28
	v_mul_f32_e32 v20, v20, v22
	v_sub_f32_e32 v22, v0, v25
	v_mul_f32_e32 v22, 0x3fb8aa3b, v22
	v_exp_f32_e32 v22, v22
	v_cndmask_b32_e64 v20, v20, 0, s[80:81]
	v_mul_f32_e32 v0, 0x3fb8aa3b, v0
	v_exp_f32_e32 v0, v0
	v_mul_f32_e32 v22, v22, v29
	v_mul_f32_e32 v21, v21, v22
	v_cndmask_b32_e64 v21, v21, 0, s[2:3]
	v_cvt_pk_bf16_f32 v19, v20, v21
	ds_write_b64 v184, v[18:19] offset:34912
	v_add_lshl_u32 v18, s0, v126, 6
	v_readlane_b32 s0, v254, 47
	s_add_u32 s0, s0, s94
	s_addc_u32 s1, s1, 0
	v_ashrrev_i32_e32 v19, 31, v18
	v_lshl_add_u64 v[26:27], s[0:1], 0, v[126:127]
	v_lshl_add_u64 v[18:19], v[18:19], 1, v[130:131]
	v_lshl_add_u64 v[26:27], v[26:27], 2, s[52:53]
	s_waitcnt lgkmcnt(0)
	s_barrier
	global_load_dwordx2 v[28:29], v[18:19], off
	global_load_dwordx2 v[32:33], v[18:19], off offset:32
	global_load_dwordx2 v[30:31], v[18:19], off offset:64
	global_load_dwordx2 v[38:39], v[18:19], off offset:96
	ds_read_b128 v[18:21], v188 offset:34816
	ds_read_b128 v[22:25], v188 offset:34880
	global_load_dword v43, v[26:27], off offset:8
	ds_read_b64_tr_b16 v[64:65], v36 offset:44608
	ds_read_b64_tr_b16 v[62:63], v36 offset:44032
	ds_read_b64_tr_b16 v[26:27], v36 offset:44064
	ds_read_b64_tr_b16 v[66:67], v36 offset:48640
	ds_read_b64_tr_b16 v[68:69], v36 offset:49216
	ds_read_b128 v[70:73], v182 offset:53248
	ds_read_b128 v[74:77], v182 offset:53312
	s_waitcnt lgkmcnt(1)
	v_mfma_f32_16x16x32_bf16 v[70:73], v[70:73], v[14:17], 0
	v_readlane_b32 s0, v254, 59
	v_readlane_b32 s1, v254, 60
	s_waitcnt lgkmcnt(0)
	v_mfma_f32_16x16x32_bf16 v[70:73], v[74:77], v[10:13], v[70:73]
	ds_read_b128 v[74:77], v182 offset:53376
	s_waitcnt lgkmcnt(0)
	v_mfma_f32_16x16x32_bf16 v[70:73], v[74:77], v[6:9], v[70:73]
	ds_read_b128 v[74:77], v182 offset:53440
	v_mfma_f32_16x16x32_bf16 v[62:65], v[62:65], v[18:21], 0
	v_mfma_f32_16x16x32_bf16 v[62:65], v[66:69], v[22:25], v[62:65]
	ds_read2_b64 v[66:69], v183 offset0:128 offset1:132
	s_waitcnt lgkmcnt(0)
	v_lshlrev_b32_e32 v34, 16, v66
	v_mfma_f32_16x16x32_bf16 v[70:73], v[74:77], v[2:5], v[70:73]
	v_and_b32_e32 v35, 0xffff0000, v66
	v_lshlrev_b32_e32 v37, 16, v67
	v_and_b32_e32 v45, 0xffff0000, v67
	s_waitcnt vmcnt(4)
	v_lshlrev_b32_e32 v66, 16, v28
	s_nop 2
	v_fma_f32 v62, v0, v70, v62
	v_and_b32_e32 v28, 0xffff0000, v28
	v_lshlrev_b32_e32 v67, 16, v29
	v_and_b32_e32 v29, 0xffff0000, v29
	s_waitcnt vmcnt(0)
	v_fmac_f32_e32 v62, v43, v34
	v_mul_f32_e32 v34, 0xbfb8aa3b, v66
	v_exp_f32_e32 v34, v34
	v_fmac_f32_e32 v65, v0, v73
	v_fmac_f32_e32 v65, v43, v45
	v_and_b32_e32 v45, 0xffff0000, v69
	v_add_f32_e32 v34, 1.0, v34
	v_rcp_f32_e32 v34, v34
	s_nop 0
	v_mul_f32_e32 v34, v34, v66
	v_mul_f32_e32 v62, v34, v62
	v_fma_f32 v34, v0, v71, v63
	v_fmac_f32_e32 v34, v43, v35
	v_mul_f32_e32 v35, 0xbfb8aa3b, v28
	v_exp_f32_e32 v35, v35
	v_lshlrev_b32_e32 v66, 16, v32
	v_and_b32_e32 v32, 0xffff0000, v32
	v_fmac_f32_e32 v61, v62, v62
	v_add_f32_e32 v35, 1.0, v35
	v_rcp_f32_e32 v35, v35
	s_nop 0
	v_mul_f32_e32 v28, v35, v28
	v_mul_f32_e32 v63, v28, v34
	v_mul_f32_e32 v34, 0xbfb8aa3b, v67
	v_exp_f32_e32 v34, v34
	v_fma_f32 v28, v0, v72, v64
	v_fmac_f32_e32 v28, v43, v37
	v_and_b32_e32 v35, 0xffff0000, v68
	v_add_f32_e32 v34, 1.0, v34
	v_rcp_f32_e32 v34, v34
	v_lshlrev_b32_e32 v37, 16, v69
	v_fmac_f32_e32 v61, v63, v63
	v_mul_f32_e32 v34, v34, v67
	v_mul_f32_e32 v64, v34, v28
	v_mul_f32_e32 v28, 0xbfb8aa3b, v29
	v_exp_f32_e32 v28, v28
	v_lshlrev_b32_e32 v34, 16, v68
	v_lshlrev_b32_e32 v68, 16, v33
	v_and_b32_e32 v33, 0xffff0000, v33
	v_add_f32_e32 v28, 1.0, v28
	v_rcp_f32_e32 v28, v28
	v_fmac_f32_e32 v61, v64, v64
	v_mul_f32_e32 v28, v28, v29
	v_mul_f32_e32 v65, v28, v65
	ds_read_b64_tr_b16 v[28:29], v36 offset:44640
	ds_read_b64_tr_b16 v[70:71], v36 offset:48672
	ds_read_b64_tr_b16 v[72:73], v36 offset:49248
	ds_read_b128 v[74:77], v182 offset:57600
	ds_read_b128 v[78:81], v182 offset:57664
	s_waitcnt lgkmcnt(1)
; #define LAS __attribute__((address_space(3)))
; __device__ __forceinline__ float siluf_(float x) { return x * __builtin_amdgcn_rcpf(1.f + fexp_(-x)); }
; #define MFMA(X, Y, C) __builtin_amdgcn_mfma_f32_16x16x32_bf16((X), (Y), (C), 0, 0, 0)
; __device__ void ssd_m2(const Params& p, LAS unsigned char* lds, int l, int b, int c, int g) {
;     ...
;         for (int pt = 0; pt < 4; ++pt) {
;             f32x4 a1 = {0.f, 0.f, 0.f, 0.f}, a2 = {0.f, 0.f, 0.f, 0.f};
; #pragma unroll
;             for (int kk = 0; kk < 2; ++kk) a1 = MFMA(frag_tr(X, 72, kk * 32, pt * 16, fr, fq), Yp[kk], a1);
; #pragma unroll
;             for (int kk = 0; kk < 4; ++kk) a2 = MFMA(frag_row(S, 136, pt * 16, kk * 32, fr, fq), Yc[kk], a2);
;             const int pp = pt * 16 + 4 * fq;
;             float xv[4], zv[4]; unpack4(*(const LAS u32x2*)(X + irow * 72 + pp), xv);
;             unpack4(zraw[pt], zv);
;             f32x4 r;
; #pragma unroll
;             for (int i = 0; i < 4; ++i) { const float y = a1[i] + ecum * a2[i] + Dh * xv[i]; r[i] = y * siluf_(zv[i]); ssq += r[i] * r[i]; }
;             gy[pr][pt] = r;
;         }
	v_mfma_f32_16x16x32_bf16 v[74:77], v[74:77], v[14:17], 0
	v_fmac_f32_e32 v61, v65, v65
	s_waitcnt lgkmcnt(0)
	v_mfma_f32_16x16x32_bf16 v[74:77], v[78:81], v[10:13], v[74:77]
	ds_read_b128 v[78:81], v182 offset:57728
	s_waitcnt lgkmcnt(0)
	v_mfma_f32_16x16x32_bf16 v[74:77], v[78:81], v[6:9], v[74:77]
	ds_read_b128 v[78:81], v182 offset:57792
	v_mfma_f32_16x16x32_bf16 v[26:29], v[26:29], v[18:21], 0
	s_waitcnt lgkmcnt(0)
	v_mfma_f32_16x16x32_bf16 v[74:77], v[78:81], v[2:5], v[74:77]
	v_mfma_f32_16x16x32_bf16 v[26:29], v[70:73], v[22:25], v[26:29]
	s_nop 7
	v_fma_f32 v26, v0, v74, v26
	v_fmac_f32_e32 v26, v43, v34
	v_mul_f32_e32 v34, 0xbfb8aa3b, v66
	v_exp_f32_e32 v34, v34
	v_fmac_f32_e32 v29, v0, v77
	v_fmac_f32_e32 v29, v43, v45
	v_add_f32_e32 v34, 1.0, v34
	v_rcp_f32_e32 v34, v34
	s_nop 0
	v_mul_f32_e32 v34, v34, v66
	v_mul_f32_e32 v66, v34, v26
	v_fma_f32 v26, v0, v75, v27
	v_mul_f32_e32 v27, 0xbfb8aa3b, v32
	v_exp_f32_e32 v27, v27
	v_fmac_f32_e32 v26, v43, v35
	v_fmac_f32_e32 v61, v66, v66
	v_add_f32_e32 v27, 1.0, v27
	v_rcp_f32_e32 v27, v27
	s_nop 0
	v_mul_f32_e32 v27, v27, v32
	v_mul_f32_e32 v67, v27, v26
	v_mul_f32_e32 v27, 0xbfb8aa3b, v68
	v_exp_f32_e32 v27, v27
	v_fma_f32 v26, v0, v76, v28
	v_fmac_f32_e32 v26, v43, v37
	v_fmac_f32_e32 v61, v67, v67
	v_add_f32_e32 v27, 1.0, v27
	v_rcp_f32_e32 v27, v27
	s_nop 0
	v_mul_f32_e32 v27, v27, v68
	v_mul_f32_e32 v68, v27, v26
	v_mul_f32_e32 v26, 0xbfb8aa3b, v33
	v_exp_f32_e32 v26, v26
	v_fmac_f32_e32 v61, v68, v68
	v_add_f32_e32 v26, 1.0, v26
	v_rcp_f32_e32 v26, v26
	s_nop 0
	v_mul_f32_e32 v26, v26, v33
	v_mul_f32_e32 v69, v26, v29
	ds_read_b64_tr_b16 v[26:27], v36 offset:44096
	ds_read_b64_tr_b16 v[28:29], v36 offset:44672
	ds_read_b64_tr_b16 v[32:33], v36 offset:48704
	ds_read_b64_tr_b16 v[34:35], v36 offset:49280
	ds_read_b128 v[70:73], v182 offset:61952
	ds_read_b128 v[74:77], v182 offset:62016
	s_waitcnt lgkmcnt(1)
	v_mfma_f32_16x16x32_bf16 v[70:73], v[70:73], v[14:17], 0
	v_fmac_f32_e32 v61, v69, v69
	s_waitcnt lgkmcnt(0)
	v_mfma_f32_16x16x32_bf16 v[70:73], v[74:77], v[10:13], v[70:73]
	ds_read_b128 v[74:77], v182 offset:62080
	s_waitcnt lgkmcnt(0)
	v_mfma_f32_16x16x32_bf16 v[70:73], v[74:77], v[6:9], v[70:73]
	ds_read_b128 v[74:77], v182 offset:62144
	v_mfma_f32_16x16x32_bf16 v[26:29], v[26:29], v[18:21], 0
	v_mfma_f32_16x16x32_bf16 v[32:35], v[32:35], v[22:25], v[26:29]
	s_waitcnt lgkmcnt(0)
	v_mfma_f32_16x16x32_bf16 v[70:73], v[74:77], v[2:5], v[70:73]
	s_nop 4
	ds_read2_b64 v[26:29], v183 offset0:136 offset1:140
	v_lshlrev_b32_e32 v74, 16, v30
	v_and_b32_e32 v30, 0xffff0000, v30
	v_lshlrev_b32_e32 v75, 16, v31
	v_and_b32_e32 v31, 0xffff0000, v31
	s_waitcnt lgkmcnt(0)
	v_lshlrev_b32_e32 v37, 16, v26
	v_fma_f32 v32, v0, v70, v32
	v_fmac_f32_e32 v32, v43, v37
	v_mul_f32_e32 v37, 0xbfb8aa3b, v74
	v_exp_f32_e32 v37, v37
	v_and_b32_e32 v26, 0xffff0000, v26
	v_lshlrev_b32_e32 v45, 16, v27
	v_and_b32_e32 v27, 0xffff0000, v27
	v_add_f32_e32 v37, 1.0, v37
	v_rcp_f32_e32 v37, v37
	v_fmac_f32_e32 v35, v0, v73
	v_fmac_f32_e32 v35, v43, v27
	v_mul_f32_e32 v37, v37, v74
	v_mul_f32_e32 v70, v37, v32
	v_fma_f32 v32, v0, v71, v33
	v_fmac_f32_e32 v32, v43, v26
	v_mul_f32_e32 v26, 0xbfb8aa3b, v30
	v_exp_f32_e32 v26, v26
	v_fmac_f32_e32 v61, v70, v70
	v_add_f32_e32 v26, 1.0, v26
	v_rcp_f32_e32 v26, v26
	s_nop 0
	v_mul_f32_e32 v26, v26, v30
	v_mul_f32_e32 v30, 0xbfb8aa3b, v75
	v_exp_f32_e32 v30, v30
	v_mul_f32_e32 v71, v26, v32
	v_fma_f32 v26, v0, v72, v34
	v_fmac_f32_e32 v26, v43, v45
	v_add_f32_e32 v30, 1.0, v30
	v_rcp_f32_e32 v30, v30
	v_ashrrev_i32_e32 v45, 31, v44
	v_fmac_f32_e32 v61, v71, v71
	v_mul_f32_e32 v30, v30, v75
	v_mul_f32_e32 v72, v30, v26
	v_mul_f32_e32 v26, 0xbfb8aa3b, v31
	v_exp_f32_e32 v26, v26
	v_fmac_f32_e32 v61, v72, v72
	v_add_f32_e32 v26, 1.0, v26
	v_rcp_f32_e32 v26, v26
	s_nop 0
	v_mul_f32_e32 v26, v26, v31
	v_mul_f32_e32 v73, v26, v35
	ds_read_b64_tr_b16 v[30:31], v36 offset:44128
	ds_read_b64_tr_b16 v[32:33], v36 offset:44704
	ds_read_b64_tr_b16 v[34:35], v36 offset:48736
	ds_read_b64_tr_b16 v[36:37], v36 offset:49312
	ds_read_b128 v[74:77], v129 offset:13056
	s_waitcnt lgkmcnt(0)
	v_mfma_f32_16x16x32_bf16 v[14:17], v[74:77], v[14:17], 0
	ds_read_b128 v[74:77], v129 offset:13120
	v_fmac_f32_e32 v61, v73, v73
	s_waitcnt lgkmcnt(0)
	v_mfma_f32_16x16x32_bf16 v[10:13], v[74:77], v[10:13], v[14:17]
	s_nop 3
	ds_read_b128 v[14:17], v129 offset:13184
	s_waitcnt lgkmcnt(0)
	v_mfma_f32_16x16x32_bf16 v[6:9], v[14:17], v[6:9], v[10:13]
	s_nop 2
	ds_read_b128 v[10:13], v129 offset:13248
	v_lshlrev_b32_e32 v14, 16, v38
	v_and_b32_e32 v15, 0xffff0000, v38
	s_waitcnt lgkmcnt(0)
	v_mfma_f32_16x16x32_bf16 v[2:5], v[10:13], v[2:5], v[6:9]
	v_lshlrev_b32_e32 v10, 16, v28
	v_and_b32_e32 v11, 0xffff0000, v28
	v_lshlrev_b32_e32 v16, 16, v39
	v_mfma_f32_16x16x32_bf16 v[6:9], v[30:33], v[18:21], 0
	v_and_b32_e32 v17, 0xffff0000, v39
	v_lshlrev_b32_e32 v12, 16, v29
	v_and_b32_e32 v13, 0xffff0000, v29
	v_mfma_f32_16x16x32_bf16 v[6:9], v[34:37], v[22:25], v[6:9]
	s_barrier
; #define LAS __attribute__((address_space(3)))
; __device__ __forceinline__ float siluf_(float x) { return x * __builtin_amdgcn_rcpf(1.f + fexp_(-x)); }
; __device__ __forceinline__ float shfl_xor_(float v, int o, int lane) { return shfl_idx(v, lane ^ o); }
; #define MFMA(X, Y, C) __builtin_amdgcn_mfma_f32_16x16x32_bf16((X), (Y), (C), 0, 0, 0)
; __device__ void ssd_m2(const Params& p, LAS unsigned char* lds, int l, int b, int c, int g) {
;     ...
;         for (int pt = 0; pt < 4; ++pt) {
;             f32x4 a1 = {0.f, 0.f, 0.f, 0.f}, a2 = {0.f, 0.f, 0.f, 0.f};
; #pragma unroll
;             for (int kk = 0; kk < 2; ++kk) a1 = MFMA(frag_tr(X, 72, kk * 32, pt * 16, fr, fq), Yp[kk], a1);
; #pragma unroll
;             for (int kk = 0; kk < 4; ++kk) a2 = MFMA(frag_row(S, 136, pt * 16, kk * 32, fr, fq), Yc[kk], a2);
;             const int pp = pt * 16 + 4 * fq;
;             float xv[4], zv[4]; unpack4(*(const LAS u32x2*)(X + irow * 72 + pp), xv);
;             unpack4(zraw[pt], zv);
;             f32x4 r;
; #pragma unroll
;             for (int i = 0; i < 4; ++i) { const float y = a1[i] + ecum * a2[i] + Dh * xv[i]; r[i] = y * siluf_(zv[i]); ssq += r[i] * r[i]; }
;             gy[pr][pt] = r;
;         }
;         __syncthreads();
;     }
;     f32x4 ngv[2][4];
; #pragma unroll
;     for (int pr = 0; pr < 2; ++pr)
; #pragma unroll
;         for (int pt = 0; pt < 4; ++pt) ngv[pr][pt] = *(const f32x4*)(p.in[23] + l * 512 + g * 256 + (2 * pr + hh) * 64 + pt * 16 + 4 * fq);
;     ssq += shfl_xor_(ssq, 16, lane); ssq += shfl_xor_(ssq, 32, lane);
;     if (fq == 0) ssqb[irow * 2 + hh] = ssq;
	s_nop 6
	v_fma_f32 v2, v0, v2, v6
	v_mul_f32_e32 v6, 0xbfb8aa3b, v14
	v_exp_f32_e32 v6, v6
	v_fmac_f32_e32 v2, v43, v10
	v_fmac_f32_e32 v9, v0, v5
	v_fmac_f32_e32 v9, v43, v13
	v_add_f32_e32 v6, 1.0, v6
	v_rcp_f32_e32 v6, v6
	s_nop 0
	v_mul_f32_e32 v6, v6, v14
	v_mul_f32_e32 v34, v6, v2
	v_fma_f32 v2, v0, v3, v7
	v_mul_f32_e32 v3, 0xbfb8aa3b, v15
	v_exp_f32_e32 v3, v3
	v_fmac_f32_e32 v2, v43, v11
	v_fmac_f32_e32 v61, v34, v34
	v_add_f32_e32 v3, 1.0, v3
	v_rcp_f32_e32 v3, v3
	s_nop 0
	v_mul_f32_e32 v3, v3, v15
	v_mul_f32_e32 v35, v3, v2
	v_fma_f32 v2, v0, v4, v8
	v_mul_f32_e32 v3, 0xbfb8aa3b, v16
	v_mul_f32_e32 v0, 0xbfb8aa3b, v17
	v_exp_f32_e32 v3, v3
	v_exp_f32_e32 v0, v0
	v_fmac_f32_e32 v2, v43, v12
	v_mov_b32_e32 v43, v1
	v_add_f32_e32 v3, 1.0, v3
	v_add_f32_e32 v0, 1.0, v0
	v_rcp_f32_e32 v3, v3
	v_rcp_f32_e32 v0, v0
	v_fmac_f32_e32 v61, v35, v35
	v_mul_f32_e32 v3, v3, v16
	v_mul_f32_e32 v0, v0, v17
	v_mul_f32_e32 v36, v3, v2
	v_mul_f32_e32 v37, v0, v9
	v_lshl_add_u64 v[2:3], v[42:43], 2, s[0:1]
	v_lshlrev_b32_e32 v0, 2, v168
	v_lshl_add_u64 v[2:3], v[2:3], 0, v[0:1]
	v_lshl_add_u64 v[2:3], v[44:45], 2, v[2:3]
	global_load_dwordx4 v[30:33], v[2:3], off
	global_load_dwordx4 v[26:29], v[2:3], off offset:64
	global_load_dwordx4 v[22:25], v[2:3], off offset:128
	global_load_dwordx4 v[18:21], v[2:3], off offset:192
	global_load_dwordx4 v[14:17], v[2:3], off offset:512
	global_load_dwordx4 v[10:13], v[2:3], off offset:576
	global_load_dwordx4 v[6:9], v[2:3], off offset:640
	s_nop 0
	global_load_dwordx4 v[2:5], v[2:3], off offset:704
	v_fmac_f32_e32 v61, v36, v36
	v_lshlrev_b32_e32 v0, 2, v46
	v_fmac_f32_e32 v61, v37, v37
	v_xor_b32_e32 v38, 64, v0
	ds_bpermute_b32 v38, v38, v61
	v_xor_b32_e32 v0, 0x80, v0
	s_waitcnt lgkmcnt(0)
	v_add_f32_e32 v38, v61, v38
	ds_bpermute_b32 v39, v0, v38
	v_lshlrev_b32_e32 v0, 3, v171
	s_and_saveexec_b64 s[0:1], vcc
	s_mov_b32 s96, 0xa000
	s_cbranch_execz .LBB0_301
	s_waitcnt lgkmcnt(0)
	v_add_f32_e32 v38, v38, v39
	v_lshlrev_b32_e32 v39, 2, v126
	v_readlane_b32 s2, v253, 58
	s_nop 1
	v_add3_u32 v39, s2, v0, v39
	ds_write_b32 v39, v38
	s_branch .LBB0_301

; #define LAS __attribute__((address_space(3)))
; #define TIDX opaque_tid()
; __device__ __forceinline__ float fexp_(float x) { return __builtin_amdgcn_exp2f(x * 1.44269504089f); }
; __device__ __forceinline__ float ret_logg(int h) { return log1pf(-exp2f(-5.f - (float)h)); }
; __device__ void ret_m1(const Params& p, LAS unsigned char* lds, int b, int c) {
;     const int tid = TIDX, wid = tid >> 6, lane = tid & 63, fr = lane & 15, fq = lane >> 4;
;     const bf16_t* proj = (const bf16_t*)(p.ws + W_PROJ);
;     const float* rc = (const float*)(p.ws + W_ROPE); const float* rs = rc + 2049 * 32;
;     float* dS = (float*)(p.ws + W_DS);
;     LAS bf16_t* Kt = (LAS bf16_t*)lds;
;     LAS bf16_t* Vt = (LAS bf16_t*)(lds + 33792);
;     const int row0 = b * SEQ + c * 64, pos0 = c * 64;
;     {
;         const int j = tid >> 3, sub = tid & 7, h = sub >> 1, d0 = (sub & 1) * 16;
;         const float scale = 0.125f * fexp_((float)(63 - j) * ret_logg(h));
;         rot16(proj + (size_t)(row0 + j) * NPROJ + PC_K + h * 64 + d0, rc + (pos0 + j) * 32 + d0, rs + (pos0 + j) * 32 + d0, scale, Kt + j * 264 + h * 64 + d0);
.LBB0_384:
	v_mov_b32_e32 v34, v163
	s_mov_b32 s26, 0xc2fc0000
	v_bfe_u32 v0, v34, 1, 2
	v_cvt_f32_ubyte0_e32 v4, v0
	v_sub_f32_e32 v4, 0xc0a00000, v4
	v_cmp_gt_f32_e32 vcc, s26, v4
	s_mov_b32 s26, 0x3f2aaaab
	s_waitcnt lgkmcnt(0)
	v_ashrrev_i32_e32 v2, 3, v34
	v_cndmask_b32_e32 v5, 0, v230, vcc
	v_add_f32_e32 v4, v4, v5
	v_exp_f32_e32 v4, v4
	v_cndmask_b32_e32 v5, 0, v231, vcc
	v_sub_u32_e32 v3, 63, v2
	v_cvt_f32_i32_e32 v3, v3
	v_ldexp_f32 v20, v4, v5
	v_sub_f32_e32 v6, 1.0, v20
	v_add_f32_e32 v4, -1.0, v6
	v_sub_f32_e32 v5, v4, v6
	v_add_f32_e32 v5, 1.0, v5
	v_sub_f32_e64 v4, -v20, v4
	v_add_f32_e32 v7, v4, v5
	v_frexp_mant_f32_e32 v4, v6
	v_cmp_gt_f32_e32 vcc, s26, v4
	v_cvt_f64_f32_e32 v[4:5], v6
	v_frexp_exp_i32_f64_e32 v4, v[4:5]
	v_subbrev_co_u32_e32 v14, vcc, 0, v4, vcc
	v_sub_u32_e32 v4, 0, v14
	v_ldexp_f32 v5, v6, v4
	v_add_f32_e32 v6, -1.0, v5
	v_add_f32_e32 v10, 1.0, v5
	v_ldexp_f32 v4, v7, v4
	v_add_f32_e32 v7, 1.0, v6
	v_add_f32_e32 v11, -1.0, v10
	v_sub_f32_e32 v7, v5, v7
	v_sub_f32_e32 v5, v5, v11
	v_add_f32_e32 v7, v4, v7
	v_add_f32_e32 v4, v4, v5
	v_add_f32_e32 v15, v10, v4
	v_rcp_f32_e32 v17, v15
	v_sub_f32_e32 v5, v15, v10
	v_sub_f32_e32 v16, v4, v5
	v_add_f32_e32 v5, v6, v7
	v_mul_f32_e32 v19, v5, v17
	v_sub_f32_e32 v4, v5, v6
	v_mul_f32_e32 v6, v15, v19
	v_fma_f32 v10, v19, v15, -v6
	v_fmac_f32_e32 v10, v19, v16
	v_sub_f32_e32 v18, v7, v4
	v_add_f32_e32 v4, v6, v10
	v_sub_f32_e32 v7, v5, v4
	v_pk_add_f32 v[12:13], v[4:5], v[6:7] neg_lo:[0,1] neg_hi:[0,1]
	v_mov_b32_e32 v11, v4
	v_pk_add_f32 v[4:5], v[12:13], v[10:11] neg_lo:[0,1] neg_hi:[0,1]
	s_mov_b32 s26, 0x3f317218
	v_add_f32_e32 v5, v18, v5
	v_add_f32_e32 v4, v4, v5
	v_add_f32_e32 v5, v7, v4
	v_mul_f32_e32 v18, v17, v5
	v_mul_f32_e32 v6, v15, v18
	v_fma_f32 v10, v18, v15, -v6
	v_fmac_f32_e32 v10, v18, v16
	v_sub_f32_e32 v7, v7, v5
	v_add_f32_e32 v15, v4, v7
	v_add_f32_e32 v4, v6, v10
	v_sub_f32_e32 v7, v5, v4
	v_pk_add_f32 v[12:13], v[4:5], v[6:7] neg_lo:[0,1] neg_hi:[0,1]
	v_mov_b32_e32 v11, v4
	v_pk_add_f32 v[4:5], v[12:13], v[10:11] neg_lo:[0,1] neg_hi:[0,1]
	v_cmp_nlt_f32_e32 vcc, 1.0, v20
	v_add_f32_e32 v5, v15, v5
	v_add_f32_e32 v4, v4, v5
	v_add_f32_e32 v5, v19, v18
	v_add_f32_e32 v4, v7, v4
	v_sub_f32_e32 v6, v5, v19
	v_mul_f32_e32 v4, v17, v4
	v_sub_f32_e32 v6, v18, v6
	v_add_f32_e32 v6, v6, v4
	v_add_f32_e32 v10, v5, v6
	v_mul_f32_e32 v11, v10, v10
	v_fmamk_f32 v4, v11, 0x3e9b6dac, v225
	v_fmaak_f32 v171, v11, v4, 0x3f2aaada
	v_cvt_f32_i32_e32 v4, v14
	v_sub_f32_e32 v5, v10, v5
	v_sub_f32_e32 v5, v6, v5
	v_ldexp_f32 v12, v5, 1
	v_mul_f32_e32 v5, v10, v11
	v_ldexp_f32 v7, v10, 1
	v_pk_mul_f32 v[10:11], v[4:5], v[170:171]
	s_ashr_i32 s1, s0, 5
	v_fma_f32 v6, v4, s26, -v10
	v_fmac_f32_e32 v6, 0xb102e308, v4
	v_pk_add_f32 v[4:5], v[10:11], v[6:7]
	s_and_b32 s2, s0, 31
	v_sub_f32_e32 v7, v5, v7
	v_sub_f32_e32 v7, v11, v7
	v_add_f32_e32 v13, v12, v7
	v_mov_b32_e32 v12, v10
	v_pk_add_f32 v[10:11], v[4:5], v[10:11] neg_lo:[0,1] neg_hi:[0,1]
	v_pk_add_f32 v[14:15], v[4:5], v[12:13]
	v_mov_b32_e32 v7, v4
	v_mov_b32_e32 v11, v15
	v_pk_add_f32 v[16:17], v[6:7], v[10:11] neg_lo:[0,1] neg_hi:[0,1]
	v_pk_add_f32 v[6:7], v[6:7], v[10:11]
	v_mov_b32_e32 v12, v13
	v_pk_add_f32 v[10:11], v[6:7], v[4:5] op_sel:[1,0] op_sel_hi:[0,1] neg_lo:[0,1] neg_hi:[0,1]
	v_pk_add_f32 v[18:19], v[14:15], v[10:11] op_sel_hi:[1,0] neg_lo:[0,1] neg_hi:[0,1]
	v_mov_b32_e32 v14, v15
	v_mov_b32_e32 v15, v7
	v_pk_mov_b32 v[10:11], v[4:5], v[10:11] op_sel:[1,0]
	v_mov_b32_e32 v13, v4
	v_pk_add_f32 v[10:11], v[14:15], v[10:11] neg_lo:[0,1] neg_hi:[0,1]
	v_mov_b32_e32 v18, v16
	v_pk_add_f32 v[4:5], v[12:13], v[10:11] neg_lo:[0,1] neg_hi:[0,1]
	v_mov_b32_e32 v17, v7
	v_pk_add_f32 v[10:11], v[18:19], v[4:5]
	s_mov_b32 s26, 0x33800000
	v_pk_add_f32 v[12:13], v[10:11], v[10:11] op_sel:[0,1] op_sel_hi:[1,0]
	s_lshl_b32 s3, s1, 11
	v_pk_add_f32 v[6:7], v[6:7], v[12:13] op_sel:[1,0] op_sel_hi:[0,1]
	v_mov_b32_e32 v11, v6
	v_pk_add_f32 v[14:15], v[10:11], v[16:17] neg_lo:[0,1] neg_hi:[0,1]
	v_mov_b32_e32 v5, v12
	v_sub_f32_e32 v7, v10, v14
	v_pk_add_f32 v[4:5], v[4:5], v[14:15] neg_lo:[0,1] neg_hi:[0,1]
	v_sub_f32_e32 v7, v16, v7
	v_add_f32_e32 v4, v4, v7
	v_add_f32_e32 v4, v4, v5
	v_add_f32_e32 v4, v6, v4
	v_cndmask_b32_e32 v4, v232, v4, vcc
	v_cmp_neq_f32_e32 vcc, 1.0, v20
	s_lshl_b32 s24, s2, 6
	s_or_b32 s3, s24, s3
	v_cndmask_b32_e32 v4, v233, v4, vcc
	v_cmp_gt_f32_e32 vcc, s26, v20
	v_lshlrev_b32_e32 v8, 4, v34
	v_and_b32_e32 v9, 16, v8
	v_cndmask_b32_e64 v4, v4, -v20, vcc
	v_mul_f32_e32 v3, v4, v3
	v_add_u32_e32 v4, s3, v2
	v_ashrrev_i32_e32 v5, 31, v4
	v_lshlrev_b64 v[4:5], 13, v[4:5]
	v_lshl_add_u64 v[4:5], s[34:35], 0, v[4:5]
	v_lshlrev_b32_e32 v0, 7, v0
	v_lshl_add_u64 v[6:7], v[4:5], 0, v[0:1]
	v_lshlrev_b32_e32 v4, 1, v9
	v_mov_b32_e32 v5, v1
	v_lshl_add_u64 v[18:19], v[6:7], 0, v[4:5]
	v_add_lshl_u32 v6, v2, s24, 5
	v_ashrrev_i32_e32 v7, 31, v6
	v_readlane_b32 s36, v254, 36
	v_lshlrev_b64 v[6:7], 2, v[6:7]
	v_readlane_b32 s37, v254, 37
	s_movk_i32 s24, 0x210
	v_lshlrev_b32_e32 v12, 2, v9
	v_lshl_add_u64 v[10:11], s[36:37], 0, v[6:7]
	v_readlane_b32 s36, v254, 38
	v_readlane_b32 s37, v254, 39
	v_mov_b32_e32 v13, v1
	v_mul_lo_u32 v2, v2, s24
	v_lshl_add_u64 v[6:7], s[36:37], 0, v[6:7]
	v_lshl_add_u64 v[36:37], v[10:11], 0, v[12:13]
	v_lshl_add_u64 v[52:53], v[6:7], 0, v[12:13]
	v_add_u32_e32 v2, 0, v2
	v_add3_u32 v0, v2, v0, v4
	global_load_dwordx4 v[4:7], v[18:19], off offset:2576
	global_load_dwordx4 v[10:13], v[18:19], off offset:2560
	global_load_dwordx4 v[14:17], v[18:19], off offset:2640
	s_nop 0
	global_load_dwordx4 v[18:21], v[18:19], off offset:2624
	s_waitcnt lgkmcnt(0)
; #define LAS __attribute__((address_space(3)))
; __device__ __forceinline__ u32x4 pack8(const float* f) { u32x4 w; w.x = pk2(f[0], f[1]); w.y = pk2(f[2], f[3]); w.z = pk2(f[4], f[5]); w.w = pk2(f[6], f[7]); return w; }
; __device__ __forceinline__ void rot16(const bf16_t* src, const float* rc, const float* rs, float scale, LAS bf16_t* dst) {
;     float x1[16], x2[16], o1[16], o2[16];
;     unpack8(*(const u32x4*)src, x1); unpack8(*(const u32x4*)(src + 8), x1 + 8);
;     unpack8(*(const u32x4*)(src + 32), x2); unpack8(*(const u32x4*)(src + 40), x2 + 8);
; #pragma unroll
;     for (int e = 0; e < 16; ++e) { const float c = rc[e], s = rs[e]; o1[e] = (x1[e] * c - x2[e] * s) * scale; o2[e] = (x1[e] * s + x2[e] * c) * scale; }
;     *(LAS u32x4*)dst = pack8(o1); *(LAS u32x4*)(dst + 8) = pack8(o1 + 8);
;     *(LAS u32x4*)(dst + 32) = pack8(o2); *(LAS u32x4*)(dst + 40) = pack8(o2 + 8);
	global_load_dwordx4 v[22:25], v[36:37], off offset:48
	global_load_dwordx4 v[26:29], v[36:37], off offset:32
	global_load_dwordx4 v[30:33], v[36:37], off offset:16
	s_nop 0
	global_load_dwordx4 v[36:39], v[36:37], off
	s_nop 0
	global_load_dwordx4 v[40:43], v[52:53], off offset:48
	global_load_dwordx4 v[44:47], v[52:53], off offset:32
	global_load_dwordx4 v[48:51], v[52:53], off offset:16
	s_nop 0
	global_load_dwordx4 v[52:55], v[52:53], off
	v_mul_f32_e32 v3, 0x3fb8aa3b, v3
	v_exp_f32_e32 v3, v3
	s_movk_i32 s24, 0x410
	s_waitcnt vmcnt(10)
	v_lshlrev_b32_e32 v56, 16, v10
	s_waitcnt vmcnt(8)
	v_lshlrev_b32_e32 v57, 16, v18
	s_waitcnt vmcnt(5)
	v_mov_b32_e32 v2, v32
	s_waitcnt vmcnt(4)
	v_mov_b32_e32 v58, v36
	v_mov_b32_e32 v61, v36
	v_mov_b32_e32 v65, v38
	s_waitcnt vmcnt(0)
	v_mov_b32_e32 v59, v52
	v_mov_b32_e32 v60, v52
	v_pk_mul_f32 v[58:59], v[58:59], v[56:57]
	v_pk_mul_f32 v[56:57], v[60:61], v[56:57]
	v_and_b32_e32 v61, 0xffff0000, v18
	v_and_b32_e32 v60, 0xffff0000, v10
	v_mov_b32_e32 v52, v37
	v_mov_b32_e32 v36, v53
	v_pk_mul_f32 v[62:63], v[52:53], v[60:61]
	v_pk_mul_f32 v[36:37], v[36:37], v[60:61]
	v_lshlrev_b32_e32 v53, 16, v19
	v_lshlrev_b32_e32 v52, 16, v11
	v_mov_b32_e32 v60, v38
	v_mov_b32_e32 v61, v54
	v_mov_b32_e32 v64, v54
	v_and_b32_e32 v19, 0xffff0000, v19
	v_and_b32_e32 v18, 0xffff0000, v11
	v_mov_b32_e32 v54, v39
	v_mov_b32_e32 v38, v55
	v_pk_mul_f32 v[60:61], v[60:61], v[52:53]
	v_pk_mul_f32 v[52:53], v[64:65], v[52:53]
	v_pk_mul_f32 v[10:11], v[54:55], v[18:19]
	v_pk_mul_f32 v[18:19], v[38:39], v[18:19]
	v_lshlrev_b32_e32 v39, 16, v20
	v_lshlrev_b32_e32 v38, 16, v12
	v_mov_b32_e32 v54, v30
	v_mov_b32_e32 v55, v48
	v_mov_b32_e32 v64, v48
	v_mov_b32_e32 v65, v30
	v_pk_mul_f32 v[54:55], v[54:55], v[38:39]
	v_pk_mul_f32 v[38:39], v[64:65], v[38:39]
	v_and_b32_e32 v65, 0xffff0000, v20
	v_and_b32_e32 v64, 0xffff0000, v12
	v_mov_b32_e32 v48, v31
	v_pk_mul_f32 v[66:67], v[48:49], v[64:65]
	v_mov_b32_e32 v30, v49
	v_lshlrev_b32_e32 v49, 16, v13
	v_mov_b32_e32 v168, v49
	v_pk_mul_f32 v[2:3], v[2:3], v[168:169]
	v_add_f32_e32 v12, v57, v56
	v_mul_f32_e32 v20, v12, v3
	v_sub_f32_e32 v12, v62, v63
	v_mul_f32_e32 v35, v12, v3
	v_add_f32_e32 v12, v37, v36
	v_mul_f32_e32 v36, v12, v3
	v_sub_f32_e32 v12, v60, v61
	v_sub_f32_e32 v10, v10, v11
	v_mul_f32_e32 v37, v12, v3
	v_add_f32_e32 v12, v53, v52
	v_mul_f32_e32 v53, v10, v3
	v_add_f32_e32 v10, v19, v18
	v_mul_f32_e32 v18, v10, v3
	v_sub_f32_e32 v10, v54, v55
	v_mul_f32_e32 v19, v10, v3
	v_add_f32_e32 v10, v39, v38
	v_pk_mul_f32 v[30:31], v[30:31], v[64:65]
	v_mul_f32_e32 v38, v10, v3
	v_sub_f32_e32 v10, v66, v67
	v_mul_f32_e32 v39, v10, v3
	v_add_f32_e32 v10, v31, v30
	v_lshlrev_b32_e32 v48, 16, v21
	v_mul_f32_e32 v30, v10, v3
	v_mov_b32_e32 v10, v32
	v_mov_b32_e32 v11, v50
	v_fma_f32 v2, -v50, v48, v2
	v_pk_mul_f32 v[10:11], v[10:11], v[48:49]
	v_mul_f32_e32 v31, v2, v3
	v_add_f32_e32 v2, v10, v11
	v_and_b32_e32 v11, 0xffff0000, v21
	v_and_b32_e32 v10, 0xffff0000, v13
	v_mov_b32_e32 v50, v33
	v_mul_f32_e32 v52, v12, v3
	v_pk_mul_f32 v[12:13], v[50:51], v[10:11]
	v_mov_b32_e32 v32, v51
	v_mul_f32_e32 v48, v2, v3
	v_sub_f32_e32 v2, v12, v13
	v_pk_mul_f32 v[10:11], v[32:33], v[10:11]
	v_mul_f32_e32 v21, v2, v3
	v_add_f32_e32 v2, v11, v10
	v_lshlrev_b32_e32 v11, 16, v14
	v_lshlrev_b32_e32 v10, 16, v4
	v_mov_b32_e32 v12, v26
	v_mov_b32_e32 v13, v44
	v_pk_mul_f32 v[12:13], v[12:13], v[10:11]
	v_mul_f32_e32 v32, v2, v3
	v_sub_f32_e32 v2, v12, v13
	v_mov_b32_e32 v12, v44
	v_mov_b32_e32 v13, v26
	v_pk_mul_f32 v[10:11], v[12:13], v[10:11]
	v_mul_f32_e32 v33, v2, v3
	v_add_f32_e32 v2, v11, v10
	v_and_b32_e32 v11, 0xffff0000, v14
	v_and_b32_e32 v10, 0xffff0000, v4
	v_mov_b32_e32 v44, v27
	v_pk_mul_f32 v[12:13], v[44:45], v[10:11]
	v_mov_b32_e32 v26, v45
	v_mul_f32_e32 v49, v2, v3
	v_sub_f32_e32 v2, v12, v13
	v_pk_mul_f32 v[10:11], v[26:27], v[10:11]
	v_mul_f32_e32 v14, v2, v3
	v_add_f32_e32 v2, v11, v10
	v_lshlrev_b32_e32 v11, 16, v15
	v_lshlrev_b32_e32 v10, 16, v5
	v_mov_b32_e32 v12, v28
	v_mov_b32_e32 v13, v46
	v_pk_mul_f32 v[12:13], v[12:13], v[10:11]
	v_mul_f32_e32 v26, v2, v3
	v_sub_f32_e32 v2, v12, v13
	v_mov_b32_e32 v12, v46
	v_mov_b32_e32 v13, v28
	v_pk_mul_f32 v[10:11], v[12:13], v[10:11]
	v_mul_f32_e32 v27, v2, v3
	v_add_f32_e32 v2, v11, v10
	v_and_b32_e32 v11, 0xffff0000, v15
	v_and_b32_e32 v10, 0xffff0000, v5
	v_mov_b32_e32 v46, v29
	v_pk_mul_f32 v[4:5], v[46:47], v[10:11]
	v_mov_b32_e32 v28, v47
	v_mul_f32_e32 v12, v2, v3
	v_sub_f32_e32 v2, v4, v5
	v_pk_mul_f32 v[4:5], v[28:29], v[10:11]
	v_mul_f32_e32 v13, v2, v3
	v_add_f32_e32 v2, v5, v4
	v_lshlrev_b32_e32 v5, 16, v16
	v_lshlrev_b32_e32 v4, 16, v6
	v_mov_b32_e32 v10, v22
	v_mov_b32_e32 v11, v40
	v_pk_mul_f32 v[10:11], v[10:11], v[4:5]
	v_mul_f32_e32 v15, v2, v3
	v_sub_f32_e32 v2, v10, v11
	v_mov_b32_e32 v10, v40
	v_mov_b32_e32 v11, v22
	v_pk_mul_f32 v[4:5], v[10:11], v[4:5]
	v_mul_f32_e32 v28, v2, v3
	v_add_f32_e32 v2, v5, v4
	v_and_b32_e32 v5, 0xffff0000, v16
	v_and_b32_e32 v4, 0xffff0000, v6
	v_mov_b32_e32 v40, v23
	v_pk_mul_f32 v[10:11], v[40:41], v[4:5]
	v_mov_b32_e32 v22, v41
	v_mul_f32_e32 v29, v2, v3
	v_sub_f32_e32 v2, v10, v11
	v_pk_mul_f32 v[4:5], v[22:23], v[4:5]
	v_mul_f32_e32 v16, v2, v3
	v_add_f32_e32 v2, v5, v4
	v_lshlrev_b32_e32 v5, 16, v17
	v_lshlrev_b32_e32 v4, 16, v7
	v_mov_b32_e32 v10, v24
	v_mov_b32_e32 v11, v42
	v_pk_mul_f32 v[10:11], v[10:11], v[4:5]
	v_mul_f32_e32 v22, v2, v3
	v_sub_f32_e32 v2, v10, v11
	v_mov_b32_e32 v10, v42
	v_mov_b32_e32 v11, v24
	v_pk_mul_f32 v[4:5], v[10:11], v[4:5]
	v_mul_f32_e32 v23, v2, v3
	v_add_f32_e32 v2, v5, v4
	v_and_b32_e32 v5, 0xffff0000, v17
	v_and_b32_e32 v4, 0xffff0000, v7
; #define LAS __attribute__((address_space(3)))
; #define TIDX opaque_tid()
; __device__ __forceinline__ u32x4 pack8(const float* f) { u32x4 w; w.x = pk2(f[0], f[1]); w.y = pk2(f[2], f[3]); w.z = pk2(f[4], f[5]); w.w = pk2(f[6], f[7]); return w; }
; __device__ __forceinline__ float fexp_(float x) { return __builtin_amdgcn_exp2f(x * 1.44269504089f); }
; __device__ __forceinline__ float ret_logg(int h) { return log1pf(-exp2f(-5.f - (float)h)); }
; __device__ __forceinline__ void rot16(const bf16_t* src, const float* rc, const float* rs, float scale, LAS bf16_t* dst) {
;     ...
;     *(LAS u32x4*)dst = pack8(o1); *(LAS u32x4*)(dst + 8) = pack8(o1 + 8);
;     *(LAS u32x4*)(dst + 32) = pack8(o2); *(LAS u32x4*)(dst + 40) = pack8(o2 + 8);
; }
; __device__ void ret_m1(const Params& p, LAS unsigned char* lds, int b, int c) {
;     const int tid = TIDX, wid = tid >> 6, lane = tid & 63, fr = lane & 15, fq = lane >> 4;
;     const bf16_t* proj = (const bf16_t*)(p.ws + W_PROJ);
;     const float* rc = (const float*)(p.ws + W_ROPE); const float* rs = rc + 2049 * 32;
;     float* dS = (float*)(p.ws + W_DS);
;     LAS bf16_t* Kt = (LAS bf16_t*)lds;
;     LAS bf16_t* Vt = (LAS bf16_t*)(lds + 33792);
;     const int row0 = b * SEQ + c * 64, pos0 = c * 64;
;     {
;         const int j = tid >> 3, sub = tid & 7, h = sub >> 1, d0 = (sub & 1) * 16;
;         const float scale = 0.125f * fexp_((float)(63 - j) * ret_logg(h));
;         rot16(proj + (size_t)(row0 + j) * NPROJ + PC_K + h * 64 + d0, rc + (pos0 + j) * 32 + d0, rs + (pos0 + j) * 32 + d0, scale, Kt + j * 264 + h * 64 + d0);
; #pragma unroll
;         for (int i = 0; i < 8; ++i) { const int id = tid + 512 * i, jj = id >> 6, cc = id & 63;
;             *(LAS u32x4*)(Vt + jj * 520 + cc * 8) = *(const u32x4*)(proj + (size_t)(row0 + jj) * NPROJ + PC_V + cc * 8); }
;     }
;     __syncthreads();
	v_mov_b32_e32 v42, v25
	v_pk_mul_f32 v[6:7], v[42:43], v[4:5]
	v_mov_b32_e32 v24, v43
	v_mul_f32_e32 v10, v2, v3
	v_sub_f32_e32 v2, v6, v7
	v_pk_mul_f32 v[4:5], v[24:25], v[4:5]
	v_sub_f32_e32 v9, v58, v59
	v_mul_f32_e32 v6, v2, v3
	v_add_f32_e32 v2, v5, v4
	v_mul_f32_e32 v9, v9, v3
	v_mul_f32_e32 v7, v2, v3
	v_cvt_pk_bf16_f32 v2, v9, v35
	v_cvt_pk_bf16_f32 v3, v37, v53
	v_cvt_pk_bf16_f32 v4, v19, v39
	v_cvt_pk_bf16_f32 v5, v31, v21
	ds_write_b128 v0, v[2:5]
	v_cvt_pk_bf16_f32 v2, v33, v14
	v_cvt_pk_bf16_f32 v3, v27, v13
	v_cvt_pk_bf16_f32 v4, v28, v16
	v_cvt_pk_bf16_f32 v5, v23, v6
	ds_write_b128 v0, v[2:5] offset:16
	v_cvt_pk_bf16_f32 v2, v20, v36
	v_cvt_pk_bf16_f32 v3, v52, v18
	v_cvt_pk_bf16_f32 v4, v38, v30
	v_cvt_pk_bf16_f32 v5, v48, v32
	ds_write_b128 v0, v[2:5] offset:64
	v_cvt_pk_bf16_f32 v2, v49, v26
	v_cvt_pk_bf16_f32 v3, v12, v15
	v_cvt_pk_bf16_f32 v4, v29, v22
	v_cvt_pk_bf16_f32 v5, v10, v7
	ds_write_b128 v0, v[2:5] offset:80
	v_ashrrev_i32_e32 v3, 6, v34
	v_add_u32_e32 v4, s3, v3
	v_ashrrev_i32_e32 v5, 31, v4
	v_lshlrev_b64 v[4:5], 13, v[4:5]
	v_and_b32_e32 v0, 0x3f0, v8
	v_lshl_add_u64 v[4:5], s[34:35], 0, v[4:5]
	v_lshl_add_u64 v[4:5], v[4:5], 0, v[0:1]
	global_load_dwordx4 v[92:95], v[4:5], off offset:3072
	v_add_u32_e32 v2, 0, v0
	v_mad_u64_u32 v[132:133], s[36:37], v3, s24, v[2:3]
	v_add_u32_e32 v3, 0x200, v34
	v_ashrrev_i32_e32 v3, 6, v3
	v_lshlrev_b32_e32 v10, 3, v34
	v_and_b32_e32 v40, 15, v34
	v_and_b32_e32 v37, 0xffffff80, v34
	v_bfe_u32 v42, v34, 6, 1
	v_add_u32_e32 v38, 0, v37
	v_and_b32_e32 v41, 24, v10
	v_lshlrev_b32_e32 v39, 7, v42
	v_add3_u32 v37, v38, v37, v39
	v_add_u32_e32 v4, s3, v3
	v_ashrrev_i32_e32 v5, 31, v4
	v_lshlrev_b64 v[4:5], 13, v[4:5]
	v_lshl_add_u64 v[4:5], s[34:35], 0, v[4:5]
	v_lshl_add_u64 v[4:5], v[4:5], 0, v[0:1]
	global_load_dwordx4 v[96:99], v[4:5], off offset:3072
	v_mad_u64_u32 v[134:135], s[36:37], v3, s24, v[2:3]
	v_add_u32_e32 v3, 0x400, v34
	v_ashrrev_i32_e32 v3, 6, v3
	v_add_u32_e32 v4, s3, v3
	v_ashrrev_i32_e32 v5, 31, v4
	v_lshlrev_b64 v[4:5], 13, v[4:5]
	v_lshl_add_u64 v[4:5], s[34:35], 0, v[4:5]
	v_lshl_add_u64 v[4:5], v[4:5], 0, v[0:1]
	global_load_dwordx4 v[100:103], v[4:5], off offset:3072
	v_mad_u64_u32 v[136:137], s[36:37], v3, s24, v[2:3]
	v_add_u32_e32 v3, 0x600, v34
	v_ashrrev_i32_e32 v3, 6, v3
	v_add_u32_e32 v4, s3, v3
	v_ashrrev_i32_e32 v5, 31, v4
	v_lshlrev_b64 v[4:5], 13, v[4:5]
	v_lshl_add_u64 v[4:5], s[34:35], 0, v[4:5]
	v_lshl_add_u64 v[4:5], v[4:5], 0, v[0:1]
	global_load_dwordx4 v[104:107], v[4:5], off offset:3072
	v_mad_u64_u32 v[138:139], s[36:37], v3, s24, v[2:3]
	v_add_u32_e32 v3, 0x800, v34
	v_ashrrev_i32_e32 v3, 6, v3
	v_add_u32_e32 v4, s3, v3
	v_ashrrev_i32_e32 v5, 31, v4
	v_lshlrev_b64 v[4:5], 13, v[4:5]
	v_lshl_add_u64 v[4:5], s[34:35], 0, v[4:5]
	v_lshl_add_u64 v[4:5], v[4:5], 0, v[0:1]
	global_load_dwordx4 v[108:111], v[4:5], off offset:3072
	v_mad_u64_u32 v[140:141], s[36:37], v3, s24, v[2:3]
	v_add_u32_e32 v3, 0xa00, v34
	v_ashrrev_i32_e32 v3, 6, v3
	v_add_u32_e32 v4, s3, v3
	v_ashrrev_i32_e32 v5, 31, v4
	v_lshlrev_b64 v[4:5], 13, v[4:5]
	v_lshl_add_u64 v[4:5], s[34:35], 0, v[4:5]
	v_lshl_add_u64 v[4:5], v[4:5], 0, v[0:1]
	global_load_dwordx4 v[112:115], v[4:5], off offset:3072
	v_mad_u64_u32 v[142:143], s[36:37], v3, s24, v[2:3]
	v_add_u32_e32 v3, 0xc00, v34
	v_ashrrev_i32_e32 v3, 6, v3
	v_add_u32_e32 v4, s3, v3
	v_ashrrev_i32_e32 v5, 31, v4
	v_lshlrev_b64 v[4:5], 13, v[4:5]
	v_lshl_add_u64 v[4:5], s[34:35], 0, v[4:5]
	v_lshl_add_u64 v[4:5], v[4:5], 0, v[0:1]
	global_load_dwordx4 v[116:119], v[4:5], off offset:3072
	v_mad_u64_u32 v[144:145], s[36:37], v3, s24, v[2:3]
	v_add_u32_e32 v3, 0xe00, v34
	v_ashrrev_i32_e32 v3, 6, v3
	v_add_u32_e32 v4, s3, v3
	v_ashrrev_i32_e32 v5, 31, v4
	v_lshlrev_b64 v[4:5], 13, v[4:5]
	v_lshl_add_u64 v[4:5], s[34:35], 0, v[4:5]
	v_lshl_add_u64 v[4:5], v[4:5], 0, v[0:1]
	global_load_dwordx4 v[120:123], v[4:5], off offset:3072
	v_mad_u64_u32 v[146:147], s[36:37], v3, s24, v[2:3]
	v_bfe_u32 v0, v34, 4, 2
	s_waitcnt vmcnt(7)
	ds_write_b128 v132, v[92:95] offset:33792
	s_waitcnt vmcnt(6)
	ds_write_b128 v134, v[96:99] offset:33792
	s_waitcnt vmcnt(5)
	ds_write_b128 v136, v[100:103] offset:33792
	s_waitcnt vmcnt(4)
	ds_write_b128 v138, v[104:107] offset:33792
	s_waitcnt vmcnt(3)
	ds_write_b128 v140, v[108:111] offset:33792
	s_waitcnt vmcnt(2)
	ds_write_b128 v142, v[112:115] offset:33792
	s_waitcnt vmcnt(1)
	ds_write_b128 v144, v[116:119] offset:33792
	s_waitcnt vmcnt(0)
	ds_write_b128 v146, v[120:123] offset:33792
	v_bfe_u32 v2, v34, 2, 2
	v_ashrrev_i32_e32 v34, 2, v34
	v_and_b32_e32 v34, 0xffffffe0, v34
	v_lshl_add_u32 v34, s1, 7, v34
	v_or_b32_e32 v34, s2, v34
	v_ashrrev_i32_e32 v35, 31, v34
	v_readlane_b32 s2, v252, 57
	v_lshl_or_b32 v36, v0, 3, v2
	v_lshlrev_b64 v[34:35], 15, v[34:35]
	v_readlane_b32 s3, v252, 58
	v_mul_u32_u24_e32 v2, 0x210, v36
	v_lshlrev_b32_e32 v0, 4, v0
	v_lshl_add_u64 v[34:35], s[2:3], 0, v[34:35]
	v_add3_u32 v4, v38, v41, v2
	v_lshl_add_u64 v[38:39], v[34:35], 0, v[0:1]
	v_mul_u32_u24_e32 v0, 0x410, v36
	v_add3_u32 v41, v37, v41, v0
	s_waitcnt lgkmcnt(0)
	s_barrier
; #define MFMA(X, Y, C) __builtin_amdgcn_mfma_f32_16x16x32_bf16((X), (Y), (C), 0, 0, 0)
; __device__ void ret_m1(const Params& p, LAS unsigned char* lds, int b, int c) {
;     ...
;     {
;         const int h = wid >> 1, vh = wid & 1;
;         bf16x8 X[4][2];
; #pragma unroll
;         for (int kt = 0; kt < 4; ++kt)
; #pragma unroll
;             for (int kk = 0; kk < 2; ++kk) X[kt][kk] = frag_tr(Kt, 264, kk * 32, h * 64 + kt * 16, fr, fq);
;         float* out = dS + ((size_t)((b * 4 + h) * NCH + c)) * 8192;
; #pragma unroll
;         for (int vt = 0; vt < 4; ++vt) {
;             bf16x8 Y[2];
; #pragma unroll
;             for (int kk = 0; kk < 2; ++kk) Y[kk] = frag_tr(Vt, 520, kk * 32, h * 128 + vh * 64 + vt * 16, fr, fq);
; #pragma unroll
;             for (int kt = 0; kt < 4; ++kt) {
;                 f32x4 a = {0.f, 0.f, 0.f, 0.f};
;                 a = MFMA(X[kt][0], Y[0], a); a = MFMA(X[kt][1], Y[1], a);
;                 *(f32x4*)(out + (vh * 64 + vt * 16 + fr) * 64 + kt * 16 + 4 * fq) = a;
;             }
;         }
;     }
;     __syncthreads();
; }
; __device__ void phase_m1(const Params& p, LAS unsigned char* lds, int l) {
;     for (int rr = 0; rr < 1 + ((REP_ITEM >> 0) & 1); ++rr) { if (IT_EN(0)) for (int it = blockIdx.x; it < 256; it += gridDim.x) ret_m1(p, lds, it >> 5, it & 31); }
	ds_read_b64_tr_b16 v[28:29], v4 offset:2112
	ds_read_b64_tr_b16 v[26:27], v4
	ds_read_b64_tr_b16 v[18:19], v4 offset:32
	ds_read_b64_tr_b16 v[30:31], v4 offset:16896
	ds_read_b64_tr_b16 v[32:33], v4 offset:19008
	ds_read_b64_tr_b16 v[20:21], v4 offset:2144
	ds_read_b64_tr_b16 v[22:23], v4 offset:16928
	ds_read_b64_tr_b16 v[24:25], v4 offset:19040
	ds_read_b64_tr_b16 v[10:11], v4 offset:64
	ds_read_b64_tr_b16 v[12:13], v4 offset:2176
	ds_read_b64_tr_b16 v[14:15], v4 offset:16960
	ds_read_b64_tr_b16 v[16:17], v4 offset:19072
	ds_read_b64_tr_b16 v[6:7], v4 offset:96
	ds_read_b64_tr_b16 v[8:9], v4 offset:2208
	ds_read_b64_tr_b16 v[2:3], v4 offset:16992
	ds_read_b64_tr_b16 v[4:5], v4 offset:19104
	ds_read_b64_tr_b16 v[34:35], v41 offset:33792
	ds_read_b64_tr_b16 v[36:37], v41 offset:37952
	v_add_u32_e32 v54, 0x8200, v41
	ds_read_b64_tr_b16 v[44:45], v54 offset:33792
	ds_read_b64_tr_b16 v[46:47], v54 offset:37952
	s_waitcnt lgkmcnt(2)
	v_mfma_f32_16x16x32_bf16 v[48:51], v[26:29], v[34:37], 0
	v_lshlrev_b32_e32 v0, 8, v40
	v_lshl_or_b32 v0, v42, 14, v0
	v_lshl_add_u64 v[38:39], v[38:39], 0, v[0:1]
	s_waitcnt lgkmcnt(0)
	v_mfma_f32_16x16x32_bf16 v[48:51], v[30:33], v[44:47], v[48:51]
	s_movk_i32 s1, 0x3000
	s_nop 6
	global_store_dwordx4 v[38:39], v[48:51], off
	s_nop 1
	v_mfma_f32_16x16x32_bf16 v[48:51], v[18:21], v[34:37], 0
	v_mfma_f32_16x16x32_bf16 v[48:51], v[22:25], v[44:47], v[48:51]
	s_nop 7
	global_store_dwordx4 v[38:39], v[48:51], off offset:64
	s_nop 1
	v_mfma_f32_16x16x32_bf16 v[48:51], v[10:13], v[34:37], 0
	v_mfma_f32_16x16x32_bf16 v[34:37], v[6:9], v[34:37], 0
	v_mfma_f32_16x16x32_bf16 v[48:51], v[14:17], v[44:47], v[48:51]
	v_mfma_f32_16x16x32_bf16 v[34:37], v[2:5], v[44:47], v[34:37]
	s_nop 6
	global_store_dwordx4 v[38:39], v[48:51], off offset:128
	global_store_dwordx4 v[38:39], v[34:37], off offset:192
	ds_read_b64_tr_b16 v[34:35], v41 offset:33824
	ds_read_b64_tr_b16 v[36:37], v41 offset:37984
	ds_read_b64_tr_b16 v[42:43], v54 offset:33824
	ds_read_b64_tr_b16 v[44:45], v54 offset:37984
	s_waitcnt lgkmcnt(2)
	v_mfma_f32_16x16x32_bf16 v[46:49], v[26:29], v[34:37], 0
	v_add_co_u32_e32 v50, vcc, s93, v38
	s_waitcnt lgkmcnt(0)
	v_mfma_f32_16x16x32_bf16 v[46:49], v[30:33], v[42:45], v[46:49]
	v_addc_co_u32_e32 v51, vcc, 0, v39, vcc
	v_add_co_u32_e32 v52, vcc, s87, v38
	s_nop 1
	v_addc_co_u32_e32 v53, vcc, 0, v39, vcc
	s_nop 2
	global_store_dwordx4 v[52:53], v[46:49], off offset:-4096
	s_nop 1
	v_mfma_f32_16x16x32_bf16 v[46:49], v[18:21], v[34:37], 0
	v_mfma_f32_16x16x32_bf16 v[46:49], v[22:25], v[42:45], v[46:49]
	s_nop 7
	global_store_dwordx4 v[50:51], v[46:49], off offset:64
	s_nop 1
	v_mfma_f32_16x16x32_bf16 v[46:49], v[10:13], v[34:37], 0
	v_mfma_f32_16x16x32_bf16 v[34:37], v[6:9], v[34:37], 0
	v_mfma_f32_16x16x32_bf16 v[46:49], v[14:17], v[42:45], v[46:49]
	v_mfma_f32_16x16x32_bf16 v[34:37], v[2:5], v[42:45], v[34:37]
	s_nop 6
	global_store_dwordx4 v[50:51], v[46:49], off offset:128
	global_store_dwordx4 v[50:51], v[34:37], off offset:192
	ds_read_b64_tr_b16 v[34:35], v41 offset:33856
	ds_read_b64_tr_b16 v[36:37], v41 offset:38016
	ds_read_b64_tr_b16 v[42:43], v54 offset:33856
	ds_read_b64_tr_b16 v[44:45], v54 offset:38016
	s_waitcnt lgkmcnt(2)
	v_mfma_f32_16x16x32_bf16 v[46:49], v[26:29], v[34:37], 0
	s_waitcnt lgkmcnt(0)
	v_mfma_f32_16x16x32_bf16 v[46:49], v[30:33], v[42:45], v[46:49]
	s_nop 7
	global_store_dwordx4 v[52:53], v[46:49], off
	s_nop 1
	v_mfma_f32_16x16x32_bf16 v[46:49], v[18:21], v[34:37], 0
	v_mfma_f32_16x16x32_bf16 v[46:49], v[22:25], v[42:45], v[46:49]
	s_nop 7
	global_store_dwordx4 v[52:53], v[46:49], off offset:64
	s_nop 1
	v_mfma_f32_16x16x32_bf16 v[46:49], v[10:13], v[34:37], 0
	v_mfma_f32_16x16x32_bf16 v[34:37], v[6:9], v[34:37], 0
	v_mfma_f32_16x16x32_bf16 v[46:49], v[14:17], v[42:45], v[46:49]
	v_mfma_f32_16x16x32_bf16 v[34:37], v[2:5], v[42:45], v[34:37]
	s_nop 6
	global_store_dwordx4 v[52:53], v[46:49], off offset:128
	global_store_dwordx4 v[52:53], v[34:37], off offset:192
	ds_read_b64_tr_b16 v[42:43], v41 offset:33888
	ds_read_b64_tr_b16 v[44:45], v41 offset:38048
	ds_read_b64_tr_b16 v[34:35], v54 offset:33888
	ds_read_b64_tr_b16 v[36:37], v54 offset:38048
	s_waitcnt lgkmcnt(2)
	v_mfma_f32_16x16x32_bf16 v[26:29], v[26:29], v[42:45], 0
	v_mfma_f32_16x16x32_bf16 v[18:21], v[18:21], v[42:45], 0
	v_mfma_f32_16x16x32_bf16 v[10:13], v[10:13], v[42:45], 0
	v_mfma_f32_16x16x32_bf16 v[6:9], v[6:9], v[42:45], 0
	s_waitcnt lgkmcnt(0)
	v_mfma_f32_16x16x32_bf16 v[28:31], v[30:33], v[34:37], v[26:29]
	v_mfma_f32_16x16x32_bf16 v[18:21], v[22:25], v[34:37], v[18:21]
	s_nop 1
	v_add_co_u32_e32 v26, vcc, s1, v38
	v_mfma_f32_16x16x32_bf16 v[10:13], v[14:17], v[34:37], v[10:13]
	s_nop 0
	v_addc_co_u32_e32 v27, vcc, 0, v39, vcc
	s_nop 0
	global_store_dwordx4 v[26:27], v[28:31], off
	v_mfma_f32_16x16x32_bf16 v[2:5], v[2:5], v[34:37], v[6:9]
	global_store_dwordx4 v[26:27], v[18:21], off offset:64
	s_nop 1
	global_store_dwordx4 v[26:27], v[10:13], off offset:128
	s_nop 3
	global_store_dwordx4 v[26:27], v[2:5], off offset:192
	s_barrier
	s_load_dword s1, s[40:41], 0x10
	s_waitcnt lgkmcnt(0)
	s_lshr_b32 s1, s1, 16
	s_cmp_lg_u32 s1, 0
	s_cselect_b64 s[2:3], -1, 0
	s_cmp_lg_u64 s[2:3], 0
	s_addc_u32 s0, s0, s94
	s_cmpk_lt_i32 s0, 0x100
	s_cbranch_scc1 .LBB0_384
	v_readlane_b32 s0, v253, 46
	s_mov_b32 s24, s0
	v_readlane_b32 s1, v253, 47
	s_branch .LBB0_387

; __device__ void sample_item(const Params& p, LAS unsigned char* lds, int l, int s, int g) {
;     ...
;     if (tid < 256) {
;         const int j = tid & 63, hl = tid >> 6, h = 4 * g + hl, ch = h * 64 + j;
;         const float* wr = p.in[12] + (size_t)(l * 8 + h) * 4096; const float* wi = p.in[14] + (size_t)(l * 8 + h) * 4096;
;         float r = 0.f, ig = 0.f;
;         for (int i = 0; i < 64; ++i) { const float xv = sxc[hl * 64 + i]; r += xv * wr[i * 64 + j]; ig += xv * wi[i * 64 + j]; }
.LBB0_481:
	s_or_b64 exec, exec, s[0:1]
	s_waitcnt lgkmcnt(0)
	s_barrier
	s_and_saveexec_b64 s[0:1], s[40:41]
	s_cbranch_execz .LBB0_446
	v_add_u32_e32 v14, s24, v44
	v_readlane_b32 s2, v254, 47
	v_readlane_b32 s52, v254, 0
	v_readlane_b32 s60, v254, 8
	v_add_u32_e32 v2, s2, v14
	v_ashrrev_i32_e32 v3, 31, v2
	v_lshlrev_b64 v[2:3], 14, v[2:3]
	v_readlane_b32 s61, v254, 9
	v_and_b32_e32 v0, 0x3fffffc0, v114
	v_mov_b32_e32 v39, v1
	v_lshl_add_u64 v[8:9], s[60:61], 0, v[2:3]
	v_readlane_b32 s64, v254, 12
	v_readlane_b32 s65, v254, 13
	v_lshl_add_u32 v15, v0, 2, 0
	v_lshl_add_u64 v[12:13], v[8:9], 0, v[38:39]
	v_lshl_add_u64 v[6:7], s[64:65], 0, v[2:3]
	v_readlane_b32 s2, v254, 52
	v_readlane_b32 s62, v254, 10
	v_readlane_b32 s63, v254, 11
	v_readlane_b32 s53, v254, 1
	v_readlane_b32 s54, v254, 2
	v_readlane_b32 s55, v254, 3
	v_readlane_b32 s56, v254, 4
	v_readlane_b32 s57, v254, 5
	v_readlane_b32 s58, v254, 6
	v_readlane_b32 s59, v254, 7
	v_readlane_b32 s66, v254, 14
	v_readlane_b32 s67, v254, 15
	s_lshl_b64 s[36:37], s[50:51], 11
	v_readlane_b32 s3, v254, 53
	v_lshl_add_u64 v[10:11], v[6:7], 0, v[38:39]
	v_mov_b32_e32 v222, 0x1000
	v_mov_b32_e32 v223, 0
	v_mov_b32_e32 v16, 0
	v_mov_b32_e32 v17, 0
	ds_read_b128 v[204:207], v15 offset:9216
	ds_read_b128 v[208:211], v15 offset:9232
	ds_read_b128 v[212:215], v15 offset:9248
	ds_read_b128 v[216:219], v15 offset:9264
	global_load_dword v172, v[12:13], off
	global_load_dword v173, v[10:11], off
	global_load_dword v174, v[12:13], off offset:256
	global_load_dword v175, v[10:11], off offset:256
	global_load_dword v176, v[12:13], off offset:512
	global_load_dword v177, v[10:11], off offset:512
	global_load_dword v178, v[12:13], off offset:768
	global_load_dword v179, v[10:11], off offset:768
	global_load_dword v180, v[12:13], off offset:1024
	global_load_dword v181, v[10:11], off offset:1024
	global_load_dword v182, v[12:13], off offset:1280
	global_load_dword v183, v[10:11], off offset:1280
	global_load_dword v184, v[12:13], off offset:1536
	global_load_dword v185, v[10:11], off offset:1536
	global_load_dword v186, v[12:13], off offset:1792
	global_load_dword v187, v[10:11], off offset:1792
	global_load_dword v188, v[12:13], off offset:2048
	global_load_dword v189, v[10:11], off offset:2048
	global_load_dword v190, v[12:13], off offset:2304
	global_load_dword v191, v[10:11], off offset:2304
	global_load_dword v192, v[12:13], off offset:2560
	global_load_dword v193, v[10:11], off offset:2560
	global_load_dword v194, v[12:13], off offset:2816
	global_load_dword v195, v[10:11], off offset:2816
	global_load_dword v196, v[12:13], off offset:3072
	global_load_dword v197, v[10:11], off offset:3072
	global_load_dword v198, v[12:13], off offset:3328
	global_load_dword v199, v[10:11], off offset:3328
	global_load_dword v200, v[12:13], off offset:3584
	global_load_dword v201, v[10:11], off offset:3584
	global_load_dword v202, v[12:13], off offset:3840
	global_load_dword v203, v[10:11], off offset:3840
	v_lshl_add_u64 v[12:13], v[12:13], 0, v[222:223]
	v_lshl_add_u64 v[10:11], v[10:11], 0, v[222:223]
	s_waitcnt lgkmcnt(0)
	s_waitcnt vmcnt(30)
	v_fmac_f32_e32 v16, v204, v172
	v_fmac_f32_e32 v17, v204, v173
	s_waitcnt vmcnt(28)
	v_fmac_f32_e32 v16, v205, v174
	v_fmac_f32_e32 v17, v205, v175
	s_waitcnt vmcnt(26)
	v_fmac_f32_e32 v16, v206, v176
	v_fmac_f32_e32 v17, v206, v177
	s_waitcnt vmcnt(24)
	v_fmac_f32_e32 v16, v207, v178
	v_fmac_f32_e32 v17, v207, v179
	s_waitcnt vmcnt(22)
	v_fmac_f32_e32 v16, v208, v180
	v_fmac_f32_e32 v17, v208, v181
	s_waitcnt vmcnt(20)
	v_fmac_f32_e32 v16, v209, v182
	v_fmac_f32_e32 v17, v209, v183
	s_waitcnt vmcnt(18)
	v_fmac_f32_e32 v16, v210, v184
	v_fmac_f32_e32 v17, v210, v185
	s_waitcnt vmcnt(16)
	v_fmac_f32_e32 v16, v211, v186
	v_fmac_f32_e32 v17, v211, v187
	s_waitcnt vmcnt(14)
	v_fmac_f32_e32 v16, v212, v188
	v_fmac_f32_e32 v17, v212, v189
	s_waitcnt vmcnt(12)
	v_fmac_f32_e32 v16, v213, v190
	v_fmac_f32_e32 v17, v213, v191
	s_waitcnt vmcnt(10)
	v_fmac_f32_e32 v16, v214, v192
	v_fmac_f32_e32 v17, v214, v193
	s_waitcnt vmcnt(8)
	v_fmac_f32_e32 v16, v215, v194
	v_fmac_f32_e32 v17, v215, v195
	s_waitcnt vmcnt(6)
	v_fmac_f32_e32 v16, v216, v196
	v_fmac_f32_e32 v17, v216, v197
	s_waitcnt vmcnt(4)
	v_fmac_f32_e32 v16, v217, v198
	v_fmac_f32_e32 v17, v217, v199
	s_waitcnt vmcnt(2)
	v_fmac_f32_e32 v16, v218, v200
	v_fmac_f32_e32 v17, v218, v201
	s_waitcnt vmcnt(0)
	v_fmac_f32_e32 v16, v219, v202
	v_fmac_f32_e32 v17, v219, v203
	ds_read_b128 v[204:207], v15 offset:9280
	ds_read_b128 v[208:211], v15 offset:9296
	ds_read_b128 v[212:215], v15 offset:9312
	ds_read_b128 v[216:219], v15 offset:9328
	global_load_dword v172, v[12:13], off
	global_load_dword v173, v[10:11], off
	global_load_dword v174, v[12:13], off offset:256
	global_load_dword v175, v[10:11], off offset:256
	global_load_dword v176, v[12:13], off offset:512
	global_load_dword v177, v[10:11], off offset:512
	global_load_dword v178, v[12:13], off offset:768
	global_load_dword v179, v[10:11], off offset:768
	global_load_dword v180, v[12:13], off offset:1024
	global_load_dword v181, v[10:11], off offset:1024
	global_load_dword v182, v[12:13], off offset:1280
	global_load_dword v183, v[10:11], off offset:1280
	global_load_dword v184, v[12:13], off offset:1536
	global_load_dword v185, v[10:11], off offset:1536
	global_load_dword v186, v[12:13], off offset:1792
	global_load_dword v187, v[10:11], off offset:1792
	global_load_dword v188, v[12:13], off offset:2048
	global_load_dword v189, v[10:11], off offset:2048
	global_load_dword v190, v[12:13], off offset:2304
	global_load_dword v191, v[10:11], off offset:2304
	global_load_dword v192, v[12:13], off offset:2560
	global_load_dword v193, v[10:11], off offset:2560
	global_load_dword v194, v[12:13], off offset:2816
	global_load_dword v195, v[10:11], off offset:2816
	global_load_dword v196, v[12:13], off offset:3072
	global_load_dword v197, v[10:11], off offset:3072
	global_load_dword v198, v[12:13], off offset:3328
	global_load_dword v199, v[10:11], off offset:3328
	global_load_dword v200, v[12:13], off offset:3584
	global_load_dword v201, v[10:11], off offset:3584
	global_load_dword v202, v[12:13], off offset:3840
	global_load_dword v203, v[10:11], off offset:3840
	v_lshl_add_u64 v[12:13], v[12:13], 0, v[222:223]
	v_lshl_add_u64 v[10:11], v[10:11], 0, v[222:223]
	s_waitcnt lgkmcnt(0)
; __device__ void sample_item(const Params& p, LAS unsigned char* lds, int l, int s, int g) {
;     ...
;         for (int i = 0; i < 64; ++i) { const float xv = sxc[hl * 64 + i]; r += xv * wr[i * 64 + j]; ig += xv * wi[i * 64 + j]; }
	s_waitcnt vmcnt(30)
	v_fmac_f32_e32 v16, v204, v172
	v_fmac_f32_e32 v17, v204, v173
	s_waitcnt vmcnt(28)
	v_fmac_f32_e32 v16, v205, v174
	v_fmac_f32_e32 v17, v205, v175
	s_waitcnt vmcnt(26)
	v_fmac_f32_e32 v16, v206, v176
	v_fmac_f32_e32 v17, v206, v177
	s_waitcnt vmcnt(24)
	v_fmac_f32_e32 v16, v207, v178
	v_fmac_f32_e32 v17, v207, v179
	s_waitcnt vmcnt(22)
	v_fmac_f32_e32 v16, v208, v180
	v_fmac_f32_e32 v17, v208, v181
	s_waitcnt vmcnt(20)
	v_fmac_f32_e32 v16, v209, v182
	v_fmac_f32_e32 v17, v209, v183
	s_waitcnt vmcnt(18)
	v_fmac_f32_e32 v16, v210, v184
	v_fmac_f32_e32 v17, v210, v185
	s_waitcnt vmcnt(16)
	v_fmac_f32_e32 v16, v211, v186
	v_fmac_f32_e32 v17, v211, v187
	s_waitcnt vmcnt(14)
	v_fmac_f32_e32 v16, v212, v188
	v_fmac_f32_e32 v17, v212, v189
	s_waitcnt vmcnt(12)
	v_fmac_f32_e32 v16, v213, v190
	v_fmac_f32_e32 v17, v213, v191
	s_waitcnt vmcnt(10)
	v_fmac_f32_e32 v16, v214, v192
	v_fmac_f32_e32 v17, v214, v193
	s_waitcnt vmcnt(8)
	v_fmac_f32_e32 v16, v215, v194
	v_fmac_f32_e32 v17, v215, v195
	s_waitcnt vmcnt(6)
	v_fmac_f32_e32 v16, v216, v196
	v_fmac_f32_e32 v17, v216, v197
	s_waitcnt vmcnt(4)
	v_fmac_f32_e32 v16, v217, v198
	v_fmac_f32_e32 v17, v217, v199
	s_waitcnt vmcnt(2)
	v_fmac_f32_e32 v16, v218, v200
	v_fmac_f32_e32 v17, v218, v201
	s_waitcnt vmcnt(0)
	v_fmac_f32_e32 v16, v219, v202
	v_fmac_f32_e32 v17, v219, v203
	ds_read_b128 v[204:207], v15 offset:9344
	ds_read_b128 v[208:211], v15 offset:9360
	ds_read_b128 v[212:215], v15 offset:9376
	ds_read_b128 v[216:219], v15 offset:9392
	global_load_dword v172, v[12:13], off
	global_load_dword v173, v[10:11], off
	global_load_dword v174, v[12:13], off offset:256
	global_load_dword v175, v[10:11], off offset:256
	global_load_dword v176, v[12:13], off offset:512
	global_load_dword v177, v[10:11], off offset:512
	global_load_dword v178, v[12:13], off offset:768
	global_load_dword v179, v[10:11], off offset:768
	global_load_dword v180, v[12:13], off offset:1024
	global_load_dword v181, v[10:11], off offset:1024
	global_load_dword v182, v[12:13], off offset:1280
	global_load_dword v183, v[10:11], off offset:1280
	global_load_dword v184, v[12:13], off offset:1536
	global_load_dword v185, v[10:11], off offset:1536
	global_load_dword v186, v[12:13], off offset:1792
	global_load_dword v187, v[10:11], off offset:1792
	global_load_dword v188, v[12:13], off offset:2048
	global_load_dword v189, v[10:11], off offset:2048
	global_load_dword v190, v[12:13], off offset:2304
	global_load_dword v191, v[10:11], off offset:2304
	global_load_dword v192, v[12:13], off offset:2560
	global_load_dword v193, v[10:11], off offset:2560
	global_load_dword v194, v[12:13], off offset:2816
	global_load_dword v195, v[10:11], off offset:2816
	global_load_dword v196, v[12:13], off offset:3072
	global_load_dword v197, v[10:11], off offset:3072
	global_load_dword v198, v[12:13], off offset:3328
	global_load_dword v199, v[10:11], off offset:3328
	global_load_dword v200, v[12:13], off offset:3584
	global_load_dword v201, v[10:11], off offset:3584
	global_load_dword v202, v[12:13], off offset:3840
	global_load_dword v203, v[10:11], off offset:3840
	v_lshl_add_u64 v[12:13], v[12:13], 0, v[222:223]
	v_lshl_add_u64 v[10:11], v[10:11], 0, v[222:223]
	s_waitcnt lgkmcnt(0)
	s_waitcnt vmcnt(30)
	v_fmac_f32_e32 v16, v204, v172
	v_fmac_f32_e32 v17, v204, v173
	s_waitcnt vmcnt(28)
	v_fmac_f32_e32 v16, v205, v174
	v_fmac_f32_e32 v17, v205, v175
	s_waitcnt vmcnt(26)
	v_fmac_f32_e32 v16, v206, v176
	v_fmac_f32_e32 v17, v206, v177
	s_waitcnt vmcnt(24)
	v_fmac_f32_e32 v16, v207, v178
	v_fmac_f32_e32 v17, v207, v179
	s_waitcnt vmcnt(22)
	v_fmac_f32_e32 v16, v208, v180
	v_fmac_f32_e32 v17, v208, v181
	s_waitcnt vmcnt(20)
	v_fmac_f32_e32 v16, v209, v182
	v_fmac_f32_e32 v17, v209, v183
	s_waitcnt vmcnt(18)
	v_fmac_f32_e32 v16, v210, v184
	v_fmac_f32_e32 v17, v210, v185
	s_waitcnt vmcnt(16)
	v_fmac_f32_e32 v16, v211, v186
	v_fmac_f32_e32 v17, v211, v187
	s_waitcnt vmcnt(14)
	v_fmac_f32_e32 v16, v212, v188
	v_fmac_f32_e32 v17, v212, v189
	s_waitcnt vmcnt(12)
	v_fmac_f32_e32 v16, v213, v190
	v_fmac_f32_e32 v17, v213, v191
	s_waitcnt vmcnt(10)
	v_fmac_f32_e32 v16, v214, v192
	v_fmac_f32_e32 v17, v214, v193
	s_waitcnt vmcnt(8)
	v_fmac_f32_e32 v16, v215, v194
	v_fmac_f32_e32 v17, v215, v195
	s_waitcnt vmcnt(6)
	v_fmac_f32_e32 v16, v216, v196
	v_fmac_f32_e32 v17, v216, v197
	s_waitcnt vmcnt(4)
	v_fmac_f32_e32 v16, v217, v198
	v_fmac_f32_e32 v17, v217, v199
	s_waitcnt vmcnt(2)
	v_fmac_f32_e32 v16, v218, v200
	v_fmac_f32_e32 v17, v218, v201
	s_waitcnt vmcnt(0)
	v_fmac_f32_e32 v16, v219, v202
	v_fmac_f32_e32 v17, v219, v203
	ds_read_b128 v[204:207], v15 offset:9408
	ds_read_b128 v[208:211], v15 offset:9424
	ds_read_b128 v[212:215], v15 offset:9440
	ds_read_b128 v[216:219], v15 offset:9456
	global_load_dword v172, v[12:13], off
	global_load_dword v173, v[10:11], off
	global_load_dword v174, v[12:13], off offset:256
	global_load_dword v175, v[10:11], off offset:256
	global_load_dword v176, v[12:13], off offset:512
	global_load_dword v177, v[10:11], off offset:512
	global_load_dword v178, v[12:13], off offset:768
	global_load_dword v179, v[10:11], off offset:768
	global_load_dword v180, v[12:13], off offset:1024
	global_load_dword v181, v[10:11], off offset:1024
	global_load_dword v182, v[12:13], off offset:1280
	global_load_dword v183, v[10:11], off offset:1280
	global_load_dword v184, v[12:13], off offset:1536
	global_load_dword v185, v[10:11], off offset:1536
	global_load_dword v186, v[12:13], off offset:1792
	global_load_dword v187, v[10:11], off offset:1792
	global_load_dword v188, v[12:13], off offset:2048
	global_load_dword v189, v[10:11], off offset:2048
	global_load_dword v190, v[12:13], off offset:2304
	global_load_dword v191, v[10:11], off offset:2304
	global_load_dword v192, v[12:13], off offset:2560
	global_load_dword v193, v[10:11], off offset:2560
	global_load_dword v194, v[12:13], off offset:2816
	global_load_dword v195, v[10:11], off offset:2816
	global_load_dword v196, v[12:13], off offset:3072
	global_load_dword v197, v[10:11], off offset:3072
	global_load_dword v198, v[12:13], off offset:3328
	global_load_dword v199, v[10:11], off offset:3328
	global_load_dword v200, v[12:13], off offset:3584
	global_load_dword v201, v[10:11], off offset:3584
	global_load_dword v202, v[12:13], off offset:3840
	global_load_dword v203, v[10:11], off offset:3840
	s_waitcnt lgkmcnt(0)
; __device__ __forceinline__ float fexp_(float x) { return __builtin_amdgcn_exp2f(x * 1.44269504089f); }
; __device__ __forceinline__ float sigmoidf_(float x) { return __builtin_amdgcn_rcpf(1.f + fexp_(-x)); }
; __device__ void sample_item(const Params& p, LAS unsigned char* lds, int l, int s, int g) {
;     ...
;         for (int i = 0; i < 64; ++i) { const float xv = sxc[hl * 64 + i]; r += xv * wr[i * 64 + j]; ig += xv * wi[i * 64 + j]; }
;         r = sigmoidf_(r + p.in[13][l * 512 + ch]); ig = sigmoidf_(ig + p.in[15][l * 512 + ch]);
;         const float sp = log1pf(fexp_(-p.in[16][l * 512 + ch]));
	s_waitcnt vmcnt(30)
	v_fmac_f32_e32 v16, v204, v172
	v_fmac_f32_e32 v17, v204, v173
	s_waitcnt vmcnt(28)
	v_fmac_f32_e32 v16, v205, v174
	v_fmac_f32_e32 v17, v205, v175
	s_waitcnt vmcnt(26)
	v_fmac_f32_e32 v16, v206, v176
	v_fmac_f32_e32 v17, v206, v177
	s_waitcnt vmcnt(24)
	v_fmac_f32_e32 v16, v207, v178
	v_fmac_f32_e32 v17, v207, v179
	s_waitcnt vmcnt(22)
	v_fmac_f32_e32 v16, v208, v180
	v_fmac_f32_e32 v17, v208, v181
	s_waitcnt vmcnt(20)
	v_fmac_f32_e32 v16, v209, v182
	v_fmac_f32_e32 v17, v209, v183
	s_waitcnt vmcnt(18)
	v_fmac_f32_e32 v16, v210, v184
	v_fmac_f32_e32 v17, v210, v185
	s_waitcnt vmcnt(16)
	v_fmac_f32_e32 v16, v211, v186
	v_fmac_f32_e32 v17, v211, v187
	s_waitcnt vmcnt(14)
	v_fmac_f32_e32 v16, v212, v188
	v_fmac_f32_e32 v17, v212, v189
	s_waitcnt vmcnt(12)
	v_fmac_f32_e32 v16, v213, v190
	v_fmac_f32_e32 v17, v213, v191
	s_waitcnt vmcnt(10)
	v_fmac_f32_e32 v16, v214, v192
	v_fmac_f32_e32 v17, v214, v193
	s_waitcnt vmcnt(8)
	v_fmac_f32_e32 v16, v215, v194
	v_fmac_f32_e32 v17, v215, v195
	s_waitcnt vmcnt(6)
	v_fmac_f32_e32 v16, v216, v196
	v_fmac_f32_e32 v17, v216, v197
	s_waitcnt vmcnt(4)
	v_fmac_f32_e32 v16, v217, v198
	v_fmac_f32_e32 v17, v217, v199
	s_waitcnt vmcnt(2)
	v_fmac_f32_e32 v16, v218, v200
	v_fmac_f32_e32 v17, v218, v201
	s_waitcnt vmcnt(0)
	v_fmac_f32_e32 v16, v219, v202
	v_fmac_f32_e32 v17, v219, v203
	v_lshl_or_b32 v2, v14, 6, v131
	v_add_u32_e32 v4, s2, v2
	v_ashrrev_i32_e32 v5, 31, v4
	v_lshlrev_b64 v[4:5], 2, v[4:5]
	v_mov_b32_e32 v3, v16
	v_mov_b32_e32 v0, v17
	v_lshl_add_u64 v[6:7], s[62:63], 0, v[4:5]
	global_load_dword v6, v[6:7], off
	s_mov_b32 s2, 0x3f2aaaab
	s_waitcnt vmcnt(0)
	v_add_f32_e32 v3, v3, v6
	v_lshl_add_u64 v[6:7], s[66:67], 0, v[4:5]
	v_readlane_b32 s52, v254, 16
	v_readlane_b32 s53, v254, 17
	global_load_dword v6, v[6:7], off
	v_mul_f32_e32 v3, 0xbfb8aa3b, v3
	v_lshl_add_u64 v[4:5], s[52:53], 0, v[4:5]
	global_load_dword v4, v[4:5], off
	v_exp_f32_e32 v3, v3
	v_readlane_b32 s54, v254, 18
	v_readlane_b32 s55, v254, 19
	v_readlane_b32 s56, v254, 20
	v_add_f32_e32 v3, 1.0, v3
	v_rcp_f32_e32 v3, v3
	v_readlane_b32 s57, v254, 21
	v_readlane_b32 s58, v254, 22
	v_readlane_b32 s59, v254, 23
	v_mul_f32_e32 v3, 0xc1000000, v3
	v_readlane_b32 s60, v254, 24
	v_readlane_b32 s61, v254, 25
	v_readlane_b32 s62, v254, 26
	v_readlane_b32 s63, v254, 27
	v_readlane_b32 s64, v254, 28
	v_readlane_b32 s65, v254, 29
	v_readlane_b32 s66, v254, 30
	v_readlane_b32 s67, v254, 31
	v_readlane_b32 s52, v251, 6
	v_readlane_b32 s66, v251, 20
	v_readlane_b32 s67, v251, 21
	v_readlane_b32 s53, v251, 7
	v_readlane_b32 s54, v251, 8
	v_readlane_b32 s55, v251, 9
	v_readlane_b32 s56, v251, 10
	v_readlane_b32 s57, v251, 11
	v_readlane_b32 s58, v251, 12
	v_readlane_b32 s59, v251, 13
	v_readlane_b32 s60, v251, 14
	v_readlane_b32 s61, v251, 15
	v_readlane_b32 s62, v251, 16
	v_readlane_b32 s63, v251, 17
	v_readlane_b32 s64, v251, 18
	v_readlane_b32 s65, v251, 19
	s_waitcnt vmcnt(1)
	v_add_f32_e32 v0, v0, v6
	v_mul_f32_e32 v0, 0xbfb8aa3b, v0
	v_exp_f32_e32 v0, v0
	s_waitcnt vmcnt(0)
; __device__ __forceinline__ float bf2f(bf16_t v) { return __uint_as_float(((unsigned)v) << 16); }
; __device__ __forceinline__ bf16_t f2bf(float f) { return (bf16_t)(pk2(f, 0.f) & 0xffffu); }
; __device__ __forceinline__ float fexp_(float x) { return __builtin_amdgcn_exp2f(x * 1.44269504089f); }
; __device__ __forceinline__ float geluf_(float x) { const float z = x * __builtin_fmaf(x * x, 0.1029432397f, 2.302208198f); const float r = __builtin_amdgcn_rcpf(1.f + __builtin_amdgcn_exp2f(z)); return __builtin_fmaf(-x, r, x); }
; __device__ void sample_item(const Params& p, LAS unsigned char* lds, int l, int s, int g) {
;     ...
;         const float sp = log1pf(fexp_(-p.in[16][l * 512 + ch]));
;         const float la = -8.f * r * sp, a = fexp_(la);
;         const float hn = a * p.in[3][(size_t)(l * NS + s) * 512 + ch] + __builtin_amdgcn_sqrtf(fmaxf(-expm1f(2.f * la), 0.f)) * ig * sxc[tid];
;         p.out[O_LHS + (size_t)(l * NS + s) * 512 + ch] = hn;
;         mix[t * DMIX + ch] = f2bf(hn * geluf_(bf2f(prow[PC_LG + ch])));
	v_mul_f32_e32 v4, 0xbfb8aa3b, v4
	v_exp_f32_e32 v18, v4
	v_add_f32_e32 v0, 1.0, v0
	v_rcp_f32_e32 v0, v0
	v_add_f32_e32 v6, 1.0, v18
	v_add_f32_e32 v4, -1.0, v6
	v_sub_f32_e32 v5, v4, v6
	v_add_f32_e32 v5, 1.0, v5
	v_sub_f32_e32 v4, v18, v4
	v_add_f32_e32 v7, v4, v5
	v_frexp_mant_f32_e32 v4, v6
	v_cmp_gt_f32_e32 vcc, s2, v4
	v_cvt_f64_f32_e32 v[4:5], v6
	v_frexp_exp_i32_f64_e32 v4, v[4:5]
	v_subbrev_co_u32_e32 v12, vcc, 0, v4, vcc
	v_sub_u32_e32 v4, 0, v12
	v_ldexp_f32 v5, v6, v4
	v_add_f32_e32 v6, -1.0, v5
	v_add_f32_e32 v8, 1.0, v5
	v_ldexp_f32 v4, v7, v4
	v_add_f32_e32 v7, 1.0, v6
	v_add_f32_e32 v9, -1.0, v8
	v_sub_f32_e32 v7, v5, v7
	v_sub_f32_e32 v5, v5, v9
	v_add_f32_e32 v7, v4, v7
	v_add_f32_e32 v4, v4, v5
	v_add_f32_e32 v13, v8, v4
	v_rcp_f32_e32 v15, v13
	v_sub_f32_e32 v5, v13, v8
	v_sub_f32_e32 v14, v4, v5
	v_add_f32_e32 v5, v6, v7
	v_mul_f32_e32 v17, v5, v15
	v_sub_f32_e32 v4, v5, v6
	v_mul_f32_e32 v6, v13, v17
	v_fma_f32 v8, v17, v13, -v6
	v_fmac_f32_e32 v8, v17, v14
	v_sub_f32_e32 v16, v7, v4
	v_add_f32_e32 v4, v6, v8
	v_sub_f32_e32 v7, v5, v4
	v_pk_add_f32 v[10:11], v[4:5], v[6:7] neg_lo:[0,1] neg_hi:[0,1]
	v_mov_b32_e32 v9, v4
	v_pk_add_f32 v[4:5], v[10:11], v[8:9] neg_lo:[0,1] neg_hi:[0,1]
	s_mov_b32 s2, 0x3f317218
	v_add_f32_e32 v5, v16, v5
	v_add_f32_e32 v4, v4, v5
	v_add_f32_e32 v5, v7, v4
	v_mul_f32_e32 v16, v15, v5
	v_mul_f32_e32 v6, v13, v16
	v_fma_f32 v8, v16, v13, -v6
	v_fmac_f32_e32 v8, v16, v14
	v_sub_f32_e32 v7, v7, v5
	v_add_f32_e32 v13, v4, v7
	v_add_f32_e32 v4, v6, v8
	v_sub_f32_e32 v7, v5, v4
	v_pk_add_f32 v[10:11], v[4:5], v[6:7] neg_lo:[0,1] neg_hi:[0,1]
	v_mov_b32_e32 v9, v4
	v_pk_add_f32 v[4:5], v[10:11], v[8:9] neg_lo:[0,1] neg_hi:[0,1]
	s_nop 0
	v_add_f32_e32 v5, v13, v5
	v_add_f32_e32 v4, v4, v5
	v_add_f32_e32 v5, v17, v16
	v_add_f32_e32 v4, v7, v4
	v_sub_f32_e32 v6, v5, v17
	v_mul_f32_e32 v4, v15, v4
	v_sub_f32_e32 v6, v16, v6
	v_add_f32_e32 v6, v6, v4
	v_add_f32_e32 v8, v5, v6
	v_mul_f32_e32 v9, v8, v8
	v_fmamk_f32 v4, v9, 0x3e9b6dac, v225
	v_fmaak_f32 v171, v9, v4, 0x3f2aaada
	v_cvt_f32_i32_e32 v4, v12
	v_sub_f32_e32 v5, v8, v5
	v_sub_f32_e32 v5, v6, v5
	v_ldexp_f32 v10, v5, 1
	v_mul_f32_e32 v5, v8, v9
	v_ldexp_f32 v7, v8, 1
	v_pk_mul_f32 v[8:9], v[4:5], v[170:171]
	s_nop 0
	v_fma_f32 v6, v4, s2, -v8
	v_fmac_f32_e32 v6, 0xb102e308, v4
	v_pk_add_f32 v[4:5], v[8:9], v[6:7]
	s_mov_b32 s2, 0x7f800000
	v_sub_f32_e32 v7, v5, v7
	v_sub_f32_e32 v7, v9, v7
	v_add_f32_e32 v11, v10, v7
	v_mov_b32_e32 v10, v8
	v_pk_add_f32 v[8:9], v[4:5], v[8:9] neg_lo:[0,1] neg_hi:[0,1]
	v_pk_add_f32 v[12:13], v[4:5], v[10:11]
	v_mov_b32_e32 v7, v4
	v_mov_b32_e32 v9, v13
	v_pk_add_f32 v[14:15], v[6:7], v[8:9] neg_lo:[0,1] neg_hi:[0,1]
	v_pk_add_f32 v[6:7], v[6:7], v[8:9]
	v_mov_b32_e32 v10, v11
	v_pk_add_f32 v[8:9], v[6:7], v[4:5] op_sel:[1,0] op_sel_hi:[0,1] neg_lo:[0,1] neg_hi:[0,1]
	v_pk_add_f32 v[16:17], v[12:13], v[8:9] op_sel_hi:[1,0] neg_lo:[0,1] neg_hi:[0,1]
	v_mov_b32_e32 v12, v13
	v_mov_b32_e32 v13, v7
	v_pk_mov_b32 v[8:9], v[4:5], v[8:9] op_sel:[1,0]
	v_mov_b32_e32 v11, v4
	v_pk_add_f32 v[8:9], v[12:13], v[8:9] neg_lo:[0,1] neg_hi:[0,1]
	v_mov_b32_e32 v16, v14
	v_pk_add_f32 v[4:5], v[10:11], v[8:9] neg_lo:[0,1] neg_hi:[0,1]
	v_mov_b32_e32 v15, v7
	v_pk_add_f32 v[8:9], v[16:17], v[4:5]
	v_cmp_neq_f32_e32 vcc, s2, v18
	v_pk_add_f32 v[10:11], v[8:9], v[8:9] op_sel:[0,1] op_sel_hi:[1,0]
	s_mov_b32 s2, 0x33800000
	v_pk_add_f32 v[6:7], v[6:7], v[10:11] op_sel:[1,0] op_sel_hi:[0,1]
	v_mov_b32_e32 v9, v6
	v_pk_add_f32 v[12:13], v[8:9], v[14:15] neg_lo:[0,1] neg_hi:[0,1]
	v_mov_b32_e32 v5, v10
	v_sub_f32_e32 v7, v8, v12
	v_pk_add_f32 v[4:5], v[4:5], v[12:13] neg_lo:[0,1] neg_hi:[0,1]
	v_sub_f32_e32 v7, v14, v7
	v_add_f32_e32 v4, v4, v7
	v_add_f32_e32 v4, v4, v5
	v_add_f32_e32 v4, v6, v4
	v_cndmask_b32_e32 v4, v234, v4, vcc
	v_cmp_ngt_f32_e32 vcc, -1.0, v18
	v_mov_b32_e32 v11, 0x3ab69700
	s_nop 0
	v_cndmask_b32_e32 v4, v232, v4, vcc
	v_cmp_neq_f32_e32 vcc, -1.0, v18
	s_nop 1
	v_cndmask_b32_e32 v4, v233, v4, vcc
	v_cmp_lt_f32_e64 vcc, |v18|, s2
	s_add_u32 s2, s10, s36
	s_addc_u32 s3, s11, s37
	v_cndmask_b32_e32 v4, v4, v18, vcc
	v_mul_f32_e32 v7, v3, v4
	v_mul_f32_e32 v3, 0x3fb8aa3b, v7
	v_exp_f32_e32 v6, v3
	v_ashrrev_i32_e32 v3, 31, v2
	v_lshlrev_b64 v[4:5], 2, v[2:3]
	v_lshl_add_u64 v[8:9], s[2:3], 0, v[4:5]
	global_load_dword v8, v[8:9], off
	v_add_f32_e32 v7, v7, v7
	v_mul_f32_e32 v9, 0x3fb8aa3b, v7
	v_rndne_f32_e32 v9, v9
	v_fmamk_f32 v10, v9, 0xbf317218, v7
	v_fmac_f32_e32 v10, 0x3102e308, v9
	s_mov_b32 s2, 0x43000000
	v_fmamk_f32 v11, v10, 0x395133b1, v11
	v_cmp_eq_f32_e32 vcc, s2, v9
	v_cvt_i32_f32_e32 v9, v9
	v_fmaak_f32 v11, v10, v11, 0x3c0887f9
	v_fmaak_f32 v11, v10, v11, 0x3d2aaa81
	v_fmaak_f32 v11, v10, v11, 0x3e2aaaab
	v_fma_f32 v11, v10, v11, 0.5
	v_ldexp_f32 v9, 1.0, v9
	v_mul_f32_e32 v11, v10, v11
	v_cndmask_b32_e32 v9, v9, v238, vcc
	v_fmac_f32_e32 v10, v10, v11
	v_add_f32_e32 v11, -1.0, v9
	v_fmac_f32_e32 v11, v9, v10
	v_add_f32_e32 v9, v11, v11
	v_cndmask_b32_e32 v9, v11, v9, vcc
	s_mov_b32 s2, 0x42b17217
	v_max_f32_e64 v9, -v9, 0
	v_cmp_nlt_f32_e32 vcc, s2, v7
	s_mov_b32 s2, 0xc1880000
	v_lshlrev_b64 v[2:3], 1, v[2:3]
	v_cndmask_b32_e32 v9, 0, v9, vcc
	v_cmp_ngt_f32_e32 vcc, s2, v7
	s_add_u32 s2, s66, s36
	s_addc_u32 s3, s67, s37
	v_cndmask_b32_e32 v7, 1.0, v9, vcc
	v_sqrt_f32_e32 v7, v7
	ds_read_b32 v9, v130 offset:9216
	v_lshl_add_u64 v[4:5], s[2:3], 0, v[4:5]
	s_mov_b32 s2, 0x43c0000
	v_mul_f32_e32 v7, v0, v7
	v_add_co_u32_e32 v4, vcc, s2, v4
	s_waitcnt vmcnt(0) lgkmcnt(0)
	v_pk_mul_f32 v[6:7], v[8:9], v[6:7]
	s_nop 0
	v_add_f32_e32 v0, v6, v7
	v_addc_co_u32_e32 v5, vcc, 0, v5, vcc
	global_store_dword v[4:5], v0, off
	v_lshl_add_u64 v[4:5], s[46:47], 0, v[2:3]
	global_load_ushort v4, v[4:5], off offset:1024
	v_lshl_add_u64 v[2:3], s[48:49], 0, v[2:3]
	s_waitcnt vmcnt(0)
	v_lshlrev_b32_e32 v4, 16, v4
	v_mul_f32_e32 v5, v4, v4
	v_fmamk_f32 v5, v5, 0x3dd2d3e8, v224
	v_mul_f32_e32 v5, v5, v4
	v_exp_f32_e32 v5, v5
	s_nop 0
	v_add_f32_e32 v5, 1.0, v5
	v_rcp_f32_e32 v5, v5
	s_nop 0
	v_fma_f32 v4, -v4, v5, v4
	v_mul_f32_e32 v0, v4, v0
	v_cvt_pk_bf16_f32 v0, v0, v1
	global_store_short v[2:3], v0, off
	s_branch .LBB0_446
